# K-loop start offset rotated per workgroup (4 phases by blockIdx) in all 8 tile2 GEMM loops to spread L2 channel load; plus pipelined xin phase; accumulation order over K is rotated, same bf16 MFMA f32
# speedup vs baseline: 1.0267x; 1.0267x over previous
.LBB0_122:
	s_cmp_gt_i32 s44, 1
	s_cselect_b64 s[2:3], -1, 0
	s_cmp_lt_i32 s45, 2
	s_cselect_b64 s[4:5], -1, 0
	s_or_b64 s[2:3], s[2:3], s[4:5]
	s_and_b64 vcc, exec, s[2:3]
	s_cbranch_vccnz .LBB0_180
	s_load_dword s6, s[0:1], 0xf0
	s_mov_b32 s67, 0
	s_lshl_b64 s[2:3], s[66:67], 8
	v_and_b32_e32 v1, 0x3ff, v0
	v_or_b32_e32 v4, s2, v1
	v_mov_b32_e32 v5, s3
	s_add_u32 s8, s0, 0xf0
	s_mov_b64 s[2:3], 0x300000
	v_mov_b32_e32 v3, 0
	s_addc_u32 s9, s1, 0
	v_cmp_gt_u64_e32 vcc, s[2:3], v[4:5]
	s_and_saveexec_b64 s[2:3], vcc
	s_cbranch_execz .LBB0_126
	v_lshlrev_b32_e32 v2, 4, v1
	v_lshlrev_b32_e32 v3, 3, v1
	s_waitcnt lgkmcnt(0)
	s_mov_b32 s5, s6
	s_mov_b32 s4, s66
	s_sub_u32 s18, 0x2fff, s66
	s_mov_b32 s7, 0
.Lxin_cnt:
	s_add_u32 s7, s7, 1
	s_sub_u32 s18, s18, s5
	s_cmp_lt_i32 s18, 0
	s_cbranch_scc0 .Lxin_cnt
	s_cmp_lt_u32 s7, 4
	s_cbranch_scc1 .Lxin_tail
	s_mov_b32 s18, s4
	s_cmp_lt_u32 s18, 0x2000
	s_cselect_b32 s10, s48, s50
	s_cselect_b32 s11, s49, s51
	s_cselect_b32 s19, 0, 0x2000
	s_sub_u32 s19, s18, s19
	s_lshl_b32 s19, s19, 12
	s_add_u32 s10, s10, s19
	s_addc_u32 s11, s11, 0
	global_load_dwordx4 v[8:11], v2, s[10:11] nt
	s_sub_u32 s19, s18, 0x2000
	s_lshr_b32 s19, s19, 10
	s_add_u32 s19, s19, 1
	s_cmp_lt_u32 s18, 0x2000
	s_cselect_b32 s19, 0, s19
	s_mul_i32 s19, s19, 0x6000
	s_add_u32 s12, s42, s19
	s_addc_u32 s13, s43, 0
	s_add_u32 s12, s12, 0x6ea4000
	s_addc_u32 s13, s13, 0
	global_load_dwordx4 v[40:43], v2, s[12:13]
	s_add_u32 s12, s12, 0x1000
	s_addc_u32 s13, s13, 0
	global_load_dwordx4 v[24:27], v2, s[12:13]
	s_add_u32 s18, s18, s5
	s_cmp_lt_u32 s18, 0x2000
	s_cselect_b32 s10, s48, s50
	s_cselect_b32 s11, s49, s51
	s_cselect_b32 s19, 0, 0x2000
	s_sub_u32 s19, s18, s19
	s_lshl_b32 s19, s19, 12
	s_add_u32 s10, s10, s19
	s_addc_u32 s11, s11, 0
	global_load_dwordx4 v[12:15], v2, s[10:11] nt
	s_sub_u32 s19, s18, 0x2000
	s_lshr_b32 s19, s19, 10
	s_add_u32 s19, s19, 1
	s_cmp_lt_u32 s18, 0x2000
	s_cselect_b32 s19, 0, s19
	s_mul_i32 s19, s19, 0x6000
	s_add_u32 s12, s42, s19
	s_addc_u32 s13, s43, 0
	s_add_u32 s12, s12, 0x6ea4000
	s_addc_u32 s13, s13, 0
	global_load_dwordx4 v[44:47], v2, s[12:13]
	s_add_u32 s12, s12, 0x1000
	s_addc_u32 s13, s13, 0
	global_load_dwordx4 v[28:31], v2, s[12:13]
	s_add_u32 s18, s18, s5
	s_cmp_lt_u32 s18, 0x2000
	s_cselect_b32 s10, s48, s50
	s_cselect_b32 s11, s49, s51
	s_cselect_b32 s19, 0, 0x2000
	s_sub_u32 s19, s18, s19
	s_lshl_b32 s19, s19, 12
	s_add_u32 s10, s10, s19
	s_addc_u32 s11, s11, 0
	global_load_dwordx4 v[16:19], v2, s[10:11] nt
	s_sub_u32 s19, s18, 0x2000
	s_lshr_b32 s19, s19, 10
	s_add_u32 s19, s19, 1
	s_cmp_lt_u32 s18, 0x2000
	s_cselect_b32 s19, 0, s19
	s_mul_i32 s19, s19, 0x6000
	s_add_u32 s12, s42, s19
	s_addc_u32 s13, s43, 0
	s_add_u32 s12, s12, 0x6ea4000
	s_addc_u32 s13, s13, 0
	global_load_dwordx4 v[48:51], v2, s[12:13]
	s_add_u32 s12, s12, 0x1000
	s_addc_u32 s13, s13, 0
	global_load_dwordx4 v[32:35], v2, s[12:13]
	s_add_u32 s18, s18, s5
	s_cmp_lt_u32 s18, 0x2000
	s_cselect_b32 s10, s48, s50
	s_cselect_b32 s11, s49, s51
	s_cselect_b32 s19, 0, 0x2000
	s_sub_u32 s19, s18, s19
	s_lshl_b32 s19, s19, 12
	s_add_u32 s10, s10, s19
	s_addc_u32 s11, s11, 0
	global_load_dwordx4 v[20:23], v2, s[10:11] nt
	s_sub_u32 s19, s18, 0x2000
	s_lshr_b32 s19, s19, 10
	s_add_u32 s19, s19, 1
	s_cmp_lt_u32 s18, 0x2000
	s_cselect_b32 s19, 0, s19
	s_mul_i32 s19, s19, 0x6000
	s_add_u32 s12, s42, s19
	s_addc_u32 s13, s43, 0
	s_add_u32 s12, s12, 0x6ea4000
	s_addc_u32 s13, s13, 0
	global_load_dwordx4 v[52:55], v2, s[12:13]
	s_add_u32 s12, s12, 0x1000
	s_addc_u32 s13, s13, 0
	global_load_dwordx4 v[36:39], v2, s[12:13]
	s_waitcnt vmcnt(0)
.Lxin_A:
	v_pk_add_f32 v[24:25], v[24:25], 1.0 op_sel_hi:[1,0]
	v_pk_fma_f32 v[24:25], v[8:9], v[24:25], v[40:41]
	v_pk_add_f32 v[26:27], v[26:27], 1.0 op_sel_hi:[1,0]
	v_pk_fma_f32 v[26:27], v[10:11], v[26:27], v[42:43]
	v_cvt_pk_bf16_f32 v56, v24, v25
	v_cvt_pk_bf16_f32 v57, v26, v27
	v_pk_add_f32 v[28:29], v[28:29], 1.0 op_sel_hi:[1,0]
	v_pk_fma_f32 v[28:29], v[12:13], v[28:29], v[44:45]
	v_pk_add_f32 v[30:31], v[30:31], 1.0 op_sel_hi:[1,0]
	v_pk_fma_f32 v[30:31], v[14:15], v[30:31], v[46:47]
	v_cvt_pk_bf16_f32 v58, v28, v29
	v_cvt_pk_bf16_f32 v59, v30, v31
	v_pk_add_f32 v[32:33], v[32:33], 1.0 op_sel_hi:[1,0]
	v_pk_fma_f32 v[32:33], v[16:17], v[32:33], v[48:49]
	v_pk_add_f32 v[34:35], v[34:35], 1.0 op_sel_hi:[1,0]
	v_pk_fma_f32 v[34:35], v[18:19], v[34:35], v[50:51]
	v_cvt_pk_bf16_f32 v60, v32, v33
	v_cvt_pk_bf16_f32 v61, v34, v35
	v_pk_add_f32 v[36:37], v[36:37], 1.0 op_sel_hi:[1,0]
	v_pk_fma_f32 v[36:37], v[20:21], v[36:37], v[52:53]
	v_pk_add_f32 v[38:39], v[38:39], 1.0 op_sel_hi:[1,0]
	v_pk_fma_f32 v[38:39], v[22:23], v[38:39], v[54:55]
	v_cvt_pk_bf16_f32 v62, v36, v37
	v_cvt_pk_bf16_f32 v63, v38, v39
	s_mov_b32 s20, s4
	s_lshl_b32 s18, s5, 2
	s_add_u32 s4, s4, s18
	s_sub_u32 s7, s7, 4
	s_cmp_lt_u32 s7, 4
	s_cbranch_scc1 .Lxin_A_last
	s_mov_b32 s18, s4
	s_cmp_lt_u32 s18, 0x2000
	s_cselect_b32 s10, s48, s50
	s_cselect_b32 s11, s49, s51
	s_cselect_b32 s19, 0, 0x2000
	s_sub_u32 s19, s18, s19
	s_lshl_b32 s19, s19, 12
	s_add_u32 s10, s10, s19
	s_addc_u32 s11, s11, 0
	global_load_dwordx4 v[64:67], v2, s[10:11] nt
	s_sub_u32 s19, s18, 0x2000
	s_lshr_b32 s19, s19, 10
	s_add_u32 s19, s19, 1
	s_cmp_lt_u32 s18, 0x2000
	s_cselect_b32 s19, 0, s19
	s_mul_i32 s19, s19, 0x6000
	s_add_u32 s12, s42, s19
	s_addc_u32 s13, s43, 0
	s_add_u32 s12, s12, 0x6ea4000
	s_addc_u32 s13, s13, 0
	global_load_dwordx4 v[100:103], v2, s[12:13]
	s_add_u32 s12, s12, 0x1000
	s_addc_u32 s13, s13, 0
	global_load_dwordx4 v[80:83], v2, s[12:13]
	s_add_u32 s18, s18, s5
	s_cmp_lt_u32 s18, 0x2000
	s_cselect_b32 s10, s48, s50
	s_cselect_b32 s11, s49, s51
	s_cselect_b32 s19, 0, 0x2000
	s_sub_u32 s19, s18, s19
	s_lshl_b32 s19, s19, 12
	s_add_u32 s10, s10, s19
	s_addc_u32 s11, s11, 0
	global_load_dwordx4 v[68:71], v2, s[10:11] nt
	s_sub_u32 s19, s18, 0x2000
	s_lshr_b32 s19, s19, 10
	s_add_u32 s19, s19, 1
	s_cmp_lt_u32 s18, 0x2000
	s_cselect_b32 s19, 0, s19
	s_mul_i32 s19, s19, 0x6000
	s_add_u32 s12, s42, s19
	s_addc_u32 s13, s43, 0
	s_add_u32 s12, s12, 0x6ea4000
	s_addc_u32 s13, s13, 0
	global_load_dwordx4 v[104:107], v2, s[12:13]
	s_add_u32 s12, s12, 0x1000
	s_addc_u32 s13, s13, 0
	global_load_dwordx4 v[84:87], v2, s[12:13]
	s_add_u32 s18, s18, s5
	s_cmp_lt_u32 s18, 0x2000
	s_cselect_b32 s10, s48, s50
	s_cselect_b32 s11, s49, s51
	s_cselect_b32 s19, 0, 0x2000
	s_sub_u32 s19, s18, s19
	s_lshl_b32 s19, s19, 12
	s_add_u32 s10, s10, s19
	s_addc_u32 s11, s11, 0
	global_load_dwordx4 v[72:75], v2, s[10:11] nt
	s_sub_u32 s19, s18, 0x2000
	s_lshr_b32 s19, s19, 10
	s_add_u32 s19, s19, 1
	s_cmp_lt_u32 s18, 0x2000
	s_cselect_b32 s19, 0, s19
	s_mul_i32 s19, s19, 0x6000
	s_add_u32 s12, s42, s19
	s_addc_u32 s13, s43, 0
	s_add_u32 s12, s12, 0x6ea4000
	s_addc_u32 s13, s13, 0
	global_load_dwordx4 v[108:111], v2, s[12:13]
	s_add_u32 s12, s12, 0x1000
	s_addc_u32 s13, s13, 0
	global_load_dwordx4 v[88:91], v2, s[12:13]
	s_add_u32 s18, s18, s5
	s_cmp_lt_u32 s18, 0x2000
	s_cselect_b32 s10, s48, s50
	s_cselect_b32 s11, s49, s51
	s_cselect_b32 s19, 0, 0x2000
	s_sub_u32 s19, s18, s19
	s_lshl_b32 s19, s19, 12
	s_add_u32 s10, s10, s19
	s_addc_u32 s11, s11, 0
	global_load_dwordx4 v[76:79], v2, s[10:11] nt
	s_sub_u32 s19, s18, 0x2000
	s_lshr_b32 s19, s19, 10
	s_add_u32 s19, s19, 1
	s_cmp_lt_u32 s18, 0x2000
	s_cselect_b32 s19, 0, s19
	s_mul_i32 s19, s19, 0x6000
	s_add_u32 s12, s42, s19
	s_addc_u32 s13, s43, 0
	s_add_u32 s12, s12, 0x6ea4000
	s_addc_u32 s13, s13, 0
	global_load_dwordx4 v[112:115], v2, s[12:13]
	s_add_u32 s12, s12, 0x1000
	s_addc_u32 s13, s13, 0
	global_load_dwordx4 v[92:95], v2, s[12:13]
	s_mov_b32 s18, s20
	s_lshl_b32 s19, s18, 12
	s_add_u32 s16, s42, s19
	s_addc_u32 s17, s43, 0
	s_add_u32 s16, s16, 0x6f24000
	s_addc_u32 s17, s17, 0
	global_store_dwordx4 v2, v[8:11], s[16:17]
	s_lshl_b32 s19, s18, 11
	s_add_u32 s16, s42, s19
	s_addc_u32 s17, s43, 0
	s_add_u32 s16, s16, 0x9f24000
	s_addc_u32 s17, s17, 0
	global_store_dwordx2 v3, v[56:57], s[16:17]
	s_add_u32 s18, s18, s5
	s_lshl_b32 s19, s18, 12
	s_add_u32 s16, s42, s19
	s_addc_u32 s17, s43, 0
	s_add_u32 s16, s16, 0x6f24000
	s_addc_u32 s17, s17, 0
	global_store_dwordx4 v2, v[12:15], s[16:17]
	s_lshl_b32 s19, s18, 11
	s_add_u32 s16, s42, s19
	s_addc_u32 s17, s43, 0
	s_add_u32 s16, s16, 0x9f24000
	s_addc_u32 s17, s17, 0
	global_store_dwordx2 v3, v[58:59], s[16:17]
	s_add_u32 s18, s18, s5
	s_lshl_b32 s19, s18, 12
	s_add_u32 s16, s42, s19
	s_addc_u32 s17, s43, 0
	s_add_u32 s16, s16, 0x6f24000
	s_addc_u32 s17, s17, 0
	global_store_dwordx4 v2, v[16:19], s[16:17]
	s_lshl_b32 s19, s18, 11
	s_add_u32 s16, s42, s19
	s_addc_u32 s17, s43, 0
	s_add_u32 s16, s16, 0x9f24000
	s_addc_u32 s17, s17, 0
	global_store_dwordx2 v3, v[60:61], s[16:17]
	s_add_u32 s18, s18, s5
	s_lshl_b32 s19, s18, 12
	s_add_u32 s16, s42, s19
	s_addc_u32 s17, s43, 0
	s_add_u32 s16, s16, 0x6f24000
	s_addc_u32 s17, s17, 0
	global_store_dwordx4 v2, v[20:23], s[16:17]
	s_lshl_b32 s19, s18, 11
	s_add_u32 s16, s42, s19
	s_addc_u32 s17, s43, 0
	s_add_u32 s16, s16, 0x9f24000
	s_addc_u32 s17, s17, 0
	global_store_dwordx2 v3, v[62:63], s[16:17]
	s_waitcnt vmcnt(8)
	s_branch .Lxin_B
.Lxin_A_last:
	s_mov_b32 s18, s20
	s_lshl_b32 s19, s18, 12
	s_add_u32 s16, s42, s19
	s_addc_u32 s17, s43, 0
	s_add_u32 s16, s16, 0x6f24000
	s_addc_u32 s17, s17, 0
	global_store_dwordx4 v2, v[8:11], s[16:17]
	s_lshl_b32 s19, s18, 11
	s_add_u32 s16, s42, s19
	s_addc_u32 s17, s43, 0
	s_add_u32 s16, s16, 0x9f24000
	s_addc_u32 s17, s17, 0
	global_store_dwordx2 v3, v[56:57], s[16:17]
	s_add_u32 s18, s18, s5
	s_lshl_b32 s19, s18, 12
	s_add_u32 s16, s42, s19
	s_addc_u32 s17, s43, 0
	s_add_u32 s16, s16, 0x6f24000
	s_addc_u32 s17, s17, 0
	global_store_dwordx4 v2, v[12:15], s[16:17]
	s_lshl_b32 s19, s18, 11
	s_add_u32 s16, s42, s19
	s_addc_u32 s17, s43, 0
	s_add_u32 s16, s16, 0x9f24000
	s_addc_u32 s17, s17, 0
	global_store_dwordx2 v3, v[58:59], s[16:17]
	s_add_u32 s18, s18, s5
	s_lshl_b32 s19, s18, 12
	s_add_u32 s16, s42, s19
	s_addc_u32 s17, s43, 0
	s_add_u32 s16, s16, 0x6f24000
	s_addc_u32 s17, s17, 0
	global_store_dwordx4 v2, v[16:19], s[16:17]
	s_lshl_b32 s19, s18, 11
	s_add_u32 s16, s42, s19
	s_addc_u32 s17, s43, 0
	s_add_u32 s16, s16, 0x9f24000
	s_addc_u32 s17, s17, 0
	global_store_dwordx2 v3, v[60:61], s[16:17]
	s_add_u32 s18, s18, s5
	s_lshl_b32 s19, s18, 12
	s_add_u32 s16, s42, s19
	s_addc_u32 s17, s43, 0
	s_add_u32 s16, s16, 0x6f24000
	s_addc_u32 s17, s17, 0
	global_store_dwordx4 v2, v[20:23], s[16:17]
	s_lshl_b32 s19, s18, 11
	s_add_u32 s16, s42, s19
	s_addc_u32 s17, s43, 0
	s_add_u32 s16, s16, 0x9f24000
	s_addc_u32 s17, s17, 0
	global_store_dwordx2 v3, v[62:63], s[16:17]
	s_branch .Lxin_tail
.Lxin_B:
	v_pk_add_f32 v[80:81], v[80:81], 1.0 op_sel_hi:[1,0]
	v_pk_fma_f32 v[80:81], v[64:65], v[80:81], v[100:101]
	v_pk_add_f32 v[82:83], v[82:83], 1.0 op_sel_hi:[1,0]
	v_pk_fma_f32 v[82:83], v[66:67], v[82:83], v[102:103]
	v_cvt_pk_bf16_f32 v116, v80, v81
	v_cvt_pk_bf16_f32 v117, v82, v83
	v_pk_add_f32 v[84:85], v[84:85], 1.0 op_sel_hi:[1,0]
	v_pk_fma_f32 v[84:85], v[68:69], v[84:85], v[104:105]
	v_pk_add_f32 v[86:87], v[86:87], 1.0 op_sel_hi:[1,0]
	v_pk_fma_f32 v[86:87], v[70:71], v[86:87], v[106:107]
	v_cvt_pk_bf16_f32 v118, v84, v85
	v_cvt_pk_bf16_f32 v119, v86, v87
	v_pk_add_f32 v[88:89], v[88:89], 1.0 op_sel_hi:[1,0]
	v_pk_fma_f32 v[88:89], v[72:73], v[88:89], v[108:109]
	v_pk_add_f32 v[90:91], v[90:91], 1.0 op_sel_hi:[1,0]
	v_pk_fma_f32 v[90:91], v[74:75], v[90:91], v[110:111]
	v_cvt_pk_bf16_f32 v120, v88, v89
	v_cvt_pk_bf16_f32 v121, v90, v91
	v_pk_add_f32 v[92:93], v[92:93], 1.0 op_sel_hi:[1,0]
	v_pk_fma_f32 v[92:93], v[76:77], v[92:93], v[112:113]
	v_pk_add_f32 v[94:95], v[94:95], 1.0 op_sel_hi:[1,0]
	v_pk_fma_f32 v[94:95], v[78:79], v[94:95], v[114:115]
	v_cvt_pk_bf16_f32 v122, v92, v93
	v_cvt_pk_bf16_f32 v123, v94, v95
	s_mov_b32 s20, s4
	s_lshl_b32 s18, s5, 2
	s_add_u32 s4, s4, s18
	s_sub_u32 s7, s7, 4
	s_cmp_lt_u32 s7, 4
	s_cbranch_scc1 .Lxin_B_last
	s_mov_b32 s18, s4
	s_cmp_lt_u32 s18, 0x2000
	s_cselect_b32 s10, s48, s50
	s_cselect_b32 s11, s49, s51
	s_cselect_b32 s19, 0, 0x2000
	s_sub_u32 s19, s18, s19
	s_lshl_b32 s19, s19, 12
	s_add_u32 s10, s10, s19
	s_addc_u32 s11, s11, 0
	global_load_dwordx4 v[8:11], v2, s[10:11] nt
	s_sub_u32 s19, s18, 0x2000
	s_lshr_b32 s19, s19, 10
	s_add_u32 s19, s19, 1
	s_cmp_lt_u32 s18, 0x2000
	s_cselect_b32 s19, 0, s19
	s_mul_i32 s19, s19, 0x6000
	s_add_u32 s12, s42, s19
	s_addc_u32 s13, s43, 0
	s_add_u32 s12, s12, 0x6ea4000
	s_addc_u32 s13, s13, 0
	global_load_dwordx4 v[40:43], v2, s[12:13]
	s_add_u32 s12, s12, 0x1000
	s_addc_u32 s13, s13, 0
	global_load_dwordx4 v[24:27], v2, s[12:13]
	s_add_u32 s18, s18, s5
	s_cmp_lt_u32 s18, 0x2000
	s_cselect_b32 s10, s48, s50
	s_cselect_b32 s11, s49, s51
	s_cselect_b32 s19, 0, 0x2000
	s_sub_u32 s19, s18, s19
	s_lshl_b32 s19, s19, 12
	s_add_u32 s10, s10, s19
	s_addc_u32 s11, s11, 0
	global_load_dwordx4 v[12:15], v2, s[10:11] nt
	s_sub_u32 s19, s18, 0x2000
	s_lshr_b32 s19, s19, 10
	s_add_u32 s19, s19, 1
	s_cmp_lt_u32 s18, 0x2000
	s_cselect_b32 s19, 0, s19
	s_mul_i32 s19, s19, 0x6000
	s_add_u32 s12, s42, s19
	s_addc_u32 s13, s43, 0
	s_add_u32 s12, s12, 0x6ea4000
	s_addc_u32 s13, s13, 0
	global_load_dwordx4 v[44:47], v2, s[12:13]
	s_add_u32 s12, s12, 0x1000
	s_addc_u32 s13, s13, 0
	global_load_dwordx4 v[28:31], v2, s[12:13]
	s_add_u32 s18, s18, s5
	s_cmp_lt_u32 s18, 0x2000
	s_cselect_b32 s10, s48, s50
	s_cselect_b32 s11, s49, s51
	s_cselect_b32 s19, 0, 0x2000
	s_sub_u32 s19, s18, s19
	s_lshl_b32 s19, s19, 12
	s_add_u32 s10, s10, s19
	s_addc_u32 s11, s11, 0
	global_load_dwordx4 v[16:19], v2, s[10:11] nt
	s_sub_u32 s19, s18, 0x2000
	s_lshr_b32 s19, s19, 10
	s_add_u32 s19, s19, 1
	s_cmp_lt_u32 s18, 0x2000
	s_cselect_b32 s19, 0, s19
	s_mul_i32 s19, s19, 0x6000
	s_add_u32 s12, s42, s19
	s_addc_u32 s13, s43, 0
	s_add_u32 s12, s12, 0x6ea4000
	s_addc_u32 s13, s13, 0
	global_load_dwordx4 v[48:51], v2, s[12:13]
	s_add_u32 s12, s12, 0x1000
	s_addc_u32 s13, s13, 0
	global_load_dwordx4 v[32:35], v2, s[12:13]
	s_add_u32 s18, s18, s5
	s_cmp_lt_u32 s18, 0x2000
	s_cselect_b32 s10, s48, s50
	s_cselect_b32 s11, s49, s51
	s_cselect_b32 s19, 0, 0x2000
	s_sub_u32 s19, s18, s19
	s_lshl_b32 s19, s19, 12
	s_add_u32 s10, s10, s19
	s_addc_u32 s11, s11, 0
	global_load_dwordx4 v[20:23], v2, s[10:11] nt
	s_sub_u32 s19, s18, 0x2000
	s_lshr_b32 s19, s19, 10
	s_add_u32 s19, s19, 1
	s_cmp_lt_u32 s18, 0x2000
	s_cselect_b32 s19, 0, s19
	s_mul_i32 s19, s19, 0x6000
	s_add_u32 s12, s42, s19
	s_addc_u32 s13, s43, 0
	s_add_u32 s12, s12, 0x6ea4000
	s_addc_u32 s13, s13, 0
	global_load_dwordx4 v[52:55], v2, s[12:13]
	s_add_u32 s12, s12, 0x1000
	s_addc_u32 s13, s13, 0
	global_load_dwordx4 v[36:39], v2, s[12:13]
	s_mov_b32 s18, s20
	s_lshl_b32 s19, s18, 12
	s_add_u32 s16, s42, s19
	s_addc_u32 s17, s43, 0
	s_add_u32 s16, s16, 0x6f24000
	s_addc_u32 s17, s17, 0
	global_store_dwordx4 v2, v[64:67], s[16:17]
	s_lshl_b32 s19, s18, 11
	s_add_u32 s16, s42, s19
	s_addc_u32 s17, s43, 0
	s_add_u32 s16, s16, 0x9f24000
	s_addc_u32 s17, s17, 0
	global_store_dwordx2 v3, v[116:117], s[16:17]
	s_add_u32 s18, s18, s5
	s_lshl_b32 s19, s18, 12
	s_add_u32 s16, s42, s19
	s_addc_u32 s17, s43, 0
	s_add_u32 s16, s16, 0x6f24000
	s_addc_u32 s17, s17, 0
	global_store_dwordx4 v2, v[68:71], s[16:17]
	s_lshl_b32 s19, s18, 11
	s_add_u32 s16, s42, s19
	s_addc_u32 s17, s43, 0
	s_add_u32 s16, s16, 0x9f24000
	s_addc_u32 s17, s17, 0
	global_store_dwordx2 v3, v[118:119], s[16:17]
	s_add_u32 s18, s18, s5
	s_lshl_b32 s19, s18, 12
	s_add_u32 s16, s42, s19
	s_addc_u32 s17, s43, 0
	s_add_u32 s16, s16, 0x6f24000
	s_addc_u32 s17, s17, 0
	global_store_dwordx4 v2, v[72:75], s[16:17]
	s_lshl_b32 s19, s18, 11
	s_add_u32 s16, s42, s19
	s_addc_u32 s17, s43, 0
	s_add_u32 s16, s16, 0x9f24000
	s_addc_u32 s17, s17, 0
	global_store_dwordx2 v3, v[120:121], s[16:17]
	s_add_u32 s18, s18, s5
	s_lshl_b32 s19, s18, 12
	s_add_u32 s16, s42, s19
	s_addc_u32 s17, s43, 0
	s_add_u32 s16, s16, 0x6f24000
	s_addc_u32 s17, s17, 0
	global_store_dwordx4 v2, v[76:79], s[16:17]
	s_lshl_b32 s19, s18, 11
	s_add_u32 s16, s42, s19
	s_addc_u32 s17, s43, 0
	s_add_u32 s16, s16, 0x9f24000
	s_addc_u32 s17, s17, 0
	global_store_dwordx2 v3, v[122:123], s[16:17]
	s_waitcnt vmcnt(8)
	s_branch .Lxin_A
.Lxin_B_last:
	s_mov_b32 s18, s20
	s_lshl_b32 s19, s18, 12
	s_add_u32 s16, s42, s19
	s_addc_u32 s17, s43, 0
	s_add_u32 s16, s16, 0x6f24000
	s_addc_u32 s17, s17, 0
	global_store_dwordx4 v2, v[64:67], s[16:17]
	s_lshl_b32 s19, s18, 11
	s_add_u32 s16, s42, s19
	s_addc_u32 s17, s43, 0
	s_add_u32 s16, s16, 0x9f24000
	s_addc_u32 s17, s17, 0
	global_store_dwordx2 v3, v[116:117], s[16:17]
	s_add_u32 s18, s18, s5
	s_lshl_b32 s19, s18, 12
	s_add_u32 s16, s42, s19
	s_addc_u32 s17, s43, 0
	s_add_u32 s16, s16, 0x6f24000
	s_addc_u32 s17, s17, 0
	global_store_dwordx4 v2, v[68:71], s[16:17]
	s_lshl_b32 s19, s18, 11
	s_add_u32 s16, s42, s19
	s_addc_u32 s17, s43, 0
	s_add_u32 s16, s16, 0x9f24000
	s_addc_u32 s17, s17, 0
	global_store_dwordx2 v3, v[118:119], s[16:17]
	s_add_u32 s18, s18, s5
	s_lshl_b32 s19, s18, 12
	s_add_u32 s16, s42, s19
	s_addc_u32 s17, s43, 0
	s_add_u32 s16, s16, 0x6f24000
	s_addc_u32 s17, s17, 0
	global_store_dwordx4 v2, v[72:75], s[16:17]
	s_lshl_b32 s19, s18, 11
	s_add_u32 s16, s42, s19
	s_addc_u32 s17, s43, 0
	s_add_u32 s16, s16, 0x9f24000
	s_addc_u32 s17, s17, 0
	global_store_dwordx2 v3, v[120:121], s[16:17]
	s_add_u32 s18, s18, s5
	s_lshl_b32 s19, s18, 12
	s_add_u32 s16, s42, s19
	s_addc_u32 s17, s43, 0
	s_add_u32 s16, s16, 0x6f24000
	s_addc_u32 s17, s17, 0
	global_store_dwordx4 v2, v[76:79], s[16:17]
	s_lshl_b32 s19, s18, 11
	s_add_u32 s16, s42, s19
	s_addc_u32 s17, s43, 0
	s_add_u32 s16, s16, 0x9f24000
	s_addc_u32 s17, s17, 0
	global_store_dwordx2 v3, v[122:123], s[16:17]
	s_branch .Lxin_tail
.Lxin_tail:
	s_cmp_eq_u32 s7, 0
	s_cbranch_scc1 .LBB0_126
	s_mov_b32 s18, s4
	s_cmp_lt_u32 s18, 0x2000
	s_cselect_b32 s10, s48, s50
	s_cselect_b32 s11, s49, s51
	s_cselect_b32 s19, 0, 0x2000
	s_sub_u32 s19, s18, s19
	s_lshl_b32 s19, s19, 12
	s_add_u32 s10, s10, s19
	s_addc_u32 s11, s11, 0
	global_load_dwordx4 v[8:11], v2, s[10:11] nt
	s_sub_u32 s19, s18, 0x2000
	s_lshr_b32 s19, s19, 10
	s_add_u32 s19, s19, 1
	s_cmp_lt_u32 s18, 0x2000
	s_cselect_b32 s19, 0, s19
	s_mul_i32 s19, s19, 0x6000
	s_add_u32 s12, s42, s19
	s_addc_u32 s13, s43, 0
	s_add_u32 s12, s12, 0x6ea4000
	s_addc_u32 s13, s13, 0
	global_load_dwordx4 v[40:43], v2, s[12:13]
	s_add_u32 s12, s12, 0x1000
	s_addc_u32 s13, s13, 0
	global_load_dwordx4 v[24:27], v2, s[12:13]
	s_waitcnt vmcnt(0)
	v_pk_add_f32 v[24:25], v[24:25], 1.0 op_sel_hi:[1,0]
	v_pk_fma_f32 v[24:25], v[8:9], v[24:25], v[40:41]
	v_pk_add_f32 v[26:27], v[26:27], 1.0 op_sel_hi:[1,0]
	v_pk_fma_f32 v[26:27], v[10:11], v[26:27], v[42:43]
	v_cvt_pk_bf16_f32 v56, v24, v25
	v_cvt_pk_bf16_f32 v57, v26, v27
	s_mov_b32 s18, s4
	s_lshl_b32 s19, s18, 12
	s_add_u32 s16, s42, s19
	s_addc_u32 s17, s43, 0
	s_add_u32 s16, s16, 0x6f24000
	s_addc_u32 s17, s17, 0
	global_store_dwordx4 v2, v[8:11], s[16:17]
	s_lshl_b32 s19, s18, 11
	s_add_u32 s16, s42, s19
	s_addc_u32 s17, s43, 0
	s_add_u32 s16, s16, 0x9f24000
	s_addc_u32 s17, s17, 0
	global_store_dwordx2 v3, v[56:57], s[16:17]
	s_add_u32 s4, s4, s5
	s_sub_u32 s7, s7, 1
	s_branch .Lxin_tail

.LBB0_187:
	s_lshl_b32 s28, s67, 7
	s_ashr_i32 s29, s28, 31
	s_lshl_b64 s[26:27], s[28:29], 10
	s_lshl_b64 s[6:7], s[28:29], 11
	s_add_u32 s6, s23, s6
	s_addc_u32 s7, s33, s7
	s_ashr_i32 s25, s24, 31
	s_lshl_b64 s[8:9], s[24:25], 18
	s_add_u32 s8, s56, s8
	s_addc_u32 s9, s57, s9
	v_and_b32_e32 v200, 15, v0
	v_bfe_u32 v201, v0, 4, 2
	v_and_b32_e32 v161, 7, v200
	v_xor_b32_e32 v201, v201, v161
	v_lshlrev_b32_e32 v201, 4, v201
	v_lshl_or_b32 v201, v200, 7, v201
	v_bfe_u32 v200, v0, 7, 1
	v_lshl_or_b32 v130, v200, 13, v201
	v_bfe_u32 v200, v0, 6, 1
	v_lshl_or_b32 v194, v200, 13, v201
	v_or_b32_e32 v194, 0x4000, v194
	v_xor_b32_e32 v161, 64, v130
	v_xor_b32_e32 v195, 64, v194
	v_bfe_u32 v200, v0, 3, 3
	v_and_b32_e32 v201, 7, v0
	v_xor_b32_e32 v201, v201, v200
	v_lshlrev_b32_e32 v201, 4, v201
	v_lshl_or_b32 v201, v200, 11, v201
	v_lshrrev_b32_e32 v200, 6, v0
	v_and_b32_e32 v200, 3, v200
	v_lshl_or_b32 v196, v200, 16, v201
	v_add_u32_e32 v197, 0x3c00, v196
	v_add_u32_e32 v198, 0x7800, v196
	v_add_u32_e32 v199, 0xb400, v196
	v_lshlrev_b32_e32 v200, 12, v200
	s_nop 0
	v_readfirstlane_b32 s14, v200
	s_add_u32 s14, s14, 32
	v_mov_b32_e32 v94, 0
	v_mov_b32_e32 v95, 0
	v_mov_b32_e32 v96, 0
	v_mov_b32_e32 v97, 0
	v_mov_b32_e32 v90, 0
	v_mov_b32_e32 v91, 0
	v_mov_b32_e32 v92, 0
	v_mov_b32_e32 v93, 0
	v_mov_b32_e32 v86, 0
	v_mov_b32_e32 v87, 0
	v_mov_b32_e32 v88, 0
	v_mov_b32_e32 v89, 0
	v_mov_b32_e32 v82, 0
	v_mov_b32_e32 v83, 0
	v_mov_b32_e32 v84, 0
	v_mov_b32_e32 v85, 0
	v_mov_b32_e32 v74, 0
	v_mov_b32_e32 v75, 0
	v_mov_b32_e32 v76, 0
	v_mov_b32_e32 v77, 0
	v_mov_b32_e32 v70, 0
	v_mov_b32_e32 v71, 0
	v_mov_b32_e32 v72, 0
	v_mov_b32_e32 v73, 0
	v_mov_b32_e32 v66, 0
	v_mov_b32_e32 v67, 0
	v_mov_b32_e32 v68, 0
	v_mov_b32_e32 v69, 0
	v_mov_b32_e32 v62, 0
	v_mov_b32_e32 v63, 0
	v_mov_b32_e32 v64, 0
	v_mov_b32_e32 v65, 0
	v_mov_b32_e32 v54, 0
	v_mov_b32_e32 v55, 0
	v_mov_b32_e32 v56, 0
	v_mov_b32_e32 v57, 0
	v_mov_b32_e32 v34, 0
	v_mov_b32_e32 v35, 0
	v_mov_b32_e32 v36, 0
	v_mov_b32_e32 v37, 0
	v_mov_b32_e32 v18, 0
	v_mov_b32_e32 v19, 0
	v_mov_b32_e32 v20, 0
	v_mov_b32_e32 v21, 0
	v_mov_b32_e32 v14, 0
	v_mov_b32_e32 v15, 0
	v_mov_b32_e32 v16, 0
	v_mov_b32_e32 v17, 0
	v_mov_b32_e32 v10, 0
	v_mov_b32_e32 v11, 0
	v_mov_b32_e32 v12, 0
	v_mov_b32_e32 v13, 0
	v_mov_b32_e32 v6, 0
	v_mov_b32_e32 v7, 0
	v_mov_b32_e32 v8, 0
	v_mov_b32_e32 v9, 0
	v_mov_b32_e32 v2, 0
	v_mov_b32_e32 v3, 0
	v_mov_b32_e32 v4, 0
	v_mov_b32_e32 v5, 0
	v_mov_b32_e32 v78, 0
	v_mov_b32_e32 v79, 0
	v_mov_b32_e32 v80, 0
	v_mov_b32_e32 v81, 0
	v_mov_b32_e32 v98, 0
	v_mov_b32_e32 v99, 0
	v_mov_b32_e32 v100, 0
	v_mov_b32_e32 v101, 0
	v_mov_b32_e32 v102, 0
	v_mov_b32_e32 v103, 0
	v_mov_b32_e32 v104, 0
	v_mov_b32_e32 v105, 0
	v_mov_b32_e32 v106, 0
	v_mov_b32_e32 v107, 0
	v_mov_b32_e32 v108, 0
	v_mov_b32_e32 v109, 0
	v_mov_b32_e32 v110, 0
	v_mov_b32_e32 v111, 0
	v_mov_b32_e32 v112, 0
	v_mov_b32_e32 v113, 0
	v_mov_b32_e32 v114, 0
	v_mov_b32_e32 v115, 0
	v_mov_b32_e32 v116, 0
	v_mov_b32_e32 v117, 0
	v_mov_b32_e32 v118, 0
	v_mov_b32_e32 v119, 0
	v_mov_b32_e32 v120, 0
	v_mov_b32_e32 v121, 0
	v_mov_b32_e32 v122, 0
	v_mov_b32_e32 v123, 0
	v_mov_b32_e32 v124, 0
	v_mov_b32_e32 v125, 0
	v_mov_b32_e32 v126, 0
	v_mov_b32_e32 v127, 0
	v_mov_b32_e32 v128, 0
	v_mov_b32_e32 v129, 0
	s_waitcnt lgkmcnt(0)
	s_barrier
	v_readlane_b32 s98, v255, 16
	s_lshr_b32 s98, s98, 3
	s_and_b32 s98, s98, 3
	s_lshl_b32 s98, s98, 2
	s_lshl_b32 s99, s98, 7
	s_add_u32 s6, s6, s99
	s_addc_u32 s7, s7, 0
	s_add_u32 s8, s8, s99
	s_addc_u32 s9, s9, 0
	s_add_u32 m0, s14, 0
	s_nop 0
	global_load_lds_dwordx4 v196, s[6:7] offset:0
	global_load_lds_dwordx4 v197, s[6:7] offset:1024
	global_load_lds_dwordx4 v198, s[6:7] offset:2048
	global_load_lds_dwordx4 v199, s[6:7] offset:3072
	s_add_u32 m0, s14, 16384
	s_nop 0
	global_load_lds_dwordx4 v196, s[8:9] offset:0
	global_load_lds_dwordx4 v197, s[8:9] offset:1024
	global_load_lds_dwordx4 v198, s[8:9] offset:2048
	global_load_lds_dwordx4 v199, s[8:9] offset:3072
	s_add_u32 s99, s98, 1
	s_and_b32 s99, s99, 15
	s_sub_i32 s98, s99, s98
	s_lshl_b32 s98, s98, 7
	s_ashr_i32 s100, s98, 31
	s_add_u32 s6, s6, s98
	s_addc_u32 s7, s7, s100
	s_add_u32 s8, s8, s98
	s_addc_u32 s9, s9, s100
	s_mov_b32 s98, s99
	s_mov_b32 s25, 0
	s_waitcnt vmcnt(0)
.Lk_g1l0_loop:
	s_barrier
	s_add_u32 m0, s14, 32768
	v_mfma_f32_16x16x32_bf16 v[94:97], v[98:101], v[114:117], v[94:97]
	ds_read_b128 v[22:25], v130 offset:32
	global_load_lds_dwordx4 v196, s[6:7] offset:0
	v_mfma_f32_16x16x32_bf16 v[90:93], v[98:101], v[118:121], v[90:93]
	ds_read_b128 v[42:45], v194 offset:32
	global_load_lds_dwordx4 v197, s[6:7] offset:1024
	v_mfma_f32_16x16x32_bf16 v[86:89], v[98:101], v[122:125], v[86:89]
	ds_read_b128 v[46:49], v194 offset:2080
	global_load_lds_dwordx4 v198, s[6:7] offset:2048
	v_mfma_f32_16x16x32_bf16 v[82:85], v[98:101], v[126:129], v[82:85]
	ds_read_b128 v[26:29], v130 offset:2080
	global_load_lds_dwordx4 v199, s[6:7] offset:3072
	s_add_u32 m0, s14, 49152
	v_mfma_f32_16x16x32_bf16 v[74:77], v[102:105], v[114:117], v[74:77]
	ds_read_b128 v[50:53], v194 offset:4128
	global_load_lds_dwordx4 v196, s[8:9] offset:0
	v_mfma_f32_16x16x32_bf16 v[70:73], v[102:105], v[118:121], v[70:73]
	ds_read_b128 v[58:61], v194 offset:6176
	global_load_lds_dwordx4 v197, s[8:9] offset:1024
	v_mfma_f32_16x16x32_bf16 v[66:69], v[102:105], v[122:125], v[66:69]
	ds_read_b128 v[30:33], v130 offset:4128
	global_load_lds_dwordx4 v198, s[8:9] offset:2048
	v_mfma_f32_16x16x32_bf16 v[62:65], v[102:105], v[126:129], v[62:65]
	ds_read_b128 v[38:41], v130 offset:6176
	global_load_lds_dwordx4 v199, s[8:9] offset:3072
	v_mfma_f32_16x16x32_bf16 v[54:57], v[106:109], v[114:117], v[54:57]
	v_mfma_f32_16x16x32_bf16 v[34:37], v[106:109], v[118:121], v[34:37]
	v_mfma_f32_16x16x32_bf16 v[18:21], v[106:109], v[122:125], v[18:21]
	v_mfma_f32_16x16x32_bf16 v[14:17], v[106:109], v[126:129], v[14:17]
	v_mfma_f32_16x16x32_bf16 v[10:13], v[110:113], v[114:117], v[10:13]
	v_mfma_f32_16x16x32_bf16 v[6:9], v[110:113], v[118:121], v[6:9]
	v_mfma_f32_16x16x32_bf16 v[2:5], v[110:113], v[122:125], v[2:5]
	v_mfma_f32_16x16x32_bf16 v[78:81], v[110:113], v[126:129], v[78:81]
	s_add_u32 s99, s98, 1
	s_and_b32 s99, s99, 15
	s_sub_i32 s98, s99, s98
	s_lshl_b32 s98, s98, 7
	s_ashr_i32 s100, s98, 31
	s_add_u32 s6, s6, s98
	s_addc_u32 s7, s7, s100
	s_add_u32 s8, s8, s98
	s_addc_u32 s9, s9, s100
	s_mov_b32 s98, s99
	s_waitcnt lgkmcnt(0)
	v_mfma_f32_16x16x32_bf16 v[94:97], v[22:25], v[42:45], v[94:97]
	ds_read_b128 v[98:101], v161 offset:32
	v_mfma_f32_16x16x32_bf16 v[90:93], v[22:25], v[46:49], v[90:93]
	ds_read_b128 v[114:117], v195 offset:32
	v_mfma_f32_16x16x32_bf16 v[86:89], v[22:25], v[50:53], v[86:89]
	ds_read_b128 v[118:121], v195 offset:2080
	v_mfma_f32_16x16x32_bf16 v[82:85], v[22:25], v[58:61], v[82:85]
	ds_read_b128 v[102:105], v161 offset:2080
	v_mfma_f32_16x16x32_bf16 v[74:77], v[26:29], v[42:45], v[74:77]
	ds_read_b128 v[122:125], v195 offset:4128
	v_mfma_f32_16x16x32_bf16 v[70:73], v[26:29], v[46:49], v[70:73]
	ds_read_b128 v[126:129], v195 offset:6176
	v_mfma_f32_16x16x32_bf16 v[66:69], v[26:29], v[50:53], v[66:69]
	ds_read_b128 v[106:109], v161 offset:4128
	v_mfma_f32_16x16x32_bf16 v[62:65], v[26:29], v[58:61], v[62:65]
	ds_read_b128 v[110:113], v161 offset:6176
	v_mfma_f32_16x16x32_bf16 v[54:57], v[30:33], v[42:45], v[54:57]
	v_mfma_f32_16x16x32_bf16 v[34:37], v[30:33], v[46:49], v[34:37]
	v_mfma_f32_16x16x32_bf16 v[18:21], v[30:33], v[50:53], v[18:21]
	v_mfma_f32_16x16x32_bf16 v[14:17], v[30:33], v[58:61], v[14:17]
	v_mfma_f32_16x16x32_bf16 v[10:13], v[38:41], v[42:45], v[10:13]
	v_mfma_f32_16x16x32_bf16 v[6:9], v[38:41], v[46:49], v[6:9]
	v_mfma_f32_16x16x32_bf16 v[2:5], v[38:41], v[50:53], v[2:5]
	v_mfma_f32_16x16x32_bf16 v[78:81], v[38:41], v[58:61], v[78:81]
	s_waitcnt lgkmcnt(0)
	s_waitcnt vmcnt(0)
	s_barrier
	s_add_u32 m0, s14, 0
	v_mfma_f32_16x16x32_bf16 v[94:97], v[98:101], v[114:117], v[94:97]
	ds_read_b128 v[22:25], v130 offset:32800
	global_load_lds_dwordx4 v196, s[6:7] offset:0
	v_mfma_f32_16x16x32_bf16 v[90:93], v[98:101], v[118:121], v[90:93]
	ds_read_b128 v[42:45], v194 offset:32800
	global_load_lds_dwordx4 v197, s[6:7] offset:1024
	v_mfma_f32_16x16x32_bf16 v[86:89], v[98:101], v[122:125], v[86:89]
	ds_read_b128 v[46:49], v194 offset:34848
	global_load_lds_dwordx4 v198, s[6:7] offset:2048
	v_mfma_f32_16x16x32_bf16 v[82:85], v[98:101], v[126:129], v[82:85]
	ds_read_b128 v[26:29], v130 offset:34848
	global_load_lds_dwordx4 v199, s[6:7] offset:3072
	s_add_u32 m0, s14, 16384
	v_mfma_f32_16x16x32_bf16 v[74:77], v[102:105], v[114:117], v[74:77]
	ds_read_b128 v[50:53], v194 offset:36896
	global_load_lds_dwordx4 v196, s[8:9] offset:0
	v_mfma_f32_16x16x32_bf16 v[70:73], v[102:105], v[118:121], v[70:73]
	ds_read_b128 v[58:61], v194 offset:38944
	global_load_lds_dwordx4 v197, s[8:9] offset:1024
	v_mfma_f32_16x16x32_bf16 v[66:69], v[102:105], v[122:125], v[66:69]
	ds_read_b128 v[30:33], v130 offset:36896
	global_load_lds_dwordx4 v198, s[8:9] offset:2048
	v_mfma_f32_16x16x32_bf16 v[62:65], v[102:105], v[126:129], v[62:65]
	ds_read_b128 v[38:41], v130 offset:38944
	global_load_lds_dwordx4 v199, s[8:9] offset:3072
	v_mfma_f32_16x16x32_bf16 v[54:57], v[106:109], v[114:117], v[54:57]
	v_mfma_f32_16x16x32_bf16 v[34:37], v[106:109], v[118:121], v[34:37]
	v_mfma_f32_16x16x32_bf16 v[18:21], v[106:109], v[122:125], v[18:21]
	v_mfma_f32_16x16x32_bf16 v[14:17], v[106:109], v[126:129], v[14:17]
	v_mfma_f32_16x16x32_bf16 v[10:13], v[110:113], v[114:117], v[10:13]
	v_mfma_f32_16x16x32_bf16 v[6:9], v[110:113], v[118:121], v[6:9]
	v_mfma_f32_16x16x32_bf16 v[2:5], v[110:113], v[122:125], v[2:5]
	v_mfma_f32_16x16x32_bf16 v[78:81], v[110:113], v[126:129], v[78:81]
	s_add_u32 s99, s98, 1
	s_and_b32 s99, s99, 15
	s_sub_i32 s98, s99, s98
	s_lshl_b32 s98, s98, 7
	s_ashr_i32 s100, s98, 31
	s_add_u32 s6, s6, s98
	s_addc_u32 s7, s7, s100
	s_add_u32 s8, s8, s98
	s_addc_u32 s9, s9, s100
	s_mov_b32 s98, s99
	s_waitcnt lgkmcnt(0)
	v_mfma_f32_16x16x32_bf16 v[94:97], v[22:25], v[42:45], v[94:97]
	ds_read_b128 v[98:101], v161 offset:32800
	v_mfma_f32_16x16x32_bf16 v[90:93], v[22:25], v[46:49], v[90:93]
	ds_read_b128 v[114:117], v195 offset:32800
	v_mfma_f32_16x16x32_bf16 v[86:89], v[22:25], v[50:53], v[86:89]
	ds_read_b128 v[118:121], v195 offset:34848
	v_mfma_f32_16x16x32_bf16 v[82:85], v[22:25], v[58:61], v[82:85]
	ds_read_b128 v[102:105], v161 offset:34848
	v_mfma_f32_16x16x32_bf16 v[74:77], v[26:29], v[42:45], v[74:77]
	ds_read_b128 v[122:125], v195 offset:36896
	v_mfma_f32_16x16x32_bf16 v[70:73], v[26:29], v[46:49], v[70:73]
	ds_read_b128 v[126:129], v195 offset:38944
	v_mfma_f32_16x16x32_bf16 v[66:69], v[26:29], v[50:53], v[66:69]
	ds_read_b128 v[106:109], v161 offset:36896
	v_mfma_f32_16x16x32_bf16 v[62:65], v[26:29], v[58:61], v[62:65]
	ds_read_b128 v[110:113], v161 offset:38944
	v_mfma_f32_16x16x32_bf16 v[54:57], v[30:33], v[42:45], v[54:57]
	v_mfma_f32_16x16x32_bf16 v[34:37], v[30:33], v[46:49], v[34:37]
	v_mfma_f32_16x16x32_bf16 v[18:21], v[30:33], v[50:53], v[18:21]
	v_mfma_f32_16x16x32_bf16 v[14:17], v[30:33], v[58:61], v[14:17]
	v_mfma_f32_16x16x32_bf16 v[10:13], v[38:41], v[42:45], v[10:13]
	v_mfma_f32_16x16x32_bf16 v[6:9], v[38:41], v[46:49], v[6:9]
	v_mfma_f32_16x16x32_bf16 v[2:5], v[38:41], v[50:53], v[2:5]
	v_mfma_f32_16x16x32_bf16 v[78:81], v[38:41], v[58:61], v[78:81]
	s_waitcnt lgkmcnt(0)
	s_waitcnt vmcnt(0)
	s_add_u32 s25, s25, 1
	s_cmp_lt_u32 s25, 7
	s_cbranch_scc1 .Lk_g1l0_loop
	s_barrier
	s_add_u32 m0, s14, 32768
	v_mfma_f32_16x16x32_bf16 v[94:97], v[98:101], v[114:117], v[94:97]
	ds_read_b128 v[22:25], v130 offset:32
	global_load_lds_dwordx4 v196, s[6:7] offset:0
	v_mfma_f32_16x16x32_bf16 v[90:93], v[98:101], v[118:121], v[90:93]
	ds_read_b128 v[42:45], v194 offset:32
	global_load_lds_dwordx4 v197, s[6:7] offset:1024
	v_mfma_f32_16x16x32_bf16 v[86:89], v[98:101], v[122:125], v[86:89]
	ds_read_b128 v[46:49], v194 offset:2080
	global_load_lds_dwordx4 v198, s[6:7] offset:2048
	v_mfma_f32_16x16x32_bf16 v[82:85], v[98:101], v[126:129], v[82:85]
	ds_read_b128 v[26:29], v130 offset:2080
	global_load_lds_dwordx4 v199, s[6:7] offset:3072
	s_add_u32 m0, s14, 49152
	v_mfma_f32_16x16x32_bf16 v[74:77], v[102:105], v[114:117], v[74:77]
	ds_read_b128 v[50:53], v194 offset:4128
	global_load_lds_dwordx4 v196, s[8:9] offset:0
	v_mfma_f32_16x16x32_bf16 v[70:73], v[102:105], v[118:121], v[70:73]
	ds_read_b128 v[58:61], v194 offset:6176
	global_load_lds_dwordx4 v197, s[8:9] offset:1024
	v_mfma_f32_16x16x32_bf16 v[66:69], v[102:105], v[122:125], v[66:69]
	ds_read_b128 v[30:33], v130 offset:4128
	global_load_lds_dwordx4 v198, s[8:9] offset:2048
	v_mfma_f32_16x16x32_bf16 v[62:65], v[102:105], v[126:129], v[62:65]
	ds_read_b128 v[38:41], v130 offset:6176
	global_load_lds_dwordx4 v199, s[8:9] offset:3072
	v_mfma_f32_16x16x32_bf16 v[54:57], v[106:109], v[114:117], v[54:57]
	v_mfma_f32_16x16x32_bf16 v[34:37], v[106:109], v[118:121], v[34:37]
	v_mfma_f32_16x16x32_bf16 v[18:21], v[106:109], v[122:125], v[18:21]
	v_mfma_f32_16x16x32_bf16 v[14:17], v[106:109], v[126:129], v[14:17]
	v_mfma_f32_16x16x32_bf16 v[10:13], v[110:113], v[114:117], v[10:13]
	v_mfma_f32_16x16x32_bf16 v[6:9], v[110:113], v[118:121], v[6:9]
	v_mfma_f32_16x16x32_bf16 v[2:5], v[110:113], v[122:125], v[2:5]
	v_mfma_f32_16x16x32_bf16 v[78:81], v[110:113], v[126:129], v[78:81]
	s_add_u32 s99, s98, 1
	s_and_b32 s99, s99, 15
	s_sub_i32 s98, s99, s98
	s_lshl_b32 s98, s98, 7
	s_ashr_i32 s100, s98, 31
	s_add_u32 s6, s6, s98
	s_addc_u32 s7, s7, s100
	s_add_u32 s8, s8, s98
	s_addc_u32 s9, s9, s100
	s_mov_b32 s98, s99
	s_waitcnt lgkmcnt(0)
	v_mfma_f32_16x16x32_bf16 v[94:97], v[22:25], v[42:45], v[94:97]
	ds_read_b128 v[98:101], v161 offset:32
	v_mfma_f32_16x16x32_bf16 v[90:93], v[22:25], v[46:49], v[90:93]
	ds_read_b128 v[114:117], v195 offset:32
	v_mfma_f32_16x16x32_bf16 v[86:89], v[22:25], v[50:53], v[86:89]
	ds_read_b128 v[118:121], v195 offset:2080
	v_mfma_f32_16x16x32_bf16 v[82:85], v[22:25], v[58:61], v[82:85]
	ds_read_b128 v[102:105], v161 offset:2080
	v_mfma_f32_16x16x32_bf16 v[74:77], v[26:29], v[42:45], v[74:77]
	ds_read_b128 v[122:125], v195 offset:4128
	v_mfma_f32_16x16x32_bf16 v[70:73], v[26:29], v[46:49], v[70:73]
	ds_read_b128 v[126:129], v195 offset:6176
	v_mfma_f32_16x16x32_bf16 v[66:69], v[26:29], v[50:53], v[66:69]
	ds_read_b128 v[106:109], v161 offset:4128
	v_mfma_f32_16x16x32_bf16 v[62:65], v[26:29], v[58:61], v[62:65]
	ds_read_b128 v[110:113], v161 offset:6176
	v_mfma_f32_16x16x32_bf16 v[54:57], v[30:33], v[42:45], v[54:57]
	v_mfma_f32_16x16x32_bf16 v[34:37], v[30:33], v[46:49], v[34:37]
	v_mfma_f32_16x16x32_bf16 v[18:21], v[30:33], v[50:53], v[18:21]
	v_mfma_f32_16x16x32_bf16 v[14:17], v[30:33], v[58:61], v[14:17]
	v_mfma_f32_16x16x32_bf16 v[10:13], v[38:41], v[42:45], v[10:13]
	v_mfma_f32_16x16x32_bf16 v[6:9], v[38:41], v[46:49], v[6:9]
	v_mfma_f32_16x16x32_bf16 v[2:5], v[38:41], v[50:53], v[2:5]
	v_mfma_f32_16x16x32_bf16 v[78:81], v[38:41], v[58:61], v[78:81]
	s_waitcnt lgkmcnt(0)
	s_waitcnt vmcnt(0)
	s_barrier
	v_mfma_f32_16x16x32_bf16 v[94:97], v[98:101], v[114:117], v[94:97]
	ds_read_b128 v[22:25], v130 offset:32800
	v_mfma_f32_16x16x32_bf16 v[90:93], v[98:101], v[118:121], v[90:93]
	ds_read_b128 v[42:45], v194 offset:32800
	v_mfma_f32_16x16x32_bf16 v[86:89], v[98:101], v[122:125], v[86:89]
	ds_read_b128 v[46:49], v194 offset:34848
	v_mfma_f32_16x16x32_bf16 v[82:85], v[98:101], v[126:129], v[82:85]
	ds_read_b128 v[26:29], v130 offset:34848
	v_mfma_f32_16x16x32_bf16 v[74:77], v[102:105], v[114:117], v[74:77]
	ds_read_b128 v[50:53], v194 offset:36896
	v_mfma_f32_16x16x32_bf16 v[70:73], v[102:105], v[118:121], v[70:73]
	ds_read_b128 v[58:61], v194 offset:38944
	v_mfma_f32_16x16x32_bf16 v[66:69], v[102:105], v[122:125], v[66:69]
	ds_read_b128 v[30:33], v130 offset:36896
	v_mfma_f32_16x16x32_bf16 v[62:65], v[102:105], v[126:129], v[62:65]
	ds_read_b128 v[38:41], v130 offset:38944
	v_mfma_f32_16x16x32_bf16 v[54:57], v[106:109], v[114:117], v[54:57]
	v_mfma_f32_16x16x32_bf16 v[34:37], v[106:109], v[118:121], v[34:37]
	v_mfma_f32_16x16x32_bf16 v[18:21], v[106:109], v[122:125], v[18:21]
	v_mfma_f32_16x16x32_bf16 v[14:17], v[106:109], v[126:129], v[14:17]
	v_mfma_f32_16x16x32_bf16 v[10:13], v[110:113], v[114:117], v[10:13]
	v_mfma_f32_16x16x32_bf16 v[6:9], v[110:113], v[118:121], v[6:9]
	v_mfma_f32_16x16x32_bf16 v[2:5], v[110:113], v[122:125], v[2:5]
	v_mfma_f32_16x16x32_bf16 v[78:81], v[110:113], v[126:129], v[78:81]
	s_waitcnt lgkmcnt(0)
	v_mfma_f32_16x16x32_bf16 v[94:97], v[22:25], v[42:45], v[94:97]
	ds_read_b128 v[98:101], v161 offset:32800
	v_mfma_f32_16x16x32_bf16 v[90:93], v[22:25], v[46:49], v[90:93]
	ds_read_b128 v[114:117], v195 offset:32800
	v_mfma_f32_16x16x32_bf16 v[86:89], v[22:25], v[50:53], v[86:89]
	ds_read_b128 v[118:121], v195 offset:34848
	v_mfma_f32_16x16x32_bf16 v[82:85], v[22:25], v[58:61], v[82:85]
	ds_read_b128 v[102:105], v161 offset:34848
	v_mfma_f32_16x16x32_bf16 v[74:77], v[26:29], v[42:45], v[74:77]
	ds_read_b128 v[122:125], v195 offset:36896
	v_mfma_f32_16x16x32_bf16 v[70:73], v[26:29], v[46:49], v[70:73]
	ds_read_b128 v[126:129], v195 offset:38944
	v_mfma_f32_16x16x32_bf16 v[66:69], v[26:29], v[50:53], v[66:69]
	ds_read_b128 v[106:109], v161 offset:36896
	v_mfma_f32_16x16x32_bf16 v[62:65], v[26:29], v[58:61], v[62:65]
	ds_read_b128 v[110:113], v161 offset:38944
	v_mfma_f32_16x16x32_bf16 v[54:57], v[30:33], v[42:45], v[54:57]
	v_mfma_f32_16x16x32_bf16 v[34:37], v[30:33], v[46:49], v[34:37]
	v_mfma_f32_16x16x32_bf16 v[18:21], v[30:33], v[50:53], v[18:21]
	v_mfma_f32_16x16x32_bf16 v[14:17], v[30:33], v[58:61], v[14:17]
	v_mfma_f32_16x16x32_bf16 v[10:13], v[38:41], v[42:45], v[10:13]
	v_mfma_f32_16x16x32_bf16 v[6:9], v[38:41], v[46:49], v[6:9]
	v_mfma_f32_16x16x32_bf16 v[2:5], v[38:41], v[50:53], v[2:5]
	v_mfma_f32_16x16x32_bf16 v[78:81], v[38:41], v[58:61], v[78:81]
	s_waitcnt lgkmcnt(0)
	v_mfma_f32_16x16x32_bf16 v[94:97], v[98:101], v[114:117], v[94:97]
	v_mfma_f32_16x16x32_bf16 v[90:93], v[98:101], v[118:121], v[90:93]
	v_mfma_f32_16x16x32_bf16 v[86:89], v[98:101], v[122:125], v[86:89]
	v_mfma_f32_16x16x32_bf16 v[82:85], v[98:101], v[126:129], v[82:85]
	v_mfma_f32_16x16x32_bf16 v[74:77], v[102:105], v[114:117], v[74:77]
	v_mfma_f32_16x16x32_bf16 v[70:73], v[102:105], v[118:121], v[70:73]
	v_mfma_f32_16x16x32_bf16 v[66:69], v[102:105], v[122:125], v[66:69]
	v_mfma_f32_16x16x32_bf16 v[62:65], v[102:105], v[126:129], v[62:65]
	v_mfma_f32_16x16x32_bf16 v[54:57], v[106:109], v[114:117], v[54:57]
	v_mfma_f32_16x16x32_bf16 v[34:37], v[106:109], v[118:121], v[34:37]
	v_mfma_f32_16x16x32_bf16 v[18:21], v[106:109], v[122:125], v[18:21]
	v_mfma_f32_16x16x32_bf16 v[14:17], v[106:109], v[126:129], v[14:17]
	v_mfma_f32_16x16x32_bf16 v[10:13], v[110:113], v[114:117], v[10:13]
	v_mfma_f32_16x16x32_bf16 v[6:9], v[110:113], v[118:121], v[6:9]
	v_mfma_f32_16x16x32_bf16 v[2:5], v[110:113], v[122:125], v[2:5]
	v_mfma_f32_16x16x32_bf16 v[78:81], v[110:113], v[126:129], v[78:81]
	s_waitcnt vmcnt(7)
	v_add_u32_e32 v22, 0x400, v168
	s_barrier
	ds_write2_b32 v168, v94, v90 offset1:16
	ds_write2_b32 v168, v95, v91 offset0:132 offset1:148
	ds_write2_b32 v22, v96, v92 offset0:8 offset1:24
	ds_write2_b32 v22, v97, v93 offset0:140 offset1:156
	ds_write2_b32 v168, v86, v82 offset0:32 offset1:48
	ds_write2_b32 v168, v87, v83 offset0:164 offset1:180
	ds_write2_b32 v22, v88, v84 offset0:40 offset1:56
	ds_write2_b32 v22, v89, v85 offset0:172 offset1:188
	v_add_u32_e32 v22, 0x2000, v168
	v_add_u32_e32 v23, 0x2400, v168
	s_cmp_gt_i32 s67, 63
	ds_write2_b32 v22, v74, v70 offset0:64 offset1:80
	ds_write2_b32 v22, v75, v71 offset0:196 offset1:212
	ds_write2_b32 v23, v76, v72 offset0:72 offset1:88
	ds_write2_b32 v23, v77, v73 offset0:204 offset1:220
	ds_write2_b32 v22, v66, v62 offset0:96 offset1:112
	ds_write2_b32 v22, v67, v63 offset0:228 offset1:244
	ds_write2_b32 v23, v68, v64 offset0:104 offset1:120
	ds_write2_b32 v23, v69, v65 offset0:236 offset1:252
	v_add_u32_e32 v22, 0x4000, v168
	v_add_u32_e32 v23, 0x4400, v168
	v_add_u32_e32 v24, 0x4800, v168
	s_cselect_b64 s[34:35], -1, 0
	s_cmp_lt_i32 s67, 64
	ds_write2_b32 v22, v54, v34 offset0:128 offset1:144
	ds_write2_b32 v23, v55, v35 offset0:4 offset1:20
	ds_write2_b32 v23, v56, v36 offset0:136 offset1:152
	ds_write2_b32 v24, v57, v37 offset0:12 offset1:28
	ds_write2_b32 v22, v18, v14 offset0:160 offset1:176
	ds_write2_b32 v23, v19, v15 offset0:36 offset1:52
	ds_write2_b32 v23, v20, v16 offset0:168 offset1:184
	ds_write2_b32 v24, v21, v17 offset0:44 offset1:60
	v_add_u32_e32 v14, 0x6000, v168
	s_cselect_b64 s[46:47], -1, 0
	s_add_i32 s6, s28, 0xffffe000
	ds_write2_b32 v14, v10, v6 offset0:192 offset1:208
	v_add_u32_e32 v6, 0x6400, v168
	s_lshr_b32 s68, s6, 10
	s_ashr_i32 s30, s67, 1
	s_and_b32 s69, s28, 0x380
	s_and_b32 s25, s28, 0x80
	ds_write2_b32 v6, v11, v7 offset0:68 offset1:84
	ds_write2_b32 v6, v12, v8 offset0:200 offset1:216
	v_add_u32_e32 v7, 0x6800, v168
	v_add_u32_e32 v162, s28, v165
	s_cmp_gt_i32 s24, 9
	s_mov_b64 s[6:7], -1
	ds_write2_b32 v7, v13, v9 offset0:76 offset1:92
	ds_write2_b32 v14, v2, v78 offset0:224 offset1:240
	ds_write2_b32 v6, v3, v79 offset0:100 offset1:116
	ds_write2_b32 v6, v4, v80 offset0:232 offset1:248
	ds_write2_b32 v7, v5, v81 offset0:108 offset1:124
	s_waitcnt lgkmcnt(0)
	s_barrier
	s_cbranch_scc0 .LBB0_239
	s_cmp_gt_u32 s24, 11
	s_cbranch_scc0 .LBB0_224
	s_cmp_lg_u32 s24, 36
	s_cbranch_scc0 .LBB0_219
	s_sub_i32 s6, s24, 20
	s_cmp_gt_u32 s6, 7
	s_mov_b64 s[6:7], -1
	s_cbranch_scc0 .LBB0_215
	s_cmp_lt_u32 s24, 16
	s_cselect_b64 s[48:49], -1, 0
	s_cmp_gt_u32 s24, 15
	s_mov_b64 s[54:55], -1
	s_cbranch_scc0 .LBB0_202
	s_cmp_gt_u32 s24, 19
	s_cbranch_scc0 .LBB0_199
	s_mov_b64 s[50:51], -1
	s_cmp_gt_u32 s24, 35
	s_mov_b64 s[8:9], -1
	s_cbranch_scc0 .LBB0_197
	s_lshl_b64 s[6:7], s[28:29], 12
	s_add_u32 s6, s42, s6
	s_addc_u32 s7, s43, s7
	s_mov_b64 s[8:9], 0

.LBB0_552:
	s_and_b32 s34, s33, 0xff
	s_mul_i32 s4, s34, 0xab
	s_lshr_b32 s47, s4, 11
	s_mul_i32 s4, s47, 12
	s_sub_i32 s4, s33, s4
	s_and_b32 s4, s4, 0xff
	s_lshl_b32 s4, s4, 10
	s_or_b32 s48, s4, s15
	s_lshl_b32 s35, s48, 10
	s_lshl_b32 s4, s48, 11
	s_add_u32 s10, s16, s4
	s_addc_u32 s11, s17, 0
	s_lshl_b32 s46, s47, 17
	s_lshl_b32 s4, s47, 18
	s_add_u32 s12, s18, s4
	s_addc_u32 s13, s19, 0
	v_and_b32_e32 v164, 15, v0
	v_bfe_u32 v165, v0, 4, 2
	v_and_b32_e32 v111, 7, v164
	v_xor_b32_e32 v165, v165, v111
	v_lshlrev_b32_e32 v165, 4, v165
	v_lshl_or_b32 v165, v164, 7, v165
	v_bfe_u32 v164, v0, 7, 1
	v_lshl_or_b32 v100, v164, 13, v165
	v_bfe_u32 v164, v0, 6, 1
	v_lshl_or_b32 v158, v164, 13, v165
	v_or_b32_e32 v158, 0x4000, v158
	v_xor_b32_e32 v111, 64, v100
	v_xor_b32_e32 v159, 64, v158
	v_bfe_u32 v164, v0, 3, 3
	v_and_b32_e32 v165, 7, v0
	v_xor_b32_e32 v165, v165, v164
	v_lshlrev_b32_e32 v165, 4, v165
	v_lshl_or_b32 v165, v164, 11, v165
	v_lshrrev_b32_e32 v164, 6, v0
	v_and_b32_e32 v164, 3, v164
	v_lshl_or_b32 v160, v164, 16, v165
	v_add_u32_e32 v161, 0x3c00, v160
	v_add_u32_e32 v162, 0x7800, v160
	v_add_u32_e32 v163, 0xb400, v160
	v_lshlrev_b32_e32 v164, 12, v164
	s_nop 0
	v_readfirstlane_b32 s50, v164
	s_add_u32 s50, s50, 32
	v_mov_b32_e32 v94, 0
	v_mov_b32_e32 v95, 0
	v_mov_b32_e32 v96, 0
	v_mov_b32_e32 v97, 0
	v_mov_b32_e32 v90, 0
	v_mov_b32_e32 v91, 0
	v_mov_b32_e32 v92, 0
	v_mov_b32_e32 v93, 0
	v_mov_b32_e32 v82, 0
	v_mov_b32_e32 v83, 0
	v_mov_b32_e32 v84, 0
	v_mov_b32_e32 v85, 0
	v_mov_b32_e32 v78, 0
	v_mov_b32_e32 v79, 0
	v_mov_b32_e32 v80, 0
	v_mov_b32_e32 v81, 0
	v_mov_b32_e32 v74, 0
	v_mov_b32_e32 v75, 0
	v_mov_b32_e32 v76, 0
	v_mov_b32_e32 v77, 0
	v_mov_b32_e32 v70, 0
	v_mov_b32_e32 v71, 0
	v_mov_b32_e32 v72, 0
	v_mov_b32_e32 v73, 0
	v_mov_b32_e32 v66, 0
	v_mov_b32_e32 v67, 0
	v_mov_b32_e32 v68, 0
	v_mov_b32_e32 v69, 0
	v_mov_b32_e32 v58, 0
	v_mov_b32_e32 v59, 0
	v_mov_b32_e32 v60, 0
	v_mov_b32_e32 v61, 0
	v_mov_b32_e32 v26, 0
	v_mov_b32_e32 v27, 0
	v_mov_b32_e32 v28, 0
	v_mov_b32_e32 v29, 0
	v_mov_b32_e32 v22, 0
	v_mov_b32_e32 v23, 0
	v_mov_b32_e32 v24, 0
	v_mov_b32_e32 v25, 0
	v_mov_b32_e32 v18, 0
	v_mov_b32_e32 v19, 0
	v_mov_b32_e32 v20, 0
	v_mov_b32_e32 v21, 0
	v_mov_b32_e32 v14, 0
	v_mov_b32_e32 v15, 0
	v_mov_b32_e32 v16, 0
	v_mov_b32_e32 v17, 0
	v_mov_b32_e32 v10, 0
	v_mov_b32_e32 v11, 0
	v_mov_b32_e32 v12, 0
	v_mov_b32_e32 v13, 0
	v_mov_b32_e32 v6, 0
	v_mov_b32_e32 v7, 0
	v_mov_b32_e32 v8, 0
	v_mov_b32_e32 v9, 0
	v_mov_b32_e32 v2, 0
	v_mov_b32_e32 v3, 0
	v_mov_b32_e32 v4, 0
	v_mov_b32_e32 v5, 0
	v_mov_b32_e32 v86, 0
	v_mov_b32_e32 v87, 0
	v_mov_b32_e32 v88, 0
	v_mov_b32_e32 v89, 0
	v_mov_b32_e32 v114, 0
	v_mov_b32_e32 v115, 0
	v_mov_b32_e32 v116, 0
	v_mov_b32_e32 v117, 0
	v_mov_b32_e32 v118, 0
	v_mov_b32_e32 v119, 0
	v_mov_b32_e32 v120, 0
	v_mov_b32_e32 v121, 0
	v_mov_b32_e32 v122, 0
	v_mov_b32_e32 v123, 0
	v_mov_b32_e32 v124, 0
	v_mov_b32_e32 v125, 0
	v_mov_b32_e32 v138, 0
	v_mov_b32_e32 v139, 0
	v_mov_b32_e32 v140, 0
	v_mov_b32_e32 v141, 0
	v_mov_b32_e32 v142, 0
	v_mov_b32_e32 v143, 0
	v_mov_b32_e32 v144, 0
	v_mov_b32_e32 v145, 0
	v_mov_b32_e32 v146, 0
	v_mov_b32_e32 v147, 0
	v_mov_b32_e32 v148, 0
	v_mov_b32_e32 v149, 0
	v_mov_b32_e32 v150, 0
	v_mov_b32_e32 v151, 0
	v_mov_b32_e32 v152, 0
	v_mov_b32_e32 v153, 0
	v_mov_b32_e32 v154, 0
	v_mov_b32_e32 v155, 0
	v_mov_b32_e32 v156, 0
	v_mov_b32_e32 v157, 0
	s_waitcnt lgkmcnt(0)
	s_barrier
	v_readlane_b32 s98, v255, 16
	s_lshr_b32 s98, s98, 3
	s_and_b32 s98, s98, 3
	s_lshl_b32 s98, s98, 2
	s_lshl_b32 s99, s98, 7
	s_add_u32 s10, s10, s99
	s_addc_u32 s11, s11, 0
	s_add_u32 s12, s12, s99
	s_addc_u32 s13, s13, 0
	s_add_u32 m0, s50, 0
	s_nop 0
	global_load_lds_dwordx4 v160, s[10:11] offset:0
	global_load_lds_dwordx4 v161, s[10:11] offset:1024
	global_load_lds_dwordx4 v162, s[10:11] offset:2048
	global_load_lds_dwordx4 v163, s[10:11] offset:3072
	s_add_u32 m0, s50, 16384
	s_nop 0
	global_load_lds_dwordx4 v160, s[12:13] offset:0
	global_load_lds_dwordx4 v161, s[12:13] offset:1024
	global_load_lds_dwordx4 v162, s[12:13] offset:2048
	global_load_lds_dwordx4 v163, s[12:13] offset:3072
	s_add_u32 s99, s98, 1
	s_and_b32 s99, s99, 15
	s_sub_i32 s98, s99, s98
	s_lshl_b32 s98, s98, 7
	s_ashr_i32 s100, s98, 31
	s_add_u32 s10, s10, s98
	s_addc_u32 s11, s11, s100
	s_add_u32 s12, s12, s98
	s_addc_u32 s13, s13, s100
	s_mov_b32 s98, s99
	s_mov_b32 s49, 0
	s_waitcnt vmcnt(0)
.Lk_aol0a_loop:
	s_barrier
	s_add_u32 m0, s50, 32768
	v_mfma_f32_16x16x32_bf16 v[94:97], v[114:117], v[142:145], v[94:97]
	ds_read_b128 v[30:33], v100 offset:32
	global_load_lds_dwordx4 v160, s[10:11] offset:0
	v_mfma_f32_16x16x32_bf16 v[90:93], v[114:117], v[146:149], v[90:93]
	ds_read_b128 v[46:49], v158 offset:32
	global_load_lds_dwordx4 v161, s[10:11] offset:1024
	v_mfma_f32_16x16x32_bf16 v[82:85], v[114:117], v[150:153], v[82:85]
	ds_read_b128 v[50:53], v158 offset:2080
	global_load_lds_dwordx4 v162, s[10:11] offset:2048
	v_mfma_f32_16x16x32_bf16 v[78:81], v[114:117], v[154:157], v[78:81]
	ds_read_b128 v[34:37], v100 offset:2080
	global_load_lds_dwordx4 v163, s[10:11] offset:3072
	s_add_u32 m0, s50, 49152
	v_mfma_f32_16x16x32_bf16 v[74:77], v[118:121], v[142:145], v[74:77]
	ds_read_b128 v[54:57], v158 offset:4128
	global_load_lds_dwordx4 v160, s[12:13] offset:0
	v_mfma_f32_16x16x32_bf16 v[70:73], v[118:121], v[146:149], v[70:73]
	ds_read_b128 v[62:65], v158 offset:6176
	global_load_lds_dwordx4 v161, s[12:13] offset:1024
	v_mfma_f32_16x16x32_bf16 v[66:69], v[118:121], v[150:153], v[66:69]
	ds_read_b128 v[38:41], v100 offset:4128
	global_load_lds_dwordx4 v162, s[12:13] offset:2048
	v_mfma_f32_16x16x32_bf16 v[58:61], v[118:121], v[154:157], v[58:61]
	ds_read_b128 v[42:45], v100 offset:6176
	global_load_lds_dwordx4 v163, s[12:13] offset:3072
	v_mfma_f32_16x16x32_bf16 v[26:29], v[122:125], v[142:145], v[26:29]
	v_mfma_f32_16x16x32_bf16 v[22:25], v[122:125], v[146:149], v[22:25]
	v_mfma_f32_16x16x32_bf16 v[18:21], v[122:125], v[150:153], v[18:21]
	v_mfma_f32_16x16x32_bf16 v[14:17], v[122:125], v[154:157], v[14:17]
	v_mfma_f32_16x16x32_bf16 v[10:13], v[138:141], v[142:145], v[10:13]
	v_mfma_f32_16x16x32_bf16 v[6:9], v[138:141], v[146:149], v[6:9]
	v_mfma_f32_16x16x32_bf16 v[2:5], v[138:141], v[150:153], v[2:5]
	v_mfma_f32_16x16x32_bf16 v[86:89], v[138:141], v[154:157], v[86:89]
	s_add_u32 s99, s98, 1
	s_and_b32 s99, s99, 15
	s_sub_i32 s98, s99, s98
	s_lshl_b32 s98, s98, 7
	s_ashr_i32 s100, s98, 31
	s_add_u32 s10, s10, s98
	s_addc_u32 s11, s11, s100
	s_add_u32 s12, s12, s98
	s_addc_u32 s13, s13, s100
	s_mov_b32 s98, s99
	s_waitcnt lgkmcnt(0)
	v_mfma_f32_16x16x32_bf16 v[94:97], v[30:33], v[46:49], v[94:97]
	ds_read_b128 v[114:117], v111 offset:32
	v_mfma_f32_16x16x32_bf16 v[90:93], v[30:33], v[50:53], v[90:93]
	ds_read_b128 v[142:145], v159 offset:32
	v_mfma_f32_16x16x32_bf16 v[82:85], v[30:33], v[54:57], v[82:85]
	ds_read_b128 v[146:149], v159 offset:2080
	v_mfma_f32_16x16x32_bf16 v[78:81], v[30:33], v[62:65], v[78:81]
	ds_read_b128 v[118:121], v111 offset:2080
	v_mfma_f32_16x16x32_bf16 v[74:77], v[34:37], v[46:49], v[74:77]
	ds_read_b128 v[150:153], v159 offset:4128
	v_mfma_f32_16x16x32_bf16 v[70:73], v[34:37], v[50:53], v[70:73]
	ds_read_b128 v[154:157], v159 offset:6176
	v_mfma_f32_16x16x32_bf16 v[66:69], v[34:37], v[54:57], v[66:69]
	ds_read_b128 v[122:125], v111 offset:4128
	v_mfma_f32_16x16x32_bf16 v[58:61], v[34:37], v[62:65], v[58:61]
	ds_read_b128 v[138:141], v111 offset:6176
	v_mfma_f32_16x16x32_bf16 v[26:29], v[38:41], v[46:49], v[26:29]
	v_mfma_f32_16x16x32_bf16 v[22:25], v[38:41], v[50:53], v[22:25]
	v_mfma_f32_16x16x32_bf16 v[18:21], v[38:41], v[54:57], v[18:21]
	v_mfma_f32_16x16x32_bf16 v[14:17], v[38:41], v[62:65], v[14:17]
	v_mfma_f32_16x16x32_bf16 v[10:13], v[42:45], v[46:49], v[10:13]
	v_mfma_f32_16x16x32_bf16 v[6:9], v[42:45], v[50:53], v[6:9]
	v_mfma_f32_16x16x32_bf16 v[2:5], v[42:45], v[54:57], v[2:5]
	v_mfma_f32_16x16x32_bf16 v[86:89], v[42:45], v[62:65], v[86:89]
	s_waitcnt lgkmcnt(0)
	s_waitcnt vmcnt(0)
	s_barrier
	s_add_u32 m0, s50, 0
	v_mfma_f32_16x16x32_bf16 v[94:97], v[114:117], v[142:145], v[94:97]
	ds_read_b128 v[30:33], v100 offset:32800
	global_load_lds_dwordx4 v160, s[10:11] offset:0
	v_mfma_f32_16x16x32_bf16 v[90:93], v[114:117], v[146:149], v[90:93]
	ds_read_b128 v[46:49], v158 offset:32800
	global_load_lds_dwordx4 v161, s[10:11] offset:1024
	v_mfma_f32_16x16x32_bf16 v[82:85], v[114:117], v[150:153], v[82:85]
	ds_read_b128 v[50:53], v158 offset:34848
	global_load_lds_dwordx4 v162, s[10:11] offset:2048
	v_mfma_f32_16x16x32_bf16 v[78:81], v[114:117], v[154:157], v[78:81]
	ds_read_b128 v[34:37], v100 offset:34848
	global_load_lds_dwordx4 v163, s[10:11] offset:3072
	s_add_u32 m0, s50, 16384
	v_mfma_f32_16x16x32_bf16 v[74:77], v[118:121], v[142:145], v[74:77]
	ds_read_b128 v[54:57], v158 offset:36896
	global_load_lds_dwordx4 v160, s[12:13] offset:0
	v_mfma_f32_16x16x32_bf16 v[70:73], v[118:121], v[146:149], v[70:73]
	ds_read_b128 v[62:65], v158 offset:38944
	global_load_lds_dwordx4 v161, s[12:13] offset:1024
	v_mfma_f32_16x16x32_bf16 v[66:69], v[118:121], v[150:153], v[66:69]
	ds_read_b128 v[38:41], v100 offset:36896
	global_load_lds_dwordx4 v162, s[12:13] offset:2048
	v_mfma_f32_16x16x32_bf16 v[58:61], v[118:121], v[154:157], v[58:61]
	ds_read_b128 v[42:45], v100 offset:38944
	global_load_lds_dwordx4 v163, s[12:13] offset:3072
	v_mfma_f32_16x16x32_bf16 v[26:29], v[122:125], v[142:145], v[26:29]
	v_mfma_f32_16x16x32_bf16 v[22:25], v[122:125], v[146:149], v[22:25]
	v_mfma_f32_16x16x32_bf16 v[18:21], v[122:125], v[150:153], v[18:21]
	v_mfma_f32_16x16x32_bf16 v[14:17], v[122:125], v[154:157], v[14:17]
	v_mfma_f32_16x16x32_bf16 v[10:13], v[138:141], v[142:145], v[10:13]
	v_mfma_f32_16x16x32_bf16 v[6:9], v[138:141], v[146:149], v[6:9]
	v_mfma_f32_16x16x32_bf16 v[2:5], v[138:141], v[150:153], v[2:5]
	v_mfma_f32_16x16x32_bf16 v[86:89], v[138:141], v[154:157], v[86:89]
	s_add_u32 s99, s98, 1
	s_and_b32 s99, s99, 15
	s_sub_i32 s98, s99, s98
	s_lshl_b32 s98, s98, 7
	s_ashr_i32 s100, s98, 31
	s_add_u32 s10, s10, s98
	s_addc_u32 s11, s11, s100
	s_add_u32 s12, s12, s98
	s_addc_u32 s13, s13, s100
	s_mov_b32 s98, s99
	s_waitcnt lgkmcnt(0)
	v_mfma_f32_16x16x32_bf16 v[94:97], v[30:33], v[46:49], v[94:97]
	ds_read_b128 v[114:117], v111 offset:32800
	v_mfma_f32_16x16x32_bf16 v[90:93], v[30:33], v[50:53], v[90:93]
	ds_read_b128 v[142:145], v159 offset:32800
	v_mfma_f32_16x16x32_bf16 v[82:85], v[30:33], v[54:57], v[82:85]
	ds_read_b128 v[146:149], v159 offset:34848
	v_mfma_f32_16x16x32_bf16 v[78:81], v[30:33], v[62:65], v[78:81]
	ds_read_b128 v[118:121], v111 offset:34848
	v_mfma_f32_16x16x32_bf16 v[74:77], v[34:37], v[46:49], v[74:77]
	ds_read_b128 v[150:153], v159 offset:36896
	v_mfma_f32_16x16x32_bf16 v[70:73], v[34:37], v[50:53], v[70:73]
	ds_read_b128 v[154:157], v159 offset:38944
	v_mfma_f32_16x16x32_bf16 v[66:69], v[34:37], v[54:57], v[66:69]
	ds_read_b128 v[122:125], v111 offset:36896
	v_mfma_f32_16x16x32_bf16 v[58:61], v[34:37], v[62:65], v[58:61]
	ds_read_b128 v[138:141], v111 offset:38944
	v_mfma_f32_16x16x32_bf16 v[26:29], v[38:41], v[46:49], v[26:29]
	v_mfma_f32_16x16x32_bf16 v[22:25], v[38:41], v[50:53], v[22:25]
	v_mfma_f32_16x16x32_bf16 v[18:21], v[38:41], v[54:57], v[18:21]
	v_mfma_f32_16x16x32_bf16 v[14:17], v[38:41], v[62:65], v[14:17]
	v_mfma_f32_16x16x32_bf16 v[10:13], v[42:45], v[46:49], v[10:13]
	v_mfma_f32_16x16x32_bf16 v[6:9], v[42:45], v[50:53], v[6:9]
	v_mfma_f32_16x16x32_bf16 v[2:5], v[42:45], v[54:57], v[2:5]
	v_mfma_f32_16x16x32_bf16 v[86:89], v[42:45], v[62:65], v[86:89]
	s_waitcnt lgkmcnt(0)
	s_waitcnt vmcnt(0)
	s_add_u32 s49, s49, 1
	s_cmp_lt_u32 s49, 7
	s_cbranch_scc1 .Lk_aol0a_loop
	s_barrier
	s_add_u32 m0, s50, 32768
	v_mfma_f32_16x16x32_bf16 v[94:97], v[114:117], v[142:145], v[94:97]
	ds_read_b128 v[30:33], v100 offset:32
	global_load_lds_dwordx4 v160, s[10:11] offset:0
	v_mfma_f32_16x16x32_bf16 v[90:93], v[114:117], v[146:149], v[90:93]
	ds_read_b128 v[46:49], v158 offset:32
	global_load_lds_dwordx4 v161, s[10:11] offset:1024
	v_mfma_f32_16x16x32_bf16 v[82:85], v[114:117], v[150:153], v[82:85]
	ds_read_b128 v[50:53], v158 offset:2080
	global_load_lds_dwordx4 v162, s[10:11] offset:2048
	v_mfma_f32_16x16x32_bf16 v[78:81], v[114:117], v[154:157], v[78:81]
	ds_read_b128 v[34:37], v100 offset:2080
	global_load_lds_dwordx4 v163, s[10:11] offset:3072
	s_add_u32 m0, s50, 49152
	v_mfma_f32_16x16x32_bf16 v[74:77], v[118:121], v[142:145], v[74:77]
	ds_read_b128 v[54:57], v158 offset:4128
	global_load_lds_dwordx4 v160, s[12:13] offset:0
	v_mfma_f32_16x16x32_bf16 v[70:73], v[118:121], v[146:149], v[70:73]
	ds_read_b128 v[62:65], v158 offset:6176
	global_load_lds_dwordx4 v161, s[12:13] offset:1024
	v_mfma_f32_16x16x32_bf16 v[66:69], v[118:121], v[150:153], v[66:69]
	ds_read_b128 v[38:41], v100 offset:4128
	global_load_lds_dwordx4 v162, s[12:13] offset:2048
	v_mfma_f32_16x16x32_bf16 v[58:61], v[118:121], v[154:157], v[58:61]
	ds_read_b128 v[42:45], v100 offset:6176
	global_load_lds_dwordx4 v163, s[12:13] offset:3072
	v_mfma_f32_16x16x32_bf16 v[26:29], v[122:125], v[142:145], v[26:29]
	v_mfma_f32_16x16x32_bf16 v[22:25], v[122:125], v[146:149], v[22:25]
	v_mfma_f32_16x16x32_bf16 v[18:21], v[122:125], v[150:153], v[18:21]
	v_mfma_f32_16x16x32_bf16 v[14:17], v[122:125], v[154:157], v[14:17]
	v_mfma_f32_16x16x32_bf16 v[10:13], v[138:141], v[142:145], v[10:13]
	v_mfma_f32_16x16x32_bf16 v[6:9], v[138:141], v[146:149], v[6:9]
	v_mfma_f32_16x16x32_bf16 v[2:5], v[138:141], v[150:153], v[2:5]
	v_mfma_f32_16x16x32_bf16 v[86:89], v[138:141], v[154:157], v[86:89]
	s_add_u32 s99, s98, 1
	s_and_b32 s99, s99, 15
	s_sub_i32 s98, s99, s98
	s_lshl_b32 s98, s98, 7
	s_ashr_i32 s100, s98, 31
	s_add_u32 s10, s10, s98
	s_addc_u32 s11, s11, s100
	s_add_u32 s12, s12, s98
	s_addc_u32 s13, s13, s100
	s_mov_b32 s98, s99
	s_waitcnt lgkmcnt(0)
	v_mfma_f32_16x16x32_bf16 v[94:97], v[30:33], v[46:49], v[94:97]
	ds_read_b128 v[114:117], v111 offset:32
	v_mfma_f32_16x16x32_bf16 v[90:93], v[30:33], v[50:53], v[90:93]
	ds_read_b128 v[142:145], v159 offset:32
	v_mfma_f32_16x16x32_bf16 v[82:85], v[30:33], v[54:57], v[82:85]
	ds_read_b128 v[146:149], v159 offset:2080
	v_mfma_f32_16x16x32_bf16 v[78:81], v[30:33], v[62:65], v[78:81]
	ds_read_b128 v[118:121], v111 offset:2080
	v_mfma_f32_16x16x32_bf16 v[74:77], v[34:37], v[46:49], v[74:77]
	ds_read_b128 v[150:153], v159 offset:4128
	v_mfma_f32_16x16x32_bf16 v[70:73], v[34:37], v[50:53], v[70:73]
	ds_read_b128 v[154:157], v159 offset:6176
	v_mfma_f32_16x16x32_bf16 v[66:69], v[34:37], v[54:57], v[66:69]
	ds_read_b128 v[122:125], v111 offset:4128
	v_mfma_f32_16x16x32_bf16 v[58:61], v[34:37], v[62:65], v[58:61]
	ds_read_b128 v[138:141], v111 offset:6176
	v_mfma_f32_16x16x32_bf16 v[26:29], v[38:41], v[46:49], v[26:29]
	v_mfma_f32_16x16x32_bf16 v[22:25], v[38:41], v[50:53], v[22:25]
	v_mfma_f32_16x16x32_bf16 v[18:21], v[38:41], v[54:57], v[18:21]
	v_mfma_f32_16x16x32_bf16 v[14:17], v[38:41], v[62:65], v[14:17]
	v_mfma_f32_16x16x32_bf16 v[10:13], v[42:45], v[46:49], v[10:13]
	v_mfma_f32_16x16x32_bf16 v[6:9], v[42:45], v[50:53], v[6:9]
	v_mfma_f32_16x16x32_bf16 v[2:5], v[42:45], v[54:57], v[2:5]
	v_mfma_f32_16x16x32_bf16 v[86:89], v[42:45], v[62:65], v[86:89]
	s_waitcnt lgkmcnt(0)
	s_waitcnt vmcnt(0)
	s_barrier
	v_mfma_f32_16x16x32_bf16 v[94:97], v[114:117], v[142:145], v[94:97]
	ds_read_b128 v[30:33], v100 offset:32800
	v_mfma_f32_16x16x32_bf16 v[90:93], v[114:117], v[146:149], v[90:93]
	ds_read_b128 v[46:49], v158 offset:32800
	v_mfma_f32_16x16x32_bf16 v[82:85], v[114:117], v[150:153], v[82:85]
	ds_read_b128 v[50:53], v158 offset:34848
	v_mfma_f32_16x16x32_bf16 v[78:81], v[114:117], v[154:157], v[78:81]
	ds_read_b128 v[34:37], v100 offset:34848
	v_mfma_f32_16x16x32_bf16 v[74:77], v[118:121], v[142:145], v[74:77]
	ds_read_b128 v[54:57], v158 offset:36896
	v_mfma_f32_16x16x32_bf16 v[70:73], v[118:121], v[146:149], v[70:73]
	ds_read_b128 v[62:65], v158 offset:38944
	v_mfma_f32_16x16x32_bf16 v[66:69], v[118:121], v[150:153], v[66:69]
	ds_read_b128 v[38:41], v100 offset:36896
	v_mfma_f32_16x16x32_bf16 v[58:61], v[118:121], v[154:157], v[58:61]
	ds_read_b128 v[42:45], v100 offset:38944
	v_mfma_f32_16x16x32_bf16 v[26:29], v[122:125], v[142:145], v[26:29]
	v_mfma_f32_16x16x32_bf16 v[22:25], v[122:125], v[146:149], v[22:25]
	v_mfma_f32_16x16x32_bf16 v[18:21], v[122:125], v[150:153], v[18:21]
	v_mfma_f32_16x16x32_bf16 v[14:17], v[122:125], v[154:157], v[14:17]
	v_mfma_f32_16x16x32_bf16 v[10:13], v[138:141], v[142:145], v[10:13]
	v_mfma_f32_16x16x32_bf16 v[6:9], v[138:141], v[146:149], v[6:9]
	v_mfma_f32_16x16x32_bf16 v[2:5], v[138:141], v[150:153], v[2:5]
	v_mfma_f32_16x16x32_bf16 v[86:89], v[138:141], v[154:157], v[86:89]
	s_waitcnt lgkmcnt(0)
	v_mfma_f32_16x16x32_bf16 v[94:97], v[30:33], v[46:49], v[94:97]
	ds_read_b128 v[114:117], v111 offset:32800
	v_mfma_f32_16x16x32_bf16 v[90:93], v[30:33], v[50:53], v[90:93]
	ds_read_b128 v[142:145], v159 offset:32800
	v_mfma_f32_16x16x32_bf16 v[82:85], v[30:33], v[54:57], v[82:85]
	ds_read_b128 v[146:149], v159 offset:34848
	v_mfma_f32_16x16x32_bf16 v[78:81], v[30:33], v[62:65], v[78:81]
	ds_read_b128 v[118:121], v111 offset:34848
	v_mfma_f32_16x16x32_bf16 v[74:77], v[34:37], v[46:49], v[74:77]
	ds_read_b128 v[150:153], v159 offset:36896
	v_mfma_f32_16x16x32_bf16 v[70:73], v[34:37], v[50:53], v[70:73]
	ds_read_b128 v[154:157], v159 offset:38944
	v_mfma_f32_16x16x32_bf16 v[66:69], v[34:37], v[54:57], v[66:69]
	ds_read_b128 v[122:125], v111 offset:36896
	v_mfma_f32_16x16x32_bf16 v[58:61], v[34:37], v[62:65], v[58:61]
	ds_read_b128 v[138:141], v111 offset:38944
	v_mfma_f32_16x16x32_bf16 v[26:29], v[38:41], v[46:49], v[26:29]
	v_mfma_f32_16x16x32_bf16 v[22:25], v[38:41], v[50:53], v[22:25]
	v_mfma_f32_16x16x32_bf16 v[18:21], v[38:41], v[54:57], v[18:21]
	v_mfma_f32_16x16x32_bf16 v[14:17], v[38:41], v[62:65], v[14:17]
	v_mfma_f32_16x16x32_bf16 v[10:13], v[42:45], v[46:49], v[10:13]
	v_mfma_f32_16x16x32_bf16 v[6:9], v[42:45], v[50:53], v[6:9]
	v_mfma_f32_16x16x32_bf16 v[2:5], v[42:45], v[54:57], v[2:5]
	v_mfma_f32_16x16x32_bf16 v[86:89], v[42:45], v[62:65], v[86:89]
	s_waitcnt lgkmcnt(0)
	v_mfma_f32_16x16x32_bf16 v[94:97], v[114:117], v[142:145], v[94:97]
	v_mfma_f32_16x16x32_bf16 v[90:93], v[114:117], v[146:149], v[90:93]
	v_mfma_f32_16x16x32_bf16 v[82:85], v[114:117], v[150:153], v[82:85]
	v_mfma_f32_16x16x32_bf16 v[78:81], v[114:117], v[154:157], v[78:81]
	v_mfma_f32_16x16x32_bf16 v[74:77], v[118:121], v[142:145], v[74:77]
	v_mfma_f32_16x16x32_bf16 v[70:73], v[118:121], v[146:149], v[70:73]
	v_mfma_f32_16x16x32_bf16 v[66:69], v[118:121], v[150:153], v[66:69]
	v_mfma_f32_16x16x32_bf16 v[58:61], v[118:121], v[154:157], v[58:61]
	v_mfma_f32_16x16x32_bf16 v[26:29], v[122:125], v[142:145], v[26:29]
	v_mfma_f32_16x16x32_bf16 v[22:25], v[122:125], v[146:149], v[22:25]
	v_mfma_f32_16x16x32_bf16 v[18:21], v[122:125], v[150:153], v[18:21]
	v_mfma_f32_16x16x32_bf16 v[14:17], v[122:125], v[154:157], v[14:17]
	v_mfma_f32_16x16x32_bf16 v[10:13], v[138:141], v[142:145], v[10:13]
	v_mfma_f32_16x16x32_bf16 v[6:9], v[138:141], v[146:149], v[6:9]
	v_mfma_f32_16x16x32_bf16 v[2:5], v[138:141], v[150:153], v[2:5]
	v_mfma_f32_16x16x32_bf16 v[86:89], v[138:141], v[154:157], v[86:89]
	s_mul_i32 s4, s31, s25
	s_add_i32 s4, s4, s30
	s_and_b32 s4, s4, 0xff
	s_waitcnt vmcnt(7)
	v_lshl_or_b32 v30, s4, 10, v132
	s_mul_hi_u32 s4, s4, 0x15555556
	s_mulk_i32 s4, 0xd000
	v_add_u32_e32 v30, s4, v30
	s_lshl_b32 s4, s47, 8
	v_add_u32_e32 v138, 0x400, v129
	v_add_u32_e32 v139, 0x2000, v129
	v_add_u32_e32 v140, 0x2400, v129
	v_add_u32_e32 v141, 0x4000, v129
	v_add_u32_e32 v142, 0x4400, v129
	v_add_u32_e32 v143, 0x4800, v129
	v_add_u32_e32 v144, 0x6000, v129
	v_add_u32_e32 v145, 0x6400, v129
	v_add_u32_e32 v146, 0x6800, v129
	v_lshl_add_u64 v[114:115], v[102:103], 0, s[4:5]
	v_cmp_gt_u32_e32 vcc, s29, v30
	s_barrier
	ds_write2_b32 v129, v94, v90 offset1:16
	ds_write2_b32 v129, v95, v91 offset0:132 offset1:148
	ds_write2_b32 v138, v96, v92 offset0:8 offset1:24
	ds_write2_b32 v138, v97, v93 offset0:140 offset1:156
	ds_write2_b32 v129, v82, v78 offset0:32 offset1:48
	ds_write2_b32 v129, v83, v79 offset0:164 offset1:180
	ds_write2_b32 v138, v84, v80 offset0:40 offset1:56
	ds_write2_b32 v138, v85, v81 offset0:172 offset1:188
	ds_write2_b32 v139, v74, v70 offset0:64 offset1:80
	ds_write2_b32 v139, v75, v71 offset0:196 offset1:212
	ds_write2_b32 v140, v76, v72 offset0:72 offset1:88
	ds_write2_b32 v140, v77, v73 offset0:204 offset1:220
	ds_write2_b32 v139, v66, v58 offset0:96 offset1:112
	ds_write2_b32 v139, v67, v59 offset0:228 offset1:244
	ds_write2_b32 v140, v68, v60 offset0:104 offset1:120
	ds_write2_b32 v140, v69, v61 offset0:236 offset1:252
	ds_write2_b32 v141, v26, v22 offset0:128 offset1:144
	ds_write2_b32 v142, v27, v23 offset0:4 offset1:20
	ds_write2_b32 v142, v28, v24 offset0:136 offset1:152
	ds_write2_b32 v143, v29, v25 offset0:12 offset1:28
	ds_write2_b32 v141, v18, v14 offset0:160 offset1:176
	ds_write2_b32 v142, v19, v15 offset0:36 offset1:52
	ds_write2_b32 v142, v20, v16 offset0:168 offset1:184
	ds_write2_b32 v143, v21, v17 offset0:44 offset1:60
	ds_write2_b32 v144, v10, v6 offset0:192 offset1:208
	ds_write2_b32 v145, v11, v7 offset0:68 offset1:84
	ds_write2_b32 v145, v12, v8 offset0:200 offset1:216
	ds_write2_b32 v146, v13, v9 offset0:76 offset1:92
	ds_write2_b32 v144, v2, v86 offset0:224 offset1:240
	ds_write2_b32 v145, v3, v87 offset0:100 offset1:116
	ds_write2_b32 v145, v4, v88 offset0:232 offset1:248
	ds_write2_b32 v146, v5, v89 offset0:108 offset1:124
	s_waitcnt lgkmcnt(0)
	s_barrier
	s_and_saveexec_b64 s[10:11], vcc
	s_xor_b64 s[10:11], exec, s[10:11]
	s_cbranch_execz .LBB0_557
	s_mov_b32 s4, s48
	s_mov_b32 s12, 1
	s_mov_b32 s13, 0
	s_mov_b32 s49, 8

.LBB0_560:
	s_or_b64 exec, exec, s[10:11]
	s_lshl_b32 s10, s47, 7
	s_lshl_b32 s4, s35, 1
	s_add_u32 s12, s21, s4
	s_addc_u32 s13, s22, 0
	s_lshl_b32 s4, s46, 1
	v_mov_b32_e32 v111, v101
	s_add_u32 s46, s23, s4
	s_addc_u32 s47, s24, 0
	s_waitcnt lgkmcnt(0)
	s_barrier
	ds_read2_b32 v[26:27], v129 offset1:16
	ds_read2_b32 v[148:149], v129 offset0:132 offset1:148
	ds_read2_b32 v[28:29], v138 offset0:8 offset1:24
	ds_read2_b32 v[150:151], v138 offset0:140 offset1:156
	ds_read2_b32 v[22:23], v129 offset0:32 offset1:48
	ds_read2_b32 v[152:153], v129 offset0:164 offset1:180
	ds_read2_b32 v[24:25], v138 offset0:40 offset1:56
	ds_read2_b32 v[154:155], v138 offset0:172 offset1:188
	ds_read2_b32 v[18:19], v139 offset0:64 offset1:80
	ds_read2_b32 v[156:157], v139 offset0:196 offset1:212
	ds_read2_b32 v[20:21], v140 offset0:72 offset1:88
	ds_read2_b32 v[158:159], v140 offset0:204 offset1:220
	ds_read2_b32 v[14:15], v139 offset0:96 offset1:112
	ds_read2_b32 v[160:161], v139 offset0:228 offset1:244
	ds_read2_b32 v[16:17], v140 offset0:104 offset1:120
	ds_read2_b32 v[162:163], v140 offset0:236 offset1:252
	ds_read2_b32 v[10:11], v141 offset0:128 offset1:144
	ds_read2_b32 v[164:165], v142 offset0:4 offset1:20
	ds_read2_b32 v[12:13], v142 offset0:136 offset1:152
	ds_read2_b32 v[166:167], v143 offset0:12 offset1:28
	ds_read2_b32 v[6:7], v141 offset0:160 offset1:176
	ds_read2_b32 v[168:169], v142 offset0:36 offset1:52
	ds_read2_b32 v[8:9], v142 offset0:168 offset1:184
	ds_read2_b32 v[170:171], v143 offset0:44 offset1:60
	ds_read2_b32 v[2:3], v144 offset0:192 offset1:208
	ds_read2_b32 v[172:173], v145 offset0:68 offset1:84
	ds_read2_b32 v[4:5], v145 offset0:200 offset1:216
	ds_read2_b32 v[174:175], v146 offset0:76 offset1:92
	ds_read2_b32 v[30:31], v144 offset0:224 offset1:240
	ds_read2_b32 v[176:177], v145 offset0:100 offset1:116
	ds_read2_b32 v[32:33], v145 offset0:232 offset1:248
	ds_read2_b32 v[180:181], v146 offset0:108 offset1:124
	s_waitcnt lgkmcnt(0)
	s_barrier
	v_mov_b32_e32 v94, v31
	v_mov_b32_e32 v95, v177
	v_mov_b32_e32 v96, v33
	v_mov_b32_e32 v97, v181
	v_mov_b32_e32 v31, v176
	v_mov_b32_e32 v33, v180
	v_mov_b32_e32 v66, v3
	v_mov_b32_e32 v67, v173
	v_mov_b32_e32 v68, v5
	v_mov_b32_e32 v69, v175
	v_mov_b32_e32 v3, v172
	v_mov_b32_e32 v5, v174
	v_mov_b32_e32 v70, v7
	v_mov_b32_e32 v71, v169
	v_mov_b32_e32 v72, v9
	v_mov_b32_e32 v73, v171
	v_mov_b32_e32 v7, v168
	v_mov_b32_e32 v9, v170
	v_mov_b32_e32 v74, v11
	v_mov_b32_e32 v75, v165
	v_mov_b32_e32 v76, v13
	v_mov_b32_e32 v77, v167
	v_mov_b32_e32 v11, v164
	v_mov_b32_e32 v13, v166
	v_mov_b32_e32 v78, v15
	v_mov_b32_e32 v79, v161
	v_mov_b32_e32 v80, v17
	v_mov_b32_e32 v81, v163
	v_mov_b32_e32 v15, v160
	v_mov_b32_e32 v17, v162
	v_mov_b32_e32 v82, v19
	v_mov_b32_e32 v83, v157
	v_mov_b32_e32 v84, v21
	v_mov_b32_e32 v85, v159
	v_mov_b32_e32 v19, v156
	v_mov_b32_e32 v21, v158
	v_mov_b32_e32 v86, v23
	v_mov_b32_e32 v87, v153
	v_mov_b32_e32 v88, v25
	v_mov_b32_e32 v89, v155
	v_mov_b32_e32 v23, v152
	v_mov_b32_e32 v25, v154
	v_mov_b32_e32 v90, v27
	v_mov_b32_e32 v91, v149
	v_mov_b32_e32 v92, v29
	v_mov_b32_e32 v93, v151
	v_mov_b32_e32 v27, v148
	v_mov_b32_e32 v29, v150
	s_waitcnt lgkmcnt(0)
	s_barrier
	v_and_b32_e32 v174, 15, v0
	v_bfe_u32 v175, v0, 4, 2
	v_and_b32_e32 v111, 7, v174
	v_xor_b32_e32 v175, v175, v111
	v_lshlrev_b32_e32 v175, 4, v175
	v_lshl_or_b32 v175, v174, 7, v175
	v_bfe_u32 v174, v0, 7, 1
	v_lshl_or_b32 v100, v174, 13, v175
	v_bfe_u32 v174, v0, 6, 1
	v_lshl_or_b32 v168, v174, 13, v175
	v_or_b32_e32 v168, 0x4000, v168
	v_xor_b32_e32 v111, 64, v100
	v_xor_b32_e32 v169, 64, v168
	v_bfe_u32 v174, v0, 3, 3
	v_and_b32_e32 v175, 7, v0
	v_xor_b32_e32 v175, v175, v174
	v_lshlrev_b32_e32 v175, 4, v175
	v_lshl_or_b32 v175, v174, 11, v175
	v_lshrrev_b32_e32 v174, 6, v0
	v_and_b32_e32 v174, 3, v174
	v_lshl_or_b32 v170, v174, 16, v175
	v_add_u32_e32 v171, 0x3c00, v170
	v_add_u32_e32 v172, 0x7800, v170
	v_add_u32_e32 v173, 0xb400, v170
	v_lshlrev_b32_e32 v174, 12, v174
	s_nop 0
	v_readfirstlane_b32 s4, v174
	s_add_u32 s4, s4, 32
	v_mov_b32_e32 v116, 0
	v_mov_b32_e32 v117, 0
	v_mov_b32_e32 v118, 0
	v_mov_b32_e32 v119, 0
	v_mov_b32_e32 v120, 0
	v_mov_b32_e32 v121, 0
	v_mov_b32_e32 v122, 0
	v_mov_b32_e32 v123, 0
	v_mov_b32_e32 v124, 0
	v_mov_b32_e32 v125, 0
	v_mov_b32_e32 v126, 0
	v_mov_b32_e32 v127, 0
	v_mov_b32_e32 v148, 0
	v_mov_b32_e32 v149, 0
	v_mov_b32_e32 v150, 0
	v_mov_b32_e32 v151, 0
	v_mov_b32_e32 v152, 0
	v_mov_b32_e32 v153, 0
	v_mov_b32_e32 v154, 0
	v_mov_b32_e32 v155, 0
	v_mov_b32_e32 v156, 0
	v_mov_b32_e32 v157, 0
	v_mov_b32_e32 v158, 0
	v_mov_b32_e32 v159, 0
	v_mov_b32_e32 v160, 0
	v_mov_b32_e32 v161, 0
	v_mov_b32_e32 v162, 0
	v_mov_b32_e32 v163, 0
	v_mov_b32_e32 v164, 0
	v_mov_b32_e32 v165, 0
	v_mov_b32_e32 v166, 0
	v_mov_b32_e32 v167, 0
	s_waitcnt lgkmcnt(0)
	s_barrier
	v_readlane_b32 s98, v255, 16
	s_lshr_b32 s98, s98, 3
	s_and_b32 s98, s98, 3
	s_lshl_b32 s98, s98, 2
	s_lshl_b32 s99, s98, 7
	s_add_u32 s12, s12, s99
	s_addc_u32 s13, s13, 0
	s_add_u32 s46, s46, s99
	s_addc_u32 s47, s47, 0
	s_add_u32 m0, s4, 0
	s_nop 0
	global_load_lds_dwordx4 v170, s[12:13] offset:0
	global_load_lds_dwordx4 v171, s[12:13] offset:1024
	global_load_lds_dwordx4 v172, s[12:13] offset:2048
	global_load_lds_dwordx4 v173, s[12:13] offset:3072
	s_add_u32 m0, s4, 16384
	s_nop 0
	global_load_lds_dwordx4 v170, s[46:47] offset:0
	global_load_lds_dwordx4 v171, s[46:47] offset:1024
	global_load_lds_dwordx4 v172, s[46:47] offset:2048
	global_load_lds_dwordx4 v173, s[46:47] offset:3072
	s_add_u32 s99, s98, 1
	s_and_b32 s99, s99, 15
	s_sub_i32 s98, s99, s98
	s_lshl_b32 s98, s98, 7
	s_ashr_i32 s100, s98, 31
	s_add_u32 s12, s12, s98
	s_addc_u32 s13, s13, s100
	s_add_u32 s46, s46, s98
	s_addc_u32 s47, s47, s100
	s_mov_b32 s98, s99
	s_mov_b32 s11, 0
	s_waitcnt vmcnt(0)
.Lk_aol0b_loop:
	s_barrier
	s_add_u32 m0, s4, 32768
	v_mfma_f32_16x16x32_bf16 v[26:29], v[116:119], v[152:155], v[26:29]
	ds_read_b128 v[34:37], v100 offset:32
	global_load_lds_dwordx4 v170, s[12:13] offset:0
	v_mfma_f32_16x16x32_bf16 v[90:93], v[116:119], v[156:159], v[90:93]
	ds_read_b128 v[50:53], v168 offset:32
	global_load_lds_dwordx4 v171, s[12:13] offset:1024
	v_mfma_f32_16x16x32_bf16 v[22:25], v[116:119], v[160:163], v[22:25]
	ds_read_b128 v[54:57], v168 offset:2080
	global_load_lds_dwordx4 v172, s[12:13] offset:2048
	v_mfma_f32_16x16x32_bf16 v[86:89], v[116:119], v[164:167], v[86:89]
	ds_read_b128 v[38:41], v100 offset:2080
	global_load_lds_dwordx4 v173, s[12:13] offset:3072
	s_add_u32 m0, s4, 49152
	v_mfma_f32_16x16x32_bf16 v[18:21], v[120:123], v[152:155], v[18:21]
	ds_read_b128 v[58:61], v168 offset:4128
	global_load_lds_dwordx4 v170, s[46:47] offset:0
	v_mfma_f32_16x16x32_bf16 v[82:85], v[120:123], v[156:159], v[82:85]
	ds_read_b128 v[62:65], v168 offset:6176
	global_load_lds_dwordx4 v171, s[46:47] offset:1024
	v_mfma_f32_16x16x32_bf16 v[14:17], v[120:123], v[160:163], v[14:17]
	ds_read_b128 v[42:45], v100 offset:4128
	global_load_lds_dwordx4 v172, s[46:47] offset:2048
	v_mfma_f32_16x16x32_bf16 v[78:81], v[120:123], v[164:167], v[78:81]
	ds_read_b128 v[46:49], v100 offset:6176
	global_load_lds_dwordx4 v173, s[46:47] offset:3072
	v_mfma_f32_16x16x32_bf16 v[10:13], v[124:127], v[152:155], v[10:13]
	v_mfma_f32_16x16x32_bf16 v[74:77], v[124:127], v[156:159], v[74:77]
	v_mfma_f32_16x16x32_bf16 v[6:9], v[124:127], v[160:163], v[6:9]
	v_mfma_f32_16x16x32_bf16 v[70:73], v[124:127], v[164:167], v[70:73]
	v_mfma_f32_16x16x32_bf16 v[2:5], v[148:151], v[152:155], v[2:5]
	v_mfma_f32_16x16x32_bf16 v[66:69], v[148:151], v[156:159], v[66:69]
	v_mfma_f32_16x16x32_bf16 v[30:33], v[148:151], v[160:163], v[30:33]
	v_mfma_f32_16x16x32_bf16 v[94:97], v[148:151], v[164:167], v[94:97]
	s_add_u32 s99, s98, 1
	s_and_b32 s99, s99, 15
	s_sub_i32 s98, s99, s98
	s_lshl_b32 s98, s98, 7
	s_ashr_i32 s100, s98, 31
	s_add_u32 s12, s12, s98
	s_addc_u32 s13, s13, s100
	s_add_u32 s46, s46, s98
	s_addc_u32 s47, s47, s100
	s_mov_b32 s98, s99
	s_waitcnt lgkmcnt(0)
	v_mfma_f32_16x16x32_bf16 v[26:29], v[34:37], v[50:53], v[26:29]
	ds_read_b128 v[116:119], v111 offset:32
	v_mfma_f32_16x16x32_bf16 v[90:93], v[34:37], v[54:57], v[90:93]
	ds_read_b128 v[152:155], v169 offset:32
	v_mfma_f32_16x16x32_bf16 v[22:25], v[34:37], v[58:61], v[22:25]
	ds_read_b128 v[156:159], v169 offset:2080
	v_mfma_f32_16x16x32_bf16 v[86:89], v[34:37], v[62:65], v[86:89]
	ds_read_b128 v[120:123], v111 offset:2080
	v_mfma_f32_16x16x32_bf16 v[18:21], v[38:41], v[50:53], v[18:21]
	ds_read_b128 v[160:163], v169 offset:4128
	v_mfma_f32_16x16x32_bf16 v[82:85], v[38:41], v[54:57], v[82:85]
	ds_read_b128 v[164:167], v169 offset:6176
	v_mfma_f32_16x16x32_bf16 v[14:17], v[38:41], v[58:61], v[14:17]
	ds_read_b128 v[124:127], v111 offset:4128
	v_mfma_f32_16x16x32_bf16 v[78:81], v[38:41], v[62:65], v[78:81]
	ds_read_b128 v[148:151], v111 offset:6176
	v_mfma_f32_16x16x32_bf16 v[10:13], v[42:45], v[50:53], v[10:13]
	v_mfma_f32_16x16x32_bf16 v[74:77], v[42:45], v[54:57], v[74:77]
	v_mfma_f32_16x16x32_bf16 v[6:9], v[42:45], v[58:61], v[6:9]
	v_mfma_f32_16x16x32_bf16 v[70:73], v[42:45], v[62:65], v[70:73]
	v_mfma_f32_16x16x32_bf16 v[2:5], v[46:49], v[50:53], v[2:5]
	v_mfma_f32_16x16x32_bf16 v[66:69], v[46:49], v[54:57], v[66:69]
	v_mfma_f32_16x16x32_bf16 v[30:33], v[46:49], v[58:61], v[30:33]
	v_mfma_f32_16x16x32_bf16 v[94:97], v[46:49], v[62:65], v[94:97]
	s_waitcnt lgkmcnt(0)
	s_waitcnt vmcnt(0)
	s_barrier
	s_add_u32 m0, s4, 0
	v_mfma_f32_16x16x32_bf16 v[26:29], v[116:119], v[152:155], v[26:29]
	ds_read_b128 v[34:37], v100 offset:32800
	global_load_lds_dwordx4 v170, s[12:13] offset:0
	v_mfma_f32_16x16x32_bf16 v[90:93], v[116:119], v[156:159], v[90:93]
	ds_read_b128 v[50:53], v168 offset:32800
	global_load_lds_dwordx4 v171, s[12:13] offset:1024
	v_mfma_f32_16x16x32_bf16 v[22:25], v[116:119], v[160:163], v[22:25]
	ds_read_b128 v[54:57], v168 offset:34848
	global_load_lds_dwordx4 v172, s[12:13] offset:2048
	v_mfma_f32_16x16x32_bf16 v[86:89], v[116:119], v[164:167], v[86:89]
	ds_read_b128 v[38:41], v100 offset:34848
	global_load_lds_dwordx4 v173, s[12:13] offset:3072
	s_add_u32 m0, s4, 16384
	v_mfma_f32_16x16x32_bf16 v[18:21], v[120:123], v[152:155], v[18:21]
	ds_read_b128 v[58:61], v168 offset:36896
	global_load_lds_dwordx4 v170, s[46:47] offset:0
	v_mfma_f32_16x16x32_bf16 v[82:85], v[120:123], v[156:159], v[82:85]
	ds_read_b128 v[62:65], v168 offset:38944
	global_load_lds_dwordx4 v171, s[46:47] offset:1024
	v_mfma_f32_16x16x32_bf16 v[14:17], v[120:123], v[160:163], v[14:17]
	ds_read_b128 v[42:45], v100 offset:36896
	global_load_lds_dwordx4 v172, s[46:47] offset:2048
	v_mfma_f32_16x16x32_bf16 v[78:81], v[120:123], v[164:167], v[78:81]
	ds_read_b128 v[46:49], v100 offset:38944
	global_load_lds_dwordx4 v173, s[46:47] offset:3072
	v_mfma_f32_16x16x32_bf16 v[10:13], v[124:127], v[152:155], v[10:13]
	v_mfma_f32_16x16x32_bf16 v[74:77], v[124:127], v[156:159], v[74:77]
	v_mfma_f32_16x16x32_bf16 v[6:9], v[124:127], v[160:163], v[6:9]
	v_mfma_f32_16x16x32_bf16 v[70:73], v[124:127], v[164:167], v[70:73]
	v_mfma_f32_16x16x32_bf16 v[2:5], v[148:151], v[152:155], v[2:5]
	v_mfma_f32_16x16x32_bf16 v[66:69], v[148:151], v[156:159], v[66:69]
	v_mfma_f32_16x16x32_bf16 v[30:33], v[148:151], v[160:163], v[30:33]
	v_mfma_f32_16x16x32_bf16 v[94:97], v[148:151], v[164:167], v[94:97]
	s_add_u32 s99, s98, 1
	s_and_b32 s99, s99, 15
	s_sub_i32 s98, s99, s98
	s_lshl_b32 s98, s98, 7
	s_ashr_i32 s100, s98, 31
	s_add_u32 s12, s12, s98
	s_addc_u32 s13, s13, s100
	s_add_u32 s46, s46, s98
	s_addc_u32 s47, s47, s100
	s_mov_b32 s98, s99
	s_waitcnt lgkmcnt(0)
	v_mfma_f32_16x16x32_bf16 v[26:29], v[34:37], v[50:53], v[26:29]
	ds_read_b128 v[116:119], v111 offset:32800
	v_mfma_f32_16x16x32_bf16 v[90:93], v[34:37], v[54:57], v[90:93]
	ds_read_b128 v[152:155], v169 offset:32800
	v_mfma_f32_16x16x32_bf16 v[22:25], v[34:37], v[58:61], v[22:25]
	ds_read_b128 v[156:159], v169 offset:34848
	v_mfma_f32_16x16x32_bf16 v[86:89], v[34:37], v[62:65], v[86:89]
	ds_read_b128 v[120:123], v111 offset:34848
	v_mfma_f32_16x16x32_bf16 v[18:21], v[38:41], v[50:53], v[18:21]
	ds_read_b128 v[160:163], v169 offset:36896
	v_mfma_f32_16x16x32_bf16 v[82:85], v[38:41], v[54:57], v[82:85]
	ds_read_b128 v[164:167], v169 offset:38944
	v_mfma_f32_16x16x32_bf16 v[14:17], v[38:41], v[58:61], v[14:17]
	ds_read_b128 v[124:127], v111 offset:36896
	v_mfma_f32_16x16x32_bf16 v[78:81], v[38:41], v[62:65], v[78:81]
	ds_read_b128 v[148:151], v111 offset:38944
	v_mfma_f32_16x16x32_bf16 v[10:13], v[42:45], v[50:53], v[10:13]
	v_mfma_f32_16x16x32_bf16 v[74:77], v[42:45], v[54:57], v[74:77]
	v_mfma_f32_16x16x32_bf16 v[6:9], v[42:45], v[58:61], v[6:9]
	v_mfma_f32_16x16x32_bf16 v[70:73], v[42:45], v[62:65], v[70:73]
	v_mfma_f32_16x16x32_bf16 v[2:5], v[46:49], v[50:53], v[2:5]
	v_mfma_f32_16x16x32_bf16 v[66:69], v[46:49], v[54:57], v[66:69]
	v_mfma_f32_16x16x32_bf16 v[30:33], v[46:49], v[58:61], v[30:33]
	v_mfma_f32_16x16x32_bf16 v[94:97], v[46:49], v[62:65], v[94:97]
	s_waitcnt lgkmcnt(0)
	s_waitcnt vmcnt(0)
	s_add_u32 s11, s11, 1
	s_cmp_lt_u32 s11, 7
	s_cbranch_scc1 .Lk_aol0b_loop
	s_barrier
	s_add_u32 m0, s4, 32768
	v_mfma_f32_16x16x32_bf16 v[26:29], v[116:119], v[152:155], v[26:29]
	ds_read_b128 v[34:37], v100 offset:32
	global_load_lds_dwordx4 v170, s[12:13] offset:0
	v_mfma_f32_16x16x32_bf16 v[90:93], v[116:119], v[156:159], v[90:93]
	ds_read_b128 v[50:53], v168 offset:32
	global_load_lds_dwordx4 v171, s[12:13] offset:1024
	v_mfma_f32_16x16x32_bf16 v[22:25], v[116:119], v[160:163], v[22:25]
	ds_read_b128 v[54:57], v168 offset:2080
	global_load_lds_dwordx4 v172, s[12:13] offset:2048
	v_mfma_f32_16x16x32_bf16 v[86:89], v[116:119], v[164:167], v[86:89]
	ds_read_b128 v[38:41], v100 offset:2080
	global_load_lds_dwordx4 v173, s[12:13] offset:3072
	s_add_u32 m0, s4, 49152
	v_mfma_f32_16x16x32_bf16 v[18:21], v[120:123], v[152:155], v[18:21]
	ds_read_b128 v[58:61], v168 offset:4128
	global_load_lds_dwordx4 v170, s[46:47] offset:0
	v_mfma_f32_16x16x32_bf16 v[82:85], v[120:123], v[156:159], v[82:85]
	ds_read_b128 v[62:65], v168 offset:6176
	global_load_lds_dwordx4 v171, s[46:47] offset:1024
	v_mfma_f32_16x16x32_bf16 v[14:17], v[120:123], v[160:163], v[14:17]
	ds_read_b128 v[42:45], v100 offset:4128
	global_load_lds_dwordx4 v172, s[46:47] offset:2048
	v_mfma_f32_16x16x32_bf16 v[78:81], v[120:123], v[164:167], v[78:81]
	ds_read_b128 v[46:49], v100 offset:6176
	global_load_lds_dwordx4 v173, s[46:47] offset:3072
	v_mfma_f32_16x16x32_bf16 v[10:13], v[124:127], v[152:155], v[10:13]
	v_mfma_f32_16x16x32_bf16 v[74:77], v[124:127], v[156:159], v[74:77]
	v_mfma_f32_16x16x32_bf16 v[6:9], v[124:127], v[160:163], v[6:9]
	v_mfma_f32_16x16x32_bf16 v[70:73], v[124:127], v[164:167], v[70:73]
	v_mfma_f32_16x16x32_bf16 v[2:5], v[148:151], v[152:155], v[2:5]
	v_mfma_f32_16x16x32_bf16 v[66:69], v[148:151], v[156:159], v[66:69]
	v_mfma_f32_16x16x32_bf16 v[30:33], v[148:151], v[160:163], v[30:33]
	v_mfma_f32_16x16x32_bf16 v[94:97], v[148:151], v[164:167], v[94:97]
	s_add_u32 s99, s98, 1
	s_and_b32 s99, s99, 15
	s_sub_i32 s98, s99, s98
	s_lshl_b32 s98, s98, 7
	s_ashr_i32 s100, s98, 31
	s_add_u32 s12, s12, s98
	s_addc_u32 s13, s13, s100
	s_add_u32 s46, s46, s98
	s_addc_u32 s47, s47, s100
	s_mov_b32 s98, s99
	s_waitcnt lgkmcnt(0)
	v_mfma_f32_16x16x32_bf16 v[26:29], v[34:37], v[50:53], v[26:29]
	ds_read_b128 v[116:119], v111 offset:32
	v_mfma_f32_16x16x32_bf16 v[90:93], v[34:37], v[54:57], v[90:93]
	ds_read_b128 v[152:155], v169 offset:32
	v_mfma_f32_16x16x32_bf16 v[22:25], v[34:37], v[58:61], v[22:25]
	ds_read_b128 v[156:159], v169 offset:2080
	v_mfma_f32_16x16x32_bf16 v[86:89], v[34:37], v[62:65], v[86:89]
	ds_read_b128 v[120:123], v111 offset:2080
	v_mfma_f32_16x16x32_bf16 v[18:21], v[38:41], v[50:53], v[18:21]
	ds_read_b128 v[160:163], v169 offset:4128
	v_mfma_f32_16x16x32_bf16 v[82:85], v[38:41], v[54:57], v[82:85]
	ds_read_b128 v[164:167], v169 offset:6176
	v_mfma_f32_16x16x32_bf16 v[14:17], v[38:41], v[58:61], v[14:17]
	ds_read_b128 v[124:127], v111 offset:4128
	v_mfma_f32_16x16x32_bf16 v[78:81], v[38:41], v[62:65], v[78:81]
	ds_read_b128 v[148:151], v111 offset:6176
	v_mfma_f32_16x16x32_bf16 v[10:13], v[42:45], v[50:53], v[10:13]
	v_mfma_f32_16x16x32_bf16 v[74:77], v[42:45], v[54:57], v[74:77]
	v_mfma_f32_16x16x32_bf16 v[6:9], v[42:45], v[58:61], v[6:9]
	v_mfma_f32_16x16x32_bf16 v[70:73], v[42:45], v[62:65], v[70:73]
	v_mfma_f32_16x16x32_bf16 v[2:5], v[46:49], v[50:53], v[2:5]
	v_mfma_f32_16x16x32_bf16 v[66:69], v[46:49], v[54:57], v[66:69]
	v_mfma_f32_16x16x32_bf16 v[30:33], v[46:49], v[58:61], v[30:33]
	v_mfma_f32_16x16x32_bf16 v[94:97], v[46:49], v[62:65], v[94:97]
	s_waitcnt lgkmcnt(0)
	s_waitcnt vmcnt(0)
	s_barrier
	v_mfma_f32_16x16x32_bf16 v[26:29], v[116:119], v[152:155], v[26:29]
	ds_read_b128 v[34:37], v100 offset:32800
	v_mfma_f32_16x16x32_bf16 v[90:93], v[116:119], v[156:159], v[90:93]
	ds_read_b128 v[50:53], v168 offset:32800
	v_mfma_f32_16x16x32_bf16 v[22:25], v[116:119], v[160:163], v[22:25]
	ds_read_b128 v[54:57], v168 offset:34848
	v_mfma_f32_16x16x32_bf16 v[86:89], v[116:119], v[164:167], v[86:89]
	ds_read_b128 v[38:41], v100 offset:34848
	v_mfma_f32_16x16x32_bf16 v[18:21], v[120:123], v[152:155], v[18:21]
	ds_read_b128 v[58:61], v168 offset:36896
	v_mfma_f32_16x16x32_bf16 v[82:85], v[120:123], v[156:159], v[82:85]
	ds_read_b128 v[62:65], v168 offset:38944
	v_mfma_f32_16x16x32_bf16 v[14:17], v[120:123], v[160:163], v[14:17]
	ds_read_b128 v[42:45], v100 offset:36896
	v_mfma_f32_16x16x32_bf16 v[78:81], v[120:123], v[164:167], v[78:81]
	ds_read_b128 v[46:49], v100 offset:38944
	v_mfma_f32_16x16x32_bf16 v[10:13], v[124:127], v[152:155], v[10:13]
	v_mfma_f32_16x16x32_bf16 v[74:77], v[124:127], v[156:159], v[74:77]
	v_mfma_f32_16x16x32_bf16 v[6:9], v[124:127], v[160:163], v[6:9]
	v_mfma_f32_16x16x32_bf16 v[70:73], v[124:127], v[164:167], v[70:73]
	v_mfma_f32_16x16x32_bf16 v[2:5], v[148:151], v[152:155], v[2:5]
	v_mfma_f32_16x16x32_bf16 v[66:69], v[148:151], v[156:159], v[66:69]
	v_mfma_f32_16x16x32_bf16 v[30:33], v[148:151], v[160:163], v[30:33]
	v_mfma_f32_16x16x32_bf16 v[94:97], v[148:151], v[164:167], v[94:97]
	s_waitcnt lgkmcnt(0)
	v_mfma_f32_16x16x32_bf16 v[26:29], v[34:37], v[50:53], v[26:29]
	ds_read_b128 v[116:119], v111 offset:32800
	v_mfma_f32_16x16x32_bf16 v[90:93], v[34:37], v[54:57], v[90:93]
	ds_read_b128 v[152:155], v169 offset:32800
	v_mfma_f32_16x16x32_bf16 v[22:25], v[34:37], v[58:61], v[22:25]
	ds_read_b128 v[156:159], v169 offset:34848
	v_mfma_f32_16x16x32_bf16 v[86:89], v[34:37], v[62:65], v[86:89]
	ds_read_b128 v[120:123], v111 offset:34848
	v_mfma_f32_16x16x32_bf16 v[18:21], v[38:41], v[50:53], v[18:21]
	ds_read_b128 v[160:163], v169 offset:36896
	v_mfma_f32_16x16x32_bf16 v[82:85], v[38:41], v[54:57], v[82:85]
	ds_read_b128 v[164:167], v169 offset:38944
	v_mfma_f32_16x16x32_bf16 v[14:17], v[38:41], v[58:61], v[14:17]
	ds_read_b128 v[124:127], v111 offset:36896
	v_mfma_f32_16x16x32_bf16 v[78:81], v[38:41], v[62:65], v[78:81]
	ds_read_b128 v[148:151], v111 offset:38944
	v_mfma_f32_16x16x32_bf16 v[10:13], v[42:45], v[50:53], v[10:13]
	v_mfma_f32_16x16x32_bf16 v[74:77], v[42:45], v[54:57], v[74:77]
	v_mfma_f32_16x16x32_bf16 v[6:9], v[42:45], v[58:61], v[6:9]
	v_mfma_f32_16x16x32_bf16 v[70:73], v[42:45], v[62:65], v[70:73]
	v_mfma_f32_16x16x32_bf16 v[2:5], v[46:49], v[50:53], v[2:5]
	v_mfma_f32_16x16x32_bf16 v[66:69], v[46:49], v[54:57], v[66:69]
	v_mfma_f32_16x16x32_bf16 v[30:33], v[46:49], v[58:61], v[30:33]
	v_mfma_f32_16x16x32_bf16 v[94:97], v[46:49], v[62:65], v[94:97]
	s_waitcnt lgkmcnt(0)
	v_mfma_f32_16x16x32_bf16 v[26:29], v[116:119], v[152:155], v[26:29]
	v_mfma_f32_16x16x32_bf16 v[90:93], v[116:119], v[156:159], v[90:93]
	v_mfma_f32_16x16x32_bf16 v[22:25], v[116:119], v[160:163], v[22:25]
	v_mfma_f32_16x16x32_bf16 v[86:89], v[116:119], v[164:167], v[86:89]
	v_mfma_f32_16x16x32_bf16 v[18:21], v[120:123], v[152:155], v[18:21]
	v_mfma_f32_16x16x32_bf16 v[82:85], v[120:123], v[156:159], v[82:85]
	v_mfma_f32_16x16x32_bf16 v[14:17], v[120:123], v[160:163], v[14:17]
	v_mfma_f32_16x16x32_bf16 v[78:81], v[120:123], v[164:167], v[78:81]
	v_mfma_f32_16x16x32_bf16 v[10:13], v[124:127], v[152:155], v[10:13]
	v_mfma_f32_16x16x32_bf16 v[74:77], v[124:127], v[156:159], v[74:77]
	v_mfma_f32_16x16x32_bf16 v[6:9], v[124:127], v[160:163], v[6:9]
	v_mfma_f32_16x16x32_bf16 v[70:73], v[124:127], v[164:167], v[70:73]
	v_mfma_f32_16x16x32_bf16 v[2:5], v[148:151], v[152:155], v[2:5]
	v_mfma_f32_16x16x32_bf16 v[66:69], v[148:151], v[156:159], v[66:69]
	v_mfma_f32_16x16x32_bf16 v[30:33], v[148:151], v[160:163], v[30:33]
	v_mfma_f32_16x16x32_bf16 v[94:97], v[148:151], v[164:167], v[94:97]
	s_lshl_b32 s4, s10, 1
	s_barrier
	ds_write2_b32 v129, v26, v90 offset1:16
	ds_write2_b32 v129, v27, v91 offset0:132 offset1:148
	ds_write2_b32 v138, v28, v92 offset0:8 offset1:24
	ds_write2_b32 v138, v29, v93 offset0:140 offset1:156
	ds_write2_b32 v129, v22, v86 offset0:32 offset1:48
	ds_write2_b32 v129, v23, v87 offset0:164 offset1:180
	ds_write2_b32 v138, v24, v88 offset0:40 offset1:56
	ds_write2_b32 v138, v25, v89 offset0:172 offset1:188
	ds_write2_b32 v139, v18, v82 offset0:64 offset1:80
	ds_write2_b32 v139, v19, v83 offset0:196 offset1:212
	ds_write2_b32 v140, v20, v84 offset0:72 offset1:88
	ds_write2_b32 v140, v21, v85 offset0:204 offset1:220
	ds_write2_b32 v139, v14, v78 offset0:96 offset1:112
	ds_write2_b32 v139, v15, v79 offset0:228 offset1:244
	ds_write2_b32 v140, v16, v80 offset0:104 offset1:120
	ds_write2_b32 v140, v17, v81 offset0:236 offset1:252
	ds_write2_b32 v141, v10, v74 offset0:128 offset1:144
	ds_write2_b32 v142, v11, v75 offset0:4 offset1:20
	ds_write2_b32 v142, v12, v76 offset0:136 offset1:152
	ds_write2_b32 v143, v13, v77 offset0:12 offset1:28
	ds_write2_b32 v141, v6, v70 offset0:160 offset1:176
	ds_write2_b32 v142, v7, v71 offset0:36 offset1:52
	ds_write2_b32 v142, v8, v72 offset0:168 offset1:184
	ds_write2_b32 v143, v9, v73 offset0:44 offset1:60
	ds_write2_b32 v144, v2, v66 offset0:192 offset1:208
	ds_write2_b32 v145, v3, v67 offset0:68 offset1:84
	ds_write2_b32 v145, v4, v68 offset0:200 offset1:216
	ds_write2_b32 v146, v5, v69 offset0:76 offset1:92
	ds_write2_b32 v144, v30, v94 offset0:224 offset1:240
	ds_write2_b32 v145, v31, v95 offset0:100 offset1:116
	ds_write2_b32 v145, v32, v96 offset0:232 offset1:248
	ds_write2_b32 v146, v33, v97 offset0:108 offset1:124
	v_lshl_add_u64 v[2:3], v[106:107], 0, s[4:5]
	s_lshl_b32 s4, s34, 10
	s_mul_hi_u32 s10, s34, 0x15555556
	v_or_b32_e32 v4, s4, v134
	s_mulk_i32 s10, 0x3000
	v_or_b32_e32 v5, s4, v132
	v_subrev_u32_e32 v4, s10, v4
	v_subrev_u32_e32 v100, s10, v5
	s_mov_b32 s4, 0
	s_waitcnt lgkmcnt(0)
	s_barrier

.LBB0_634:
	s_and_b32 s31, s30, 0xff
	s_mul_i32 s4, s31, 0xab
	s_lshr_b32 s33, s4, 11
	s_mul_i32 s4, s33, 12
	s_sub_i32 s4, s30, s4
	s_and_b32 s4, s4, 0xff
	s_lshl_b32 s4, s4, 21
	s_or_b32 s4, s4, s23
	s_add_u32 s14, s18, s4
	s_addc_u32 s15, s19, 0
	s_lshl_b32 s4, s33, 18
	s_add_u32 s16, s20, s4
	s_addc_u32 s17, s21, 0
	v_and_b32_e32 v162, 15, v0
	v_bfe_u32 v163, v0, 4, 2
	v_and_b32_e32 v109, 7, v162
	v_xor_b32_e32 v163, v163, v109
	v_lshlrev_b32_e32 v163, 4, v163
	v_lshl_or_b32 v163, v162, 7, v163
	v_bfe_u32 v162, v0, 7, 1
	v_lshl_or_b32 v100, v162, 13, v163
	v_bfe_u32 v162, v0, 6, 1
	v_lshl_or_b32 v156, v162, 13, v163
	v_or_b32_e32 v156, 0x4000, v156
	v_xor_b32_e32 v109, 64, v100
	v_xor_b32_e32 v157, 64, v156
	v_bfe_u32 v162, v0, 3, 3
	v_and_b32_e32 v163, 7, v0
	v_xor_b32_e32 v163, v163, v162
	v_lshlrev_b32_e32 v163, 4, v163
	v_lshl_or_b32 v163, v162, 11, v163
	v_lshrrev_b32_e32 v162, 6, v0
	v_and_b32_e32 v162, 3, v162
	v_lshl_or_b32 v158, v162, 16, v163
	v_add_u32_e32 v159, 0x3c00, v158
	v_add_u32_e32 v160, 0x7800, v158
	v_add_u32_e32 v161, 0xb400, v158
	v_lshlrev_b32_e32 v162, 12, v162
	s_nop 0
	v_readfirstlane_b32 s35, v162
	s_add_u32 s35, s35, 32
	v_mov_b32_e32 v94, 0
	v_mov_b32_e32 v95, 0
	v_mov_b32_e32 v96, 0
	v_mov_b32_e32 v97, 0
	v_mov_b32_e32 v90, 0
	v_mov_b32_e32 v91, 0
	v_mov_b32_e32 v92, 0
	v_mov_b32_e32 v93, 0
	v_mov_b32_e32 v82, 0
	v_mov_b32_e32 v83, 0
	v_mov_b32_e32 v84, 0
	v_mov_b32_e32 v85, 0
	v_mov_b32_e32 v78, 0
	v_mov_b32_e32 v79, 0
	v_mov_b32_e32 v80, 0
	v_mov_b32_e32 v81, 0
	v_mov_b32_e32 v74, 0
	v_mov_b32_e32 v75, 0
	v_mov_b32_e32 v76, 0
	v_mov_b32_e32 v77, 0
	v_mov_b32_e32 v70, 0
	v_mov_b32_e32 v71, 0
	v_mov_b32_e32 v72, 0
	v_mov_b32_e32 v73, 0
	v_mov_b32_e32 v66, 0
	v_mov_b32_e32 v67, 0
	v_mov_b32_e32 v68, 0
	v_mov_b32_e32 v69, 0
	v_mov_b32_e32 v62, 0
	v_mov_b32_e32 v63, 0
	v_mov_b32_e32 v64, 0
	v_mov_b32_e32 v65, 0
	v_mov_b32_e32 v34, 0
	v_mov_b32_e32 v35, 0
	v_mov_b32_e32 v36, 0
	v_mov_b32_e32 v37, 0
	v_mov_b32_e32 v26, 0
	v_mov_b32_e32 v27, 0
	v_mov_b32_e32 v28, 0
	v_mov_b32_e32 v29, 0
	v_mov_b32_e32 v18, 0
	v_mov_b32_e32 v19, 0
	v_mov_b32_e32 v20, 0
	v_mov_b32_e32 v21, 0
	v_mov_b32_e32 v14, 0
	v_mov_b32_e32 v15, 0
	v_mov_b32_e32 v16, 0
	v_mov_b32_e32 v17, 0
	v_mov_b32_e32 v10, 0
	v_mov_b32_e32 v11, 0
	v_mov_b32_e32 v12, 0
	v_mov_b32_e32 v13, 0
	v_mov_b32_e32 v6, 0
	v_mov_b32_e32 v7, 0
	v_mov_b32_e32 v8, 0
	v_mov_b32_e32 v9, 0
	v_mov_b32_e32 v2, 0
	v_mov_b32_e32 v3, 0
	v_mov_b32_e32 v4, 0
	v_mov_b32_e32 v5, 0
	v_mov_b32_e32 v86, 0
	v_mov_b32_e32 v87, 0
	v_mov_b32_e32 v88, 0
	v_mov_b32_e32 v89, 0
	v_mov_b32_e32 v110, 0
	v_mov_b32_e32 v111, 0
	v_mov_b32_e32 v112, 0
	v_mov_b32_e32 v113, 0
	v_mov_b32_e32 v114, 0
	v_mov_b32_e32 v115, 0
	v_mov_b32_e32 v116, 0
	v_mov_b32_e32 v117, 0
	v_mov_b32_e32 v118, 0
	v_mov_b32_e32 v119, 0
	v_mov_b32_e32 v120, 0
	v_mov_b32_e32 v121, 0
	v_mov_b32_e32 v136, 0
	v_mov_b32_e32 v137, 0
	v_mov_b32_e32 v138, 0
	v_mov_b32_e32 v139, 0
	v_mov_b32_e32 v140, 0
	v_mov_b32_e32 v141, 0
	v_mov_b32_e32 v142, 0
	v_mov_b32_e32 v143, 0
	v_mov_b32_e32 v144, 0
	v_mov_b32_e32 v145, 0
	v_mov_b32_e32 v146, 0
	v_mov_b32_e32 v147, 0
	v_mov_b32_e32 v148, 0
	v_mov_b32_e32 v149, 0
	v_mov_b32_e32 v150, 0
	v_mov_b32_e32 v151, 0
	v_mov_b32_e32 v152, 0
	v_mov_b32_e32 v153, 0
	v_mov_b32_e32 v154, 0
	v_mov_b32_e32 v155, 0
	s_waitcnt lgkmcnt(0)
	s_barrier
	v_readlane_b32 s98, v255, 16
	s_lshr_b32 s98, s98, 3
	s_and_b32 s98, s98, 3
	s_lshl_b32 s98, s98, 2
	s_lshl_b32 s99, s98, 7
	s_add_u32 s14, s14, s99
	s_addc_u32 s15, s15, 0
	s_add_u32 s16, s16, s99
	s_addc_u32 s17, s17, 0
	s_add_u32 m0, s35, 0
	s_nop 0
	global_load_lds_dwordx4 v158, s[14:15] offset:0
	global_load_lds_dwordx4 v159, s[14:15] offset:1024
	global_load_lds_dwordx4 v160, s[14:15] offset:2048
	global_load_lds_dwordx4 v161, s[14:15] offset:3072
	s_add_u32 m0, s35, 16384
	s_nop 0
	global_load_lds_dwordx4 v158, s[16:17] offset:0
	global_load_lds_dwordx4 v159, s[16:17] offset:1024
	global_load_lds_dwordx4 v160, s[16:17] offset:2048
	global_load_lds_dwordx4 v161, s[16:17] offset:3072
	s_add_u32 s99, s98, 1
	s_and_b32 s99, s99, 15
	s_sub_i32 s98, s99, s98
	s_lshl_b32 s98, s98, 7
	s_ashr_i32 s100, s98, 31
	s_add_u32 s14, s14, s98
	s_addc_u32 s15, s15, s100
	s_add_u32 s16, s16, s98
	s_addc_u32 s17, s17, s100
	s_mov_b32 s98, s99
	s_mov_b32 s34, 0
	s_waitcnt vmcnt(0)
.Lk_outl0_loop:
	s_barrier
	s_add_u32 m0, s35, 32768
	v_mfma_f32_16x16x32_bf16 v[94:97], v[110:113], v[140:143], v[94:97]
	ds_read_b128 v[22:25], v100 offset:32
	global_load_lds_dwordx4 v158, s[14:15] offset:0
	v_mfma_f32_16x16x32_bf16 v[90:93], v[110:113], v[144:147], v[90:93]
	ds_read_b128 v[46:49], v156 offset:32
	global_load_lds_dwordx4 v159, s[14:15] offset:1024
	v_mfma_f32_16x16x32_bf16 v[82:85], v[110:113], v[148:151], v[82:85]
	ds_read_b128 v[50:53], v156 offset:2080
	global_load_lds_dwordx4 v160, s[14:15] offset:2048
	v_mfma_f32_16x16x32_bf16 v[78:81], v[110:113], v[152:155], v[78:81]
	ds_read_b128 v[30:33], v100 offset:2080
	global_load_lds_dwordx4 v161, s[14:15] offset:3072
	s_add_u32 m0, s35, 49152
	v_mfma_f32_16x16x32_bf16 v[74:77], v[114:117], v[140:143], v[74:77]
	ds_read_b128 v[54:57], v156 offset:4128
	global_load_lds_dwordx4 v158, s[16:17] offset:0
	v_mfma_f32_16x16x32_bf16 v[70:73], v[114:117], v[144:147], v[70:73]
	ds_read_b128 v[58:61], v156 offset:6176
	global_load_lds_dwordx4 v159, s[16:17] offset:1024
	v_mfma_f32_16x16x32_bf16 v[66:69], v[114:117], v[148:151], v[66:69]
	ds_read_b128 v[38:41], v100 offset:4128
	global_load_lds_dwordx4 v160, s[16:17] offset:2048
	v_mfma_f32_16x16x32_bf16 v[62:65], v[114:117], v[152:155], v[62:65]
	ds_read_b128 v[42:45], v100 offset:6176
	global_load_lds_dwordx4 v161, s[16:17] offset:3072
	v_mfma_f32_16x16x32_bf16 v[34:37], v[118:121], v[140:143], v[34:37]
	v_mfma_f32_16x16x32_bf16 v[26:29], v[118:121], v[144:147], v[26:29]
	v_mfma_f32_16x16x32_bf16 v[18:21], v[118:121], v[148:151], v[18:21]
	v_mfma_f32_16x16x32_bf16 v[14:17], v[118:121], v[152:155], v[14:17]
	v_mfma_f32_16x16x32_bf16 v[10:13], v[136:139], v[140:143], v[10:13]
	v_mfma_f32_16x16x32_bf16 v[6:9], v[136:139], v[144:147], v[6:9]
	v_mfma_f32_16x16x32_bf16 v[2:5], v[136:139], v[148:151], v[2:5]
	v_mfma_f32_16x16x32_bf16 v[86:89], v[136:139], v[152:155], v[86:89]
	s_add_u32 s99, s98, 1
	s_and_b32 s99, s99, 15
	s_sub_i32 s98, s99, s98
	s_lshl_b32 s98, s98, 7
	s_ashr_i32 s100, s98, 31
	s_add_u32 s14, s14, s98
	s_addc_u32 s15, s15, s100
	s_add_u32 s16, s16, s98
	s_addc_u32 s17, s17, s100
	s_mov_b32 s98, s99
	s_waitcnt lgkmcnt(0)
	v_mfma_f32_16x16x32_bf16 v[94:97], v[22:25], v[46:49], v[94:97]
	ds_read_b128 v[110:113], v109 offset:32
	v_mfma_f32_16x16x32_bf16 v[90:93], v[22:25], v[50:53], v[90:93]
	ds_read_b128 v[140:143], v157 offset:32
	v_mfma_f32_16x16x32_bf16 v[82:85], v[22:25], v[54:57], v[82:85]
	ds_read_b128 v[144:147], v157 offset:2080
	v_mfma_f32_16x16x32_bf16 v[78:81], v[22:25], v[58:61], v[78:81]
	ds_read_b128 v[114:117], v109 offset:2080
	v_mfma_f32_16x16x32_bf16 v[74:77], v[30:33], v[46:49], v[74:77]
	ds_read_b128 v[148:151], v157 offset:4128
	v_mfma_f32_16x16x32_bf16 v[70:73], v[30:33], v[50:53], v[70:73]
	ds_read_b128 v[152:155], v157 offset:6176
	v_mfma_f32_16x16x32_bf16 v[66:69], v[30:33], v[54:57], v[66:69]
	ds_read_b128 v[118:121], v109 offset:4128
	v_mfma_f32_16x16x32_bf16 v[62:65], v[30:33], v[58:61], v[62:65]
	ds_read_b128 v[136:139], v109 offset:6176
	v_mfma_f32_16x16x32_bf16 v[34:37], v[38:41], v[46:49], v[34:37]
	v_mfma_f32_16x16x32_bf16 v[26:29], v[38:41], v[50:53], v[26:29]
	v_mfma_f32_16x16x32_bf16 v[18:21], v[38:41], v[54:57], v[18:21]
	v_mfma_f32_16x16x32_bf16 v[14:17], v[38:41], v[58:61], v[14:17]
	v_mfma_f32_16x16x32_bf16 v[10:13], v[42:45], v[46:49], v[10:13]
	v_mfma_f32_16x16x32_bf16 v[6:9], v[42:45], v[50:53], v[6:9]
	v_mfma_f32_16x16x32_bf16 v[2:5], v[42:45], v[54:57], v[2:5]
	v_mfma_f32_16x16x32_bf16 v[86:89], v[42:45], v[58:61], v[86:89]
	s_waitcnt lgkmcnt(0)
	s_waitcnt vmcnt(0)
	s_barrier
	s_add_u32 m0, s35, 0
	v_mfma_f32_16x16x32_bf16 v[94:97], v[110:113], v[140:143], v[94:97]
	ds_read_b128 v[22:25], v100 offset:32800
	global_load_lds_dwordx4 v158, s[14:15] offset:0
	v_mfma_f32_16x16x32_bf16 v[90:93], v[110:113], v[144:147], v[90:93]
	ds_read_b128 v[46:49], v156 offset:32800
	global_load_lds_dwordx4 v159, s[14:15] offset:1024
	v_mfma_f32_16x16x32_bf16 v[82:85], v[110:113], v[148:151], v[82:85]
	ds_read_b128 v[50:53], v156 offset:34848
	global_load_lds_dwordx4 v160, s[14:15] offset:2048
	v_mfma_f32_16x16x32_bf16 v[78:81], v[110:113], v[152:155], v[78:81]
	ds_read_b128 v[30:33], v100 offset:34848
	global_load_lds_dwordx4 v161, s[14:15] offset:3072
	s_add_u32 m0, s35, 16384
	v_mfma_f32_16x16x32_bf16 v[74:77], v[114:117], v[140:143], v[74:77]
	ds_read_b128 v[54:57], v156 offset:36896
	global_load_lds_dwordx4 v158, s[16:17] offset:0
	v_mfma_f32_16x16x32_bf16 v[70:73], v[114:117], v[144:147], v[70:73]
	ds_read_b128 v[58:61], v156 offset:38944
	global_load_lds_dwordx4 v159, s[16:17] offset:1024
	v_mfma_f32_16x16x32_bf16 v[66:69], v[114:117], v[148:151], v[66:69]
	ds_read_b128 v[38:41], v100 offset:36896
	global_load_lds_dwordx4 v160, s[16:17] offset:2048
	v_mfma_f32_16x16x32_bf16 v[62:65], v[114:117], v[152:155], v[62:65]
	ds_read_b128 v[42:45], v100 offset:38944
	global_load_lds_dwordx4 v161, s[16:17] offset:3072
	v_mfma_f32_16x16x32_bf16 v[34:37], v[118:121], v[140:143], v[34:37]
	v_mfma_f32_16x16x32_bf16 v[26:29], v[118:121], v[144:147], v[26:29]
	v_mfma_f32_16x16x32_bf16 v[18:21], v[118:121], v[148:151], v[18:21]
	v_mfma_f32_16x16x32_bf16 v[14:17], v[118:121], v[152:155], v[14:17]
	v_mfma_f32_16x16x32_bf16 v[10:13], v[136:139], v[140:143], v[10:13]
	v_mfma_f32_16x16x32_bf16 v[6:9], v[136:139], v[144:147], v[6:9]
	v_mfma_f32_16x16x32_bf16 v[2:5], v[136:139], v[148:151], v[2:5]
	v_mfma_f32_16x16x32_bf16 v[86:89], v[136:139], v[152:155], v[86:89]
	s_add_u32 s99, s98, 1
	s_and_b32 s99, s99, 15
	s_sub_i32 s98, s99, s98
	s_lshl_b32 s98, s98, 7
	s_ashr_i32 s100, s98, 31
	s_add_u32 s14, s14, s98
	s_addc_u32 s15, s15, s100
	s_add_u32 s16, s16, s98
	s_addc_u32 s17, s17, s100
	s_mov_b32 s98, s99
	s_waitcnt lgkmcnt(0)
	v_mfma_f32_16x16x32_bf16 v[94:97], v[22:25], v[46:49], v[94:97]
	ds_read_b128 v[110:113], v109 offset:32800
	v_mfma_f32_16x16x32_bf16 v[90:93], v[22:25], v[50:53], v[90:93]
	ds_read_b128 v[140:143], v157 offset:32800
	v_mfma_f32_16x16x32_bf16 v[82:85], v[22:25], v[54:57], v[82:85]
	ds_read_b128 v[144:147], v157 offset:34848
	v_mfma_f32_16x16x32_bf16 v[78:81], v[22:25], v[58:61], v[78:81]
	ds_read_b128 v[114:117], v109 offset:34848
	v_mfma_f32_16x16x32_bf16 v[74:77], v[30:33], v[46:49], v[74:77]
	ds_read_b128 v[148:151], v157 offset:36896
	v_mfma_f32_16x16x32_bf16 v[70:73], v[30:33], v[50:53], v[70:73]
	ds_read_b128 v[152:155], v157 offset:38944
	v_mfma_f32_16x16x32_bf16 v[66:69], v[30:33], v[54:57], v[66:69]
	ds_read_b128 v[118:121], v109 offset:36896
	v_mfma_f32_16x16x32_bf16 v[62:65], v[30:33], v[58:61], v[62:65]
	ds_read_b128 v[136:139], v109 offset:38944
	v_mfma_f32_16x16x32_bf16 v[34:37], v[38:41], v[46:49], v[34:37]
	v_mfma_f32_16x16x32_bf16 v[26:29], v[38:41], v[50:53], v[26:29]
	v_mfma_f32_16x16x32_bf16 v[18:21], v[38:41], v[54:57], v[18:21]
	v_mfma_f32_16x16x32_bf16 v[14:17], v[38:41], v[58:61], v[14:17]
	v_mfma_f32_16x16x32_bf16 v[10:13], v[42:45], v[46:49], v[10:13]
	v_mfma_f32_16x16x32_bf16 v[6:9], v[42:45], v[50:53], v[6:9]
	v_mfma_f32_16x16x32_bf16 v[2:5], v[42:45], v[54:57], v[2:5]
	v_mfma_f32_16x16x32_bf16 v[86:89], v[42:45], v[58:61], v[86:89]
	s_waitcnt lgkmcnt(0)
	s_waitcnt vmcnt(0)
	s_add_u32 s34, s34, 1
	s_cmp_lt_u32 s34, 7
	s_cbranch_scc1 .Lk_outl0_loop
	s_barrier
	s_add_u32 m0, s35, 32768
	v_mfma_f32_16x16x32_bf16 v[94:97], v[110:113], v[140:143], v[94:97]
	ds_read_b128 v[22:25], v100 offset:32
	global_load_lds_dwordx4 v158, s[14:15] offset:0
	v_mfma_f32_16x16x32_bf16 v[90:93], v[110:113], v[144:147], v[90:93]
	ds_read_b128 v[46:49], v156 offset:32
	global_load_lds_dwordx4 v159, s[14:15] offset:1024
	v_mfma_f32_16x16x32_bf16 v[82:85], v[110:113], v[148:151], v[82:85]
	ds_read_b128 v[50:53], v156 offset:2080
	global_load_lds_dwordx4 v160, s[14:15] offset:2048
	v_mfma_f32_16x16x32_bf16 v[78:81], v[110:113], v[152:155], v[78:81]
	ds_read_b128 v[30:33], v100 offset:2080
	global_load_lds_dwordx4 v161, s[14:15] offset:3072
	s_add_u32 m0, s35, 49152
	v_mfma_f32_16x16x32_bf16 v[74:77], v[114:117], v[140:143], v[74:77]
	ds_read_b128 v[54:57], v156 offset:4128
	global_load_lds_dwordx4 v158, s[16:17] offset:0
	v_mfma_f32_16x16x32_bf16 v[70:73], v[114:117], v[144:147], v[70:73]
	ds_read_b128 v[58:61], v156 offset:6176
	global_load_lds_dwordx4 v159, s[16:17] offset:1024
	v_mfma_f32_16x16x32_bf16 v[66:69], v[114:117], v[148:151], v[66:69]
	ds_read_b128 v[38:41], v100 offset:4128
	global_load_lds_dwordx4 v160, s[16:17] offset:2048
	v_mfma_f32_16x16x32_bf16 v[62:65], v[114:117], v[152:155], v[62:65]
	ds_read_b128 v[42:45], v100 offset:6176
	global_load_lds_dwordx4 v161, s[16:17] offset:3072
	v_mfma_f32_16x16x32_bf16 v[34:37], v[118:121], v[140:143], v[34:37]
	v_mfma_f32_16x16x32_bf16 v[26:29], v[118:121], v[144:147], v[26:29]
	v_mfma_f32_16x16x32_bf16 v[18:21], v[118:121], v[148:151], v[18:21]
	v_mfma_f32_16x16x32_bf16 v[14:17], v[118:121], v[152:155], v[14:17]
	v_mfma_f32_16x16x32_bf16 v[10:13], v[136:139], v[140:143], v[10:13]
	v_mfma_f32_16x16x32_bf16 v[6:9], v[136:139], v[144:147], v[6:9]
	v_mfma_f32_16x16x32_bf16 v[2:5], v[136:139], v[148:151], v[2:5]
	v_mfma_f32_16x16x32_bf16 v[86:89], v[136:139], v[152:155], v[86:89]
	s_add_u32 s99, s98, 1
	s_and_b32 s99, s99, 15
	s_sub_i32 s98, s99, s98
	s_lshl_b32 s98, s98, 7
	s_ashr_i32 s100, s98, 31
	s_add_u32 s14, s14, s98
	s_addc_u32 s15, s15, s100
	s_add_u32 s16, s16, s98
	s_addc_u32 s17, s17, s100
	s_mov_b32 s98, s99
	s_waitcnt lgkmcnt(0)
	v_mfma_f32_16x16x32_bf16 v[94:97], v[22:25], v[46:49], v[94:97]
	ds_read_b128 v[110:113], v109 offset:32
	v_mfma_f32_16x16x32_bf16 v[90:93], v[22:25], v[50:53], v[90:93]
	ds_read_b128 v[140:143], v157 offset:32
	v_mfma_f32_16x16x32_bf16 v[82:85], v[22:25], v[54:57], v[82:85]
	ds_read_b128 v[144:147], v157 offset:2080
	v_mfma_f32_16x16x32_bf16 v[78:81], v[22:25], v[58:61], v[78:81]
	ds_read_b128 v[114:117], v109 offset:2080
	v_mfma_f32_16x16x32_bf16 v[74:77], v[30:33], v[46:49], v[74:77]
	ds_read_b128 v[148:151], v157 offset:4128
	v_mfma_f32_16x16x32_bf16 v[70:73], v[30:33], v[50:53], v[70:73]
	ds_read_b128 v[152:155], v157 offset:6176
	v_mfma_f32_16x16x32_bf16 v[66:69], v[30:33], v[54:57], v[66:69]
	ds_read_b128 v[118:121], v109 offset:4128
	v_mfma_f32_16x16x32_bf16 v[62:65], v[30:33], v[58:61], v[62:65]
	ds_read_b128 v[136:139], v109 offset:6176
	v_mfma_f32_16x16x32_bf16 v[34:37], v[38:41], v[46:49], v[34:37]
	v_mfma_f32_16x16x32_bf16 v[26:29], v[38:41], v[50:53], v[26:29]
	v_mfma_f32_16x16x32_bf16 v[18:21], v[38:41], v[54:57], v[18:21]
	v_mfma_f32_16x16x32_bf16 v[14:17], v[38:41], v[58:61], v[14:17]
	v_mfma_f32_16x16x32_bf16 v[10:13], v[42:45], v[46:49], v[10:13]
	v_mfma_f32_16x16x32_bf16 v[6:9], v[42:45], v[50:53], v[6:9]
	v_mfma_f32_16x16x32_bf16 v[2:5], v[42:45], v[54:57], v[2:5]
	v_mfma_f32_16x16x32_bf16 v[86:89], v[42:45], v[58:61], v[86:89]
	s_waitcnt lgkmcnt(0)
	s_waitcnt vmcnt(0)
	s_barrier
	v_mfma_f32_16x16x32_bf16 v[94:97], v[110:113], v[140:143], v[94:97]
	ds_read_b128 v[22:25], v100 offset:32800
	v_mfma_f32_16x16x32_bf16 v[90:93], v[110:113], v[144:147], v[90:93]
	ds_read_b128 v[46:49], v156 offset:32800
	v_mfma_f32_16x16x32_bf16 v[82:85], v[110:113], v[148:151], v[82:85]
	ds_read_b128 v[50:53], v156 offset:34848
	v_mfma_f32_16x16x32_bf16 v[78:81], v[110:113], v[152:155], v[78:81]
	ds_read_b128 v[30:33], v100 offset:34848
	v_mfma_f32_16x16x32_bf16 v[74:77], v[114:117], v[140:143], v[74:77]
	ds_read_b128 v[54:57], v156 offset:36896
	v_mfma_f32_16x16x32_bf16 v[70:73], v[114:117], v[144:147], v[70:73]
	ds_read_b128 v[58:61], v156 offset:38944
	v_mfma_f32_16x16x32_bf16 v[66:69], v[114:117], v[148:151], v[66:69]
	ds_read_b128 v[38:41], v100 offset:36896
	v_mfma_f32_16x16x32_bf16 v[62:65], v[114:117], v[152:155], v[62:65]
	ds_read_b128 v[42:45], v100 offset:38944
	v_mfma_f32_16x16x32_bf16 v[34:37], v[118:121], v[140:143], v[34:37]
	v_mfma_f32_16x16x32_bf16 v[26:29], v[118:121], v[144:147], v[26:29]
	v_mfma_f32_16x16x32_bf16 v[18:21], v[118:121], v[148:151], v[18:21]
	v_mfma_f32_16x16x32_bf16 v[14:17], v[118:121], v[152:155], v[14:17]
	v_mfma_f32_16x16x32_bf16 v[10:13], v[136:139], v[140:143], v[10:13]
	v_mfma_f32_16x16x32_bf16 v[6:9], v[136:139], v[144:147], v[6:9]
	v_mfma_f32_16x16x32_bf16 v[2:5], v[136:139], v[148:151], v[2:5]
	v_mfma_f32_16x16x32_bf16 v[86:89], v[136:139], v[152:155], v[86:89]
	s_waitcnt lgkmcnt(0)
	v_mfma_f32_16x16x32_bf16 v[94:97], v[22:25], v[46:49], v[94:97]
	ds_read_b128 v[110:113], v109 offset:32800
	v_mfma_f32_16x16x32_bf16 v[90:93], v[22:25], v[50:53], v[90:93]
	ds_read_b128 v[140:143], v157 offset:32800
	v_mfma_f32_16x16x32_bf16 v[82:85], v[22:25], v[54:57], v[82:85]
	ds_read_b128 v[144:147], v157 offset:34848
	v_mfma_f32_16x16x32_bf16 v[78:81], v[22:25], v[58:61], v[78:81]
	ds_read_b128 v[114:117], v109 offset:34848
	v_mfma_f32_16x16x32_bf16 v[74:77], v[30:33], v[46:49], v[74:77]
	ds_read_b128 v[148:151], v157 offset:36896
	v_mfma_f32_16x16x32_bf16 v[70:73], v[30:33], v[50:53], v[70:73]
	ds_read_b128 v[152:155], v157 offset:38944
	v_mfma_f32_16x16x32_bf16 v[66:69], v[30:33], v[54:57], v[66:69]
	ds_read_b128 v[118:121], v109 offset:36896
	v_mfma_f32_16x16x32_bf16 v[62:65], v[30:33], v[58:61], v[62:65]
	ds_read_b128 v[136:139], v109 offset:38944
	v_mfma_f32_16x16x32_bf16 v[34:37], v[38:41], v[46:49], v[34:37]
	v_mfma_f32_16x16x32_bf16 v[26:29], v[38:41], v[50:53], v[26:29]
	v_mfma_f32_16x16x32_bf16 v[18:21], v[38:41], v[54:57], v[18:21]
	v_mfma_f32_16x16x32_bf16 v[14:17], v[38:41], v[58:61], v[14:17]
	v_mfma_f32_16x16x32_bf16 v[10:13], v[42:45], v[46:49], v[10:13]
	v_mfma_f32_16x16x32_bf16 v[6:9], v[42:45], v[50:53], v[6:9]
	v_mfma_f32_16x16x32_bf16 v[2:5], v[42:45], v[54:57], v[2:5]
	v_mfma_f32_16x16x32_bf16 v[86:89], v[42:45], v[58:61], v[86:89]
	s_waitcnt lgkmcnt(0)
	v_mfma_f32_16x16x32_bf16 v[94:97], v[110:113], v[140:143], v[94:97]
	v_mfma_f32_16x16x32_bf16 v[90:93], v[110:113], v[144:147], v[90:93]
	v_mfma_f32_16x16x32_bf16 v[82:85], v[110:113], v[148:151], v[82:85]
	v_mfma_f32_16x16x32_bf16 v[78:81], v[110:113], v[152:155], v[78:81]
	v_mfma_f32_16x16x32_bf16 v[74:77], v[114:117], v[140:143], v[74:77]
	v_mfma_f32_16x16x32_bf16 v[70:73], v[114:117], v[144:147], v[70:73]
	v_mfma_f32_16x16x32_bf16 v[66:69], v[114:117], v[148:151], v[66:69]
	v_mfma_f32_16x16x32_bf16 v[62:65], v[114:117], v[152:155], v[62:65]
	v_mfma_f32_16x16x32_bf16 v[34:37], v[118:121], v[140:143], v[34:37]
	v_mfma_f32_16x16x32_bf16 v[26:29], v[118:121], v[144:147], v[26:29]
	v_mfma_f32_16x16x32_bf16 v[18:21], v[118:121], v[148:151], v[18:21]
	v_mfma_f32_16x16x32_bf16 v[14:17], v[118:121], v[152:155], v[14:17]
	v_mfma_f32_16x16x32_bf16 v[10:13], v[136:139], v[140:143], v[10:13]
	v_mfma_f32_16x16x32_bf16 v[6:9], v[136:139], v[144:147], v[6:9]
	v_mfma_f32_16x16x32_bf16 v[2:5], v[136:139], v[148:151], v[2:5]
	v_mfma_f32_16x16x32_bf16 v[86:89], v[136:139], v[152:155], v[86:89]
	s_waitcnt vmcnt(7)
	v_add_u32_e32 v22, 0x400, v123
	s_barrier
	ds_write2_b32 v123, v94, v90 offset1:16
	ds_write2_b32 v123, v95, v91 offset0:132 offset1:148
	ds_write2_b32 v22, v96, v92 offset0:8 offset1:24
	ds_write2_b32 v22, v97, v93 offset0:140 offset1:156
	ds_write2_b32 v123, v82, v78 offset0:32 offset1:48
	ds_write2_b32 v123, v83, v79 offset0:164 offset1:180
	ds_write2_b32 v22, v84, v80 offset0:40 offset1:56
	ds_write2_b32 v22, v85, v81 offset0:172 offset1:188
	v_add_u32_e32 v22, 0x2000, v123
	v_add_u32_e32 v23, 0x2400, v123
	ds_write2_b32 v22, v74, v70 offset0:64 offset1:80
	ds_write2_b32 v22, v75, v71 offset0:196 offset1:212
	ds_write2_b32 v23, v76, v72 offset0:72 offset1:88
	ds_write2_b32 v23, v77, v73 offset0:204 offset1:220
	ds_write2_b32 v22, v66, v62 offset0:96 offset1:112
	ds_write2_b32 v22, v67, v63 offset0:228 offset1:244
	ds_write2_b32 v23, v68, v64 offset0:104 offset1:120
	ds_write2_b32 v23, v69, v65 offset0:236 offset1:252
	v_add_u32_e32 v22, 0x4000, v123
	v_add_u32_e32 v23, 0x4400, v123
	v_add_u32_e32 v24, 0x4800, v123
	ds_write2_b32 v22, v34, v26 offset0:128 offset1:144
	ds_write2_b32 v23, v35, v27 offset0:4 offset1:20
	ds_write2_b32 v23, v36, v28 offset0:136 offset1:152
	ds_write2_b32 v24, v37, v29 offset0:12 offset1:28
	ds_write2_b32 v22, v18, v14 offset0:160 offset1:176
	ds_write2_b32 v23, v19, v15 offset0:36 offset1:52
	ds_write2_b32 v23, v20, v16 offset0:168 offset1:184
	ds_write2_b32 v24, v21, v17 offset0:44 offset1:60
	v_add_u32_e32 v14, 0x6000, v123
	ds_write2_b32 v14, v10, v6 offset0:192 offset1:208
	v_add_u32_e32 v6, 0x6400, v123
	ds_write2_b32 v6, v11, v7 offset0:68 offset1:84
	ds_write2_b32 v6, v12, v8 offset0:200 offset1:216
	v_add_u32_e32 v7, 0x6800, v123
	s_lshl_b32 s4, s33, 9
	ds_write2_b32 v7, v13, v9 offset0:76 offset1:92
	ds_write2_b32 v14, v2, v86 offset0:224 offset1:240
	ds_write2_b32 v6, v3, v87 offset0:100 offset1:116
	ds_write2_b32 v6, v4, v88 offset0:232 offset1:248
	ds_write2_b32 v7, v5, v89 offset0:108 offset1:124
	v_lshl_add_u64 v[2:3], v[102:103], 0, s[4:5]
	v_lshl_add_u64 v[4:5], v[104:105], 0, s[4:5]
	s_lshl_b32 s4, s31, 10
	s_mul_hi_u32 s14, s31, 0x15555556
	s_lshl_b32 s15, s33, 7
	v_or_b32_e32 v6, s4, v125
	s_mulk_i32 s14, 0x3000
	v_or_b32_e32 v7, s4, v127
	v_or_b32_e32 v8, s4, v129
	v_or_b32_e32 v9, s4, v133
	v_subrev_u32_e32 v6, s14, v6
	v_subrev_u32_e32 v7, s14, v7
	v_subrev_u32_e32 v8, s14, v8
	v_subrev_u32_e32 v9, s14, v9
	s_mov_b32 s14, 0
	s_lshl_b32 s4, s15, 2
	v_mov_b32_e32 v10, v132
	v_mov_b32_e32 v11, v128
	v_mov_b32_e32 v12, v126
	v_mov_b32_e32 v13, v124
	s_waitcnt lgkmcnt(0)
	s_barrier

.LBB0_927:
	s_lshl_b32 s28, s66, 7
	s_ashr_i32 s29, s28, 31
	s_lshl_b64 s[26:27], s[28:29], 10
	s_lshl_b64 s[6:7], s[28:29], 11
	s_add_u32 s6, s23, s6
	s_addc_u32 s7, s33, s7
	s_ashr_i32 s25, s24, 31
	s_lshl_b64 s[8:9], s[24:25], 18
	s_add_u32 s8, s54, s8
	s_addc_u32 s9, s55, s9
	v_and_b32_e32 v200, 15, v0
	v_bfe_u32 v201, v0, 4, 2
	v_and_b32_e32 v163, 7, v200
	v_xor_b32_e32 v201, v201, v163
	v_lshlrev_b32_e32 v201, 4, v201
	v_lshl_or_b32 v201, v200, 7, v201
	v_bfe_u32 v200, v0, 7, 1
	v_lshl_or_b32 v132, v200, 13, v201
	v_bfe_u32 v200, v0, 6, 1
	v_lshl_or_b32 v194, v200, 13, v201
	v_or_b32_e32 v194, 0x4000, v194
	v_xor_b32_e32 v163, 64, v132
	v_xor_b32_e32 v195, 64, v194
	v_bfe_u32 v200, v0, 3, 3
	v_and_b32_e32 v201, 7, v0
	v_xor_b32_e32 v201, v201, v200
	v_lshlrev_b32_e32 v201, 4, v201
	v_lshl_or_b32 v201, v200, 11, v201
	v_lshrrev_b32_e32 v200, 6, v0
	v_and_b32_e32 v200, 3, v200
	v_lshl_or_b32 v196, v200, 16, v201
	v_add_u32_e32 v197, 0x3c00, v196
	v_add_u32_e32 v198, 0x7800, v196
	v_add_u32_e32 v199, 0xb400, v196
	v_lshlrev_b32_e32 v200, 12, v200
	s_nop 0
	v_readfirstlane_b32 s14, v200
	s_add_u32 s14, s14, 32
	v_mov_b32_e32 v94, 0
	v_mov_b32_e32 v95, 0
	v_mov_b32_e32 v96, 0
	v_mov_b32_e32 v97, 0
	v_mov_b32_e32 v90, 0
	v_mov_b32_e32 v91, 0
	v_mov_b32_e32 v92, 0
	v_mov_b32_e32 v93, 0
	v_mov_b32_e32 v86, 0
	v_mov_b32_e32 v87, 0
	v_mov_b32_e32 v88, 0
	v_mov_b32_e32 v89, 0
	v_mov_b32_e32 v82, 0
	v_mov_b32_e32 v83, 0
	v_mov_b32_e32 v84, 0
	v_mov_b32_e32 v85, 0
	v_mov_b32_e32 v74, 0
	v_mov_b32_e32 v75, 0
	v_mov_b32_e32 v76, 0
	v_mov_b32_e32 v77, 0
	v_mov_b32_e32 v70, 0
	v_mov_b32_e32 v71, 0
	v_mov_b32_e32 v72, 0
	v_mov_b32_e32 v73, 0
	v_mov_b32_e32 v66, 0
	v_mov_b32_e32 v67, 0
	v_mov_b32_e32 v68, 0
	v_mov_b32_e32 v69, 0
	v_mov_b32_e32 v62, 0
	v_mov_b32_e32 v63, 0
	v_mov_b32_e32 v64, 0
	v_mov_b32_e32 v65, 0
	v_mov_b32_e32 v50, 0
	v_mov_b32_e32 v51, 0
	v_mov_b32_e32 v52, 0
	v_mov_b32_e32 v53, 0
	v_mov_b32_e32 v30, 0
	v_mov_b32_e32 v31, 0
	v_mov_b32_e32 v32, 0
	v_mov_b32_e32 v33, 0
	v_mov_b32_e32 v18, 0
	v_mov_b32_e32 v19, 0
	v_mov_b32_e32 v20, 0
	v_mov_b32_e32 v21, 0
	v_mov_b32_e32 v14, 0
	v_mov_b32_e32 v15, 0
	v_mov_b32_e32 v16, 0
	v_mov_b32_e32 v17, 0
	v_mov_b32_e32 v10, 0
	v_mov_b32_e32 v11, 0
	v_mov_b32_e32 v12, 0
	v_mov_b32_e32 v13, 0
	v_mov_b32_e32 v6, 0
	v_mov_b32_e32 v7, 0
	v_mov_b32_e32 v8, 0
	v_mov_b32_e32 v9, 0
	v_mov_b32_e32 v2, 0
	v_mov_b32_e32 v3, 0
	v_mov_b32_e32 v4, 0
	v_mov_b32_e32 v5, 0
	v_mov_b32_e32 v78, 0
	v_mov_b32_e32 v79, 0
	v_mov_b32_e32 v80, 0
	v_mov_b32_e32 v81, 0
	v_mov_b32_e32 v98, 0
	v_mov_b32_e32 v99, 0
	v_mov_b32_e32 v100, 0
	v_mov_b32_e32 v101, 0
	v_mov_b32_e32 v102, 0
	v_mov_b32_e32 v103, 0
	v_mov_b32_e32 v104, 0
	v_mov_b32_e32 v105, 0
	v_mov_b32_e32 v106, 0
	v_mov_b32_e32 v107, 0
	v_mov_b32_e32 v108, 0
	v_mov_b32_e32 v109, 0
	v_mov_b32_e32 v110, 0
	v_mov_b32_e32 v111, 0
	v_mov_b32_e32 v112, 0
	v_mov_b32_e32 v113, 0
	v_mov_b32_e32 v114, 0
	v_mov_b32_e32 v115, 0
	v_mov_b32_e32 v116, 0
	v_mov_b32_e32 v117, 0
	v_mov_b32_e32 v118, 0
	v_mov_b32_e32 v119, 0
	v_mov_b32_e32 v120, 0
	v_mov_b32_e32 v121, 0
	v_mov_b32_e32 v122, 0
	v_mov_b32_e32 v123, 0
	v_mov_b32_e32 v124, 0
	v_mov_b32_e32 v125, 0
	v_mov_b32_e32 v126, 0
	v_mov_b32_e32 v127, 0
	v_mov_b32_e32 v128, 0
	v_mov_b32_e32 v129, 0
	s_waitcnt lgkmcnt(0)
	s_barrier
	v_readlane_b32 s98, v255, 16
	s_lshr_b32 s98, s98, 3
	s_and_b32 s98, s98, 3
	s_lshl_b32 s98, s98, 2
	s_lshl_b32 s99, s98, 7
	s_add_u32 s6, s6, s99
	s_addc_u32 s7, s7, 0
	s_add_u32 s8, s8, s99
	s_addc_u32 s9, s9, 0
	s_add_u32 m0, s14, 0
	s_nop 0
	global_load_lds_dwordx4 v196, s[6:7] offset:0
	global_load_lds_dwordx4 v197, s[6:7] offset:1024
	global_load_lds_dwordx4 v198, s[6:7] offset:2048
	global_load_lds_dwordx4 v199, s[6:7] offset:3072
	s_add_u32 m0, s14, 16384
	s_nop 0
	global_load_lds_dwordx4 v196, s[8:9] offset:0
	global_load_lds_dwordx4 v197, s[8:9] offset:1024
	global_load_lds_dwordx4 v198, s[8:9] offset:2048
	global_load_lds_dwordx4 v199, s[8:9] offset:3072
	s_add_u32 s99, s98, 1
	s_and_b32 s99, s99, 15
	s_sub_i32 s98, s99, s98
	s_lshl_b32 s98, s98, 7
	s_ashr_i32 s100, s98, 31
	s_add_u32 s6, s6, s98
	s_addc_u32 s7, s7, s100
	s_add_u32 s8, s8, s98
	s_addc_u32 s9, s9, s100
	s_mov_b32 s98, s99
	s_mov_b32 s25, 0
	s_waitcnt vmcnt(0)
.Lk_g1l1_loop:
	s_barrier
	s_add_u32 m0, s14, 32768
	v_mfma_f32_16x16x32_bf16 v[94:97], v[98:101], v[114:117], v[94:97]
	ds_read_b128 v[22:25], v132 offset:32
	global_load_lds_dwordx4 v196, s[6:7] offset:0
	v_mfma_f32_16x16x32_bf16 v[90:93], v[98:101], v[118:121], v[90:93]
	ds_read_b128 v[42:45], v194 offset:32
	global_load_lds_dwordx4 v197, s[6:7] offset:1024
	v_mfma_f32_16x16x32_bf16 v[86:89], v[98:101], v[122:125], v[86:89]
	ds_read_b128 v[46:49], v194 offset:2080
	global_load_lds_dwordx4 v198, s[6:7] offset:2048
	v_mfma_f32_16x16x32_bf16 v[82:85], v[98:101], v[126:129], v[82:85]
	ds_read_b128 v[26:29], v132 offset:2080
	global_load_lds_dwordx4 v199, s[6:7] offset:3072
	s_add_u32 m0, s14, 49152
	v_mfma_f32_16x16x32_bf16 v[74:77], v[102:105], v[114:117], v[74:77]
	ds_read_b128 v[54:57], v194 offset:4128
	global_load_lds_dwordx4 v196, s[8:9] offset:0
	v_mfma_f32_16x16x32_bf16 v[70:73], v[102:105], v[118:121], v[70:73]
	ds_read_b128 v[58:61], v194 offset:6176
	global_load_lds_dwordx4 v197, s[8:9] offset:1024
	v_mfma_f32_16x16x32_bf16 v[66:69], v[102:105], v[122:125], v[66:69]
	ds_read_b128 v[34:37], v132 offset:4128
	global_load_lds_dwordx4 v198, s[8:9] offset:2048
	v_mfma_f32_16x16x32_bf16 v[62:65], v[102:105], v[126:129], v[62:65]
	ds_read_b128 v[38:41], v132 offset:6176
	global_load_lds_dwordx4 v199, s[8:9] offset:3072
	v_mfma_f32_16x16x32_bf16 v[50:53], v[106:109], v[114:117], v[50:53]
	v_mfma_f32_16x16x32_bf16 v[30:33], v[106:109], v[118:121], v[30:33]
	v_mfma_f32_16x16x32_bf16 v[18:21], v[106:109], v[122:125], v[18:21]
	v_mfma_f32_16x16x32_bf16 v[14:17], v[106:109], v[126:129], v[14:17]
	v_mfma_f32_16x16x32_bf16 v[10:13], v[110:113], v[114:117], v[10:13]
	v_mfma_f32_16x16x32_bf16 v[6:9], v[110:113], v[118:121], v[6:9]
	v_mfma_f32_16x16x32_bf16 v[2:5], v[110:113], v[122:125], v[2:5]
	v_mfma_f32_16x16x32_bf16 v[78:81], v[110:113], v[126:129], v[78:81]
	s_add_u32 s99, s98, 1
	s_and_b32 s99, s99, 15
	s_sub_i32 s98, s99, s98
	s_lshl_b32 s98, s98, 7
	s_ashr_i32 s100, s98, 31
	s_add_u32 s6, s6, s98
	s_addc_u32 s7, s7, s100
	s_add_u32 s8, s8, s98
	s_addc_u32 s9, s9, s100
	s_mov_b32 s98, s99
	s_waitcnt lgkmcnt(0)
	v_mfma_f32_16x16x32_bf16 v[94:97], v[22:25], v[42:45], v[94:97]
	ds_read_b128 v[98:101], v163 offset:32
	v_mfma_f32_16x16x32_bf16 v[90:93], v[22:25], v[46:49], v[90:93]
	ds_read_b128 v[114:117], v195 offset:32
	v_mfma_f32_16x16x32_bf16 v[86:89], v[22:25], v[54:57], v[86:89]
	ds_read_b128 v[118:121], v195 offset:2080
	v_mfma_f32_16x16x32_bf16 v[82:85], v[22:25], v[58:61], v[82:85]
	ds_read_b128 v[102:105], v163 offset:2080
	v_mfma_f32_16x16x32_bf16 v[74:77], v[26:29], v[42:45], v[74:77]
	ds_read_b128 v[122:125], v195 offset:4128
	v_mfma_f32_16x16x32_bf16 v[70:73], v[26:29], v[46:49], v[70:73]
	ds_read_b128 v[126:129], v195 offset:6176
	v_mfma_f32_16x16x32_bf16 v[66:69], v[26:29], v[54:57], v[66:69]
	ds_read_b128 v[106:109], v163 offset:4128
	v_mfma_f32_16x16x32_bf16 v[62:65], v[26:29], v[58:61], v[62:65]
	ds_read_b128 v[110:113], v163 offset:6176
	v_mfma_f32_16x16x32_bf16 v[50:53], v[34:37], v[42:45], v[50:53]
	v_mfma_f32_16x16x32_bf16 v[30:33], v[34:37], v[46:49], v[30:33]
	v_mfma_f32_16x16x32_bf16 v[18:21], v[34:37], v[54:57], v[18:21]
	v_mfma_f32_16x16x32_bf16 v[14:17], v[34:37], v[58:61], v[14:17]
	v_mfma_f32_16x16x32_bf16 v[10:13], v[38:41], v[42:45], v[10:13]
	v_mfma_f32_16x16x32_bf16 v[6:9], v[38:41], v[46:49], v[6:9]
	v_mfma_f32_16x16x32_bf16 v[2:5], v[38:41], v[54:57], v[2:5]
	v_mfma_f32_16x16x32_bf16 v[78:81], v[38:41], v[58:61], v[78:81]
	s_waitcnt lgkmcnt(0)
	s_waitcnt vmcnt(0)
	s_barrier
	s_add_u32 m0, s14, 0
	v_mfma_f32_16x16x32_bf16 v[94:97], v[98:101], v[114:117], v[94:97]
	ds_read_b128 v[22:25], v132 offset:32800
	global_load_lds_dwordx4 v196, s[6:7] offset:0
	v_mfma_f32_16x16x32_bf16 v[90:93], v[98:101], v[118:121], v[90:93]
	ds_read_b128 v[42:45], v194 offset:32800
	global_load_lds_dwordx4 v197, s[6:7] offset:1024
	v_mfma_f32_16x16x32_bf16 v[86:89], v[98:101], v[122:125], v[86:89]
	ds_read_b128 v[46:49], v194 offset:34848
	global_load_lds_dwordx4 v198, s[6:7] offset:2048
	v_mfma_f32_16x16x32_bf16 v[82:85], v[98:101], v[126:129], v[82:85]
	ds_read_b128 v[26:29], v132 offset:34848
	global_load_lds_dwordx4 v199, s[6:7] offset:3072
	s_add_u32 m0, s14, 16384
	v_mfma_f32_16x16x32_bf16 v[74:77], v[102:105], v[114:117], v[74:77]
	ds_read_b128 v[54:57], v194 offset:36896
	global_load_lds_dwordx4 v196, s[8:9] offset:0
	v_mfma_f32_16x16x32_bf16 v[70:73], v[102:105], v[118:121], v[70:73]
	ds_read_b128 v[58:61], v194 offset:38944
	global_load_lds_dwordx4 v197, s[8:9] offset:1024
	v_mfma_f32_16x16x32_bf16 v[66:69], v[102:105], v[122:125], v[66:69]
	ds_read_b128 v[34:37], v132 offset:36896
	global_load_lds_dwordx4 v198, s[8:9] offset:2048
	v_mfma_f32_16x16x32_bf16 v[62:65], v[102:105], v[126:129], v[62:65]
	ds_read_b128 v[38:41], v132 offset:38944
	global_load_lds_dwordx4 v199, s[8:9] offset:3072
	v_mfma_f32_16x16x32_bf16 v[50:53], v[106:109], v[114:117], v[50:53]
	v_mfma_f32_16x16x32_bf16 v[30:33], v[106:109], v[118:121], v[30:33]
	v_mfma_f32_16x16x32_bf16 v[18:21], v[106:109], v[122:125], v[18:21]
	v_mfma_f32_16x16x32_bf16 v[14:17], v[106:109], v[126:129], v[14:17]
	v_mfma_f32_16x16x32_bf16 v[10:13], v[110:113], v[114:117], v[10:13]
	v_mfma_f32_16x16x32_bf16 v[6:9], v[110:113], v[118:121], v[6:9]
	v_mfma_f32_16x16x32_bf16 v[2:5], v[110:113], v[122:125], v[2:5]
	v_mfma_f32_16x16x32_bf16 v[78:81], v[110:113], v[126:129], v[78:81]
	s_add_u32 s99, s98, 1
	s_and_b32 s99, s99, 15
	s_sub_i32 s98, s99, s98
	s_lshl_b32 s98, s98, 7
	s_ashr_i32 s100, s98, 31
	s_add_u32 s6, s6, s98
	s_addc_u32 s7, s7, s100
	s_add_u32 s8, s8, s98
	s_addc_u32 s9, s9, s100
	s_mov_b32 s98, s99
	s_waitcnt lgkmcnt(0)
	v_mfma_f32_16x16x32_bf16 v[94:97], v[22:25], v[42:45], v[94:97]
	ds_read_b128 v[98:101], v163 offset:32800
	v_mfma_f32_16x16x32_bf16 v[90:93], v[22:25], v[46:49], v[90:93]
	ds_read_b128 v[114:117], v195 offset:32800
	v_mfma_f32_16x16x32_bf16 v[86:89], v[22:25], v[54:57], v[86:89]
	ds_read_b128 v[118:121], v195 offset:34848
	v_mfma_f32_16x16x32_bf16 v[82:85], v[22:25], v[58:61], v[82:85]
	ds_read_b128 v[102:105], v163 offset:34848
	v_mfma_f32_16x16x32_bf16 v[74:77], v[26:29], v[42:45], v[74:77]
	ds_read_b128 v[122:125], v195 offset:36896
	v_mfma_f32_16x16x32_bf16 v[70:73], v[26:29], v[46:49], v[70:73]
	ds_read_b128 v[126:129], v195 offset:38944
	v_mfma_f32_16x16x32_bf16 v[66:69], v[26:29], v[54:57], v[66:69]
	ds_read_b128 v[106:109], v163 offset:36896
	v_mfma_f32_16x16x32_bf16 v[62:65], v[26:29], v[58:61], v[62:65]
	ds_read_b128 v[110:113], v163 offset:38944
	v_mfma_f32_16x16x32_bf16 v[50:53], v[34:37], v[42:45], v[50:53]
	v_mfma_f32_16x16x32_bf16 v[30:33], v[34:37], v[46:49], v[30:33]
	v_mfma_f32_16x16x32_bf16 v[18:21], v[34:37], v[54:57], v[18:21]
	v_mfma_f32_16x16x32_bf16 v[14:17], v[34:37], v[58:61], v[14:17]
	v_mfma_f32_16x16x32_bf16 v[10:13], v[38:41], v[42:45], v[10:13]
	v_mfma_f32_16x16x32_bf16 v[6:9], v[38:41], v[46:49], v[6:9]
	v_mfma_f32_16x16x32_bf16 v[2:5], v[38:41], v[54:57], v[2:5]
	v_mfma_f32_16x16x32_bf16 v[78:81], v[38:41], v[58:61], v[78:81]
	s_waitcnt lgkmcnt(0)
	s_waitcnt vmcnt(0)
	s_add_u32 s25, s25, 1
	s_cmp_lt_u32 s25, 7
	s_cbranch_scc1 .Lk_g1l1_loop
	s_barrier
	s_add_u32 m0, s14, 32768
	v_mfma_f32_16x16x32_bf16 v[94:97], v[98:101], v[114:117], v[94:97]
	ds_read_b128 v[22:25], v132 offset:32
	global_load_lds_dwordx4 v196, s[6:7] offset:0
	v_mfma_f32_16x16x32_bf16 v[90:93], v[98:101], v[118:121], v[90:93]
	ds_read_b128 v[42:45], v194 offset:32
	global_load_lds_dwordx4 v197, s[6:7] offset:1024
	v_mfma_f32_16x16x32_bf16 v[86:89], v[98:101], v[122:125], v[86:89]
	ds_read_b128 v[46:49], v194 offset:2080
	global_load_lds_dwordx4 v198, s[6:7] offset:2048
	v_mfma_f32_16x16x32_bf16 v[82:85], v[98:101], v[126:129], v[82:85]
	ds_read_b128 v[26:29], v132 offset:2080
	global_load_lds_dwordx4 v199, s[6:7] offset:3072
	s_add_u32 m0, s14, 49152
	v_mfma_f32_16x16x32_bf16 v[74:77], v[102:105], v[114:117], v[74:77]
	ds_read_b128 v[54:57], v194 offset:4128
	global_load_lds_dwordx4 v196, s[8:9] offset:0
	v_mfma_f32_16x16x32_bf16 v[70:73], v[102:105], v[118:121], v[70:73]
	ds_read_b128 v[58:61], v194 offset:6176
	global_load_lds_dwordx4 v197, s[8:9] offset:1024
	v_mfma_f32_16x16x32_bf16 v[66:69], v[102:105], v[122:125], v[66:69]
	ds_read_b128 v[34:37], v132 offset:4128
	global_load_lds_dwordx4 v198, s[8:9] offset:2048
	v_mfma_f32_16x16x32_bf16 v[62:65], v[102:105], v[126:129], v[62:65]
	ds_read_b128 v[38:41], v132 offset:6176
	global_load_lds_dwordx4 v199, s[8:9] offset:3072
	v_mfma_f32_16x16x32_bf16 v[50:53], v[106:109], v[114:117], v[50:53]
	v_mfma_f32_16x16x32_bf16 v[30:33], v[106:109], v[118:121], v[30:33]
	v_mfma_f32_16x16x32_bf16 v[18:21], v[106:109], v[122:125], v[18:21]
	v_mfma_f32_16x16x32_bf16 v[14:17], v[106:109], v[126:129], v[14:17]
	v_mfma_f32_16x16x32_bf16 v[10:13], v[110:113], v[114:117], v[10:13]
	v_mfma_f32_16x16x32_bf16 v[6:9], v[110:113], v[118:121], v[6:9]
	v_mfma_f32_16x16x32_bf16 v[2:5], v[110:113], v[122:125], v[2:5]
	v_mfma_f32_16x16x32_bf16 v[78:81], v[110:113], v[126:129], v[78:81]
	s_add_u32 s99, s98, 1
	s_and_b32 s99, s99, 15
	s_sub_i32 s98, s99, s98
	s_lshl_b32 s98, s98, 7
	s_ashr_i32 s100, s98, 31
	s_add_u32 s6, s6, s98
	s_addc_u32 s7, s7, s100
	s_add_u32 s8, s8, s98
	s_addc_u32 s9, s9, s100
	s_mov_b32 s98, s99
	s_waitcnt lgkmcnt(0)
	v_mfma_f32_16x16x32_bf16 v[94:97], v[22:25], v[42:45], v[94:97]
	ds_read_b128 v[98:101], v163 offset:32
	v_mfma_f32_16x16x32_bf16 v[90:93], v[22:25], v[46:49], v[90:93]
	ds_read_b128 v[114:117], v195 offset:32
	v_mfma_f32_16x16x32_bf16 v[86:89], v[22:25], v[54:57], v[86:89]
	ds_read_b128 v[118:121], v195 offset:2080
	v_mfma_f32_16x16x32_bf16 v[82:85], v[22:25], v[58:61], v[82:85]
	ds_read_b128 v[102:105], v163 offset:2080
	v_mfma_f32_16x16x32_bf16 v[74:77], v[26:29], v[42:45], v[74:77]
	ds_read_b128 v[122:125], v195 offset:4128
	v_mfma_f32_16x16x32_bf16 v[70:73], v[26:29], v[46:49], v[70:73]
	ds_read_b128 v[126:129], v195 offset:6176
	v_mfma_f32_16x16x32_bf16 v[66:69], v[26:29], v[54:57], v[66:69]
	ds_read_b128 v[106:109], v163 offset:4128
	v_mfma_f32_16x16x32_bf16 v[62:65], v[26:29], v[58:61], v[62:65]
	ds_read_b128 v[110:113], v163 offset:6176
	v_mfma_f32_16x16x32_bf16 v[50:53], v[34:37], v[42:45], v[50:53]
	v_mfma_f32_16x16x32_bf16 v[30:33], v[34:37], v[46:49], v[30:33]
	v_mfma_f32_16x16x32_bf16 v[18:21], v[34:37], v[54:57], v[18:21]
	v_mfma_f32_16x16x32_bf16 v[14:17], v[34:37], v[58:61], v[14:17]
	v_mfma_f32_16x16x32_bf16 v[10:13], v[38:41], v[42:45], v[10:13]
	v_mfma_f32_16x16x32_bf16 v[6:9], v[38:41], v[46:49], v[6:9]
	v_mfma_f32_16x16x32_bf16 v[2:5], v[38:41], v[54:57], v[2:5]
	v_mfma_f32_16x16x32_bf16 v[78:81], v[38:41], v[58:61], v[78:81]
	s_waitcnt lgkmcnt(0)
	s_waitcnt vmcnt(0)
	s_barrier
	v_mfma_f32_16x16x32_bf16 v[94:97], v[98:101], v[114:117], v[94:97]
	ds_read_b128 v[22:25], v132 offset:32800
	v_mfma_f32_16x16x32_bf16 v[90:93], v[98:101], v[118:121], v[90:93]
	ds_read_b128 v[42:45], v194 offset:32800
	v_mfma_f32_16x16x32_bf16 v[86:89], v[98:101], v[122:125], v[86:89]
	ds_read_b128 v[46:49], v194 offset:34848
	v_mfma_f32_16x16x32_bf16 v[82:85], v[98:101], v[126:129], v[82:85]
	ds_read_b128 v[26:29], v132 offset:34848
	v_mfma_f32_16x16x32_bf16 v[74:77], v[102:105], v[114:117], v[74:77]
	ds_read_b128 v[54:57], v194 offset:36896
	v_mfma_f32_16x16x32_bf16 v[70:73], v[102:105], v[118:121], v[70:73]
	ds_read_b128 v[58:61], v194 offset:38944
	v_mfma_f32_16x16x32_bf16 v[66:69], v[102:105], v[122:125], v[66:69]
	ds_read_b128 v[34:37], v132 offset:36896
	v_mfma_f32_16x16x32_bf16 v[62:65], v[102:105], v[126:129], v[62:65]
	ds_read_b128 v[38:41], v132 offset:38944
	v_mfma_f32_16x16x32_bf16 v[50:53], v[106:109], v[114:117], v[50:53]
	v_mfma_f32_16x16x32_bf16 v[30:33], v[106:109], v[118:121], v[30:33]
	v_mfma_f32_16x16x32_bf16 v[18:21], v[106:109], v[122:125], v[18:21]
	v_mfma_f32_16x16x32_bf16 v[14:17], v[106:109], v[126:129], v[14:17]
	v_mfma_f32_16x16x32_bf16 v[10:13], v[110:113], v[114:117], v[10:13]
	v_mfma_f32_16x16x32_bf16 v[6:9], v[110:113], v[118:121], v[6:9]
	v_mfma_f32_16x16x32_bf16 v[2:5], v[110:113], v[122:125], v[2:5]
	v_mfma_f32_16x16x32_bf16 v[78:81], v[110:113], v[126:129], v[78:81]
	s_waitcnt lgkmcnt(0)
	v_mfma_f32_16x16x32_bf16 v[94:97], v[22:25], v[42:45], v[94:97]
	ds_read_b128 v[98:101], v163 offset:32800
	v_mfma_f32_16x16x32_bf16 v[90:93], v[22:25], v[46:49], v[90:93]
	ds_read_b128 v[114:117], v195 offset:32800
	v_mfma_f32_16x16x32_bf16 v[86:89], v[22:25], v[54:57], v[86:89]
	ds_read_b128 v[118:121], v195 offset:34848
	v_mfma_f32_16x16x32_bf16 v[82:85], v[22:25], v[58:61], v[82:85]
	ds_read_b128 v[102:105], v163 offset:34848
	v_mfma_f32_16x16x32_bf16 v[74:77], v[26:29], v[42:45], v[74:77]
	ds_read_b128 v[122:125], v195 offset:36896
	v_mfma_f32_16x16x32_bf16 v[70:73], v[26:29], v[46:49], v[70:73]
	ds_read_b128 v[126:129], v195 offset:38944
	v_mfma_f32_16x16x32_bf16 v[66:69], v[26:29], v[54:57], v[66:69]
	ds_read_b128 v[106:109], v163 offset:36896
	v_mfma_f32_16x16x32_bf16 v[62:65], v[26:29], v[58:61], v[62:65]
	ds_read_b128 v[110:113], v163 offset:38944
	v_mfma_f32_16x16x32_bf16 v[50:53], v[34:37], v[42:45], v[50:53]
	v_mfma_f32_16x16x32_bf16 v[30:33], v[34:37], v[46:49], v[30:33]
	v_mfma_f32_16x16x32_bf16 v[18:21], v[34:37], v[54:57], v[18:21]
	v_mfma_f32_16x16x32_bf16 v[14:17], v[34:37], v[58:61], v[14:17]
	v_mfma_f32_16x16x32_bf16 v[10:13], v[38:41], v[42:45], v[10:13]
	v_mfma_f32_16x16x32_bf16 v[6:9], v[38:41], v[46:49], v[6:9]
	v_mfma_f32_16x16x32_bf16 v[2:5], v[38:41], v[54:57], v[2:5]
	v_mfma_f32_16x16x32_bf16 v[78:81], v[38:41], v[58:61], v[78:81]
	s_waitcnt lgkmcnt(0)
	v_mfma_f32_16x16x32_bf16 v[94:97], v[98:101], v[114:117], v[94:97]
	v_mfma_f32_16x16x32_bf16 v[90:93], v[98:101], v[118:121], v[90:93]
	v_mfma_f32_16x16x32_bf16 v[86:89], v[98:101], v[122:125], v[86:89]
	v_mfma_f32_16x16x32_bf16 v[82:85], v[98:101], v[126:129], v[82:85]
	v_mfma_f32_16x16x32_bf16 v[74:77], v[102:105], v[114:117], v[74:77]
	v_mfma_f32_16x16x32_bf16 v[70:73], v[102:105], v[118:121], v[70:73]
	v_mfma_f32_16x16x32_bf16 v[66:69], v[102:105], v[122:125], v[66:69]
	v_mfma_f32_16x16x32_bf16 v[62:65], v[102:105], v[126:129], v[62:65]
	v_mfma_f32_16x16x32_bf16 v[50:53], v[106:109], v[114:117], v[50:53]
	v_mfma_f32_16x16x32_bf16 v[30:33], v[106:109], v[118:121], v[30:33]
	v_mfma_f32_16x16x32_bf16 v[18:21], v[106:109], v[122:125], v[18:21]
	v_mfma_f32_16x16x32_bf16 v[14:17], v[106:109], v[126:129], v[14:17]
	v_mfma_f32_16x16x32_bf16 v[10:13], v[110:113], v[114:117], v[10:13]
	v_mfma_f32_16x16x32_bf16 v[6:9], v[110:113], v[118:121], v[6:9]
	v_mfma_f32_16x16x32_bf16 v[2:5], v[110:113], v[122:125], v[2:5]
	v_mfma_f32_16x16x32_bf16 v[78:81], v[110:113], v[126:129], v[78:81]
	s_waitcnt vmcnt(7)
	v_add_u32_e32 v22, 0x400, v170
	s_barrier
	ds_write2_b32 v170, v94, v90 offset1:16
	ds_write2_b32 v170, v95, v91 offset0:132 offset1:148
	ds_write2_b32 v22, v96, v92 offset0:8 offset1:24
	ds_write2_b32 v22, v97, v93 offset0:140 offset1:156
	ds_write2_b32 v170, v86, v82 offset0:32 offset1:48
	ds_write2_b32 v170, v87, v83 offset0:164 offset1:180
	ds_write2_b32 v22, v88, v84 offset0:40 offset1:56
	ds_write2_b32 v22, v89, v85 offset0:172 offset1:188
	v_add_u32_e32 v22, 0x2000, v170
	v_add_u32_e32 v23, 0x2400, v170
	s_cmp_gt_i32 s66, 63
	ds_write2_b32 v22, v74, v70 offset0:64 offset1:80
	ds_write2_b32 v22, v75, v71 offset0:196 offset1:212
	ds_write2_b32 v23, v76, v72 offset0:72 offset1:88
	ds_write2_b32 v23, v77, v73 offset0:204 offset1:220
	ds_write2_b32 v22, v66, v62 offset0:96 offset1:112
	ds_write2_b32 v22, v67, v63 offset0:228 offset1:244
	ds_write2_b32 v23, v68, v64 offset0:104 offset1:120
	ds_write2_b32 v23, v69, v65 offset0:236 offset1:252
	v_add_u32_e32 v22, 0x4000, v170
	v_add_u32_e32 v23, 0x4400, v170
	v_add_u32_e32 v24, 0x4800, v170
	s_cselect_b64 s[34:35], -1, 0
	s_cmp_lt_i32 s66, 64
	ds_write2_b32 v22, v50, v30 offset0:128 offset1:144
	ds_write2_b32 v23, v51, v31 offset0:4 offset1:20
	ds_write2_b32 v23, v52, v32 offset0:136 offset1:152
	ds_write2_b32 v24, v53, v33 offset0:12 offset1:28
	ds_write2_b32 v22, v18, v14 offset0:160 offset1:176
	ds_write2_b32 v23, v19, v15 offset0:36 offset1:52
	ds_write2_b32 v23, v20, v16 offset0:168 offset1:184
	ds_write2_b32 v24, v21, v17 offset0:44 offset1:60
	v_add_u32_e32 v14, 0x6000, v170
	s_cselect_b64 s[36:37], -1, 0
	s_add_i32 s6, s28, 0xffffe000
	ds_write2_b32 v14, v10, v6 offset0:192 offset1:208
	v_add_u32_e32 v6, 0x6400, v170
	s_lshr_b32 s68, s6, 10
	s_ashr_i32 s30, s66, 1
	s_and_b32 s67, s28, 0x380
	s_and_b32 s25, s28, 0x80
	ds_write2_b32 v6, v11, v7 offset0:68 offset1:84
	ds_write2_b32 v6, v12, v8 offset0:200 offset1:216
	v_add_u32_e32 v7, 0x6800, v170
	v_add_u32_e32 v164, s28, v167
	s_cmp_gt_i32 s24, 9
	s_mov_b64 s[6:7], -1
	ds_write2_b32 v7, v13, v9 offset0:76 offset1:92
	ds_write2_b32 v14, v2, v78 offset0:224 offset1:240
	ds_write2_b32 v6, v3, v79 offset0:100 offset1:116
	ds_write2_b32 v6, v4, v80 offset0:232 offset1:248
	ds_write2_b32 v7, v5, v81 offset0:108 offset1:124
	s_waitcnt lgkmcnt(0)
	s_barrier
	s_cbranch_scc0 .LBB0_979
	s_cmp_gt_u32 s24, 11
	s_cbranch_scc0 .LBB0_964
	s_cmp_lg_u32 s24, 36
	s_cbranch_scc0 .LBB0_959
	s_sub_i32 s6, s24, 20
	s_cmp_gt_u32 s6, 7
	s_mov_b64 s[6:7], -1
	s_cbranch_scc0 .LBB0_955
	s_cmp_lt_u32 s24, 16
	s_cselect_b64 s[46:47], -1, 0
	s_cmp_gt_u32 s24, 15
	s_mov_b64 s[52:53], -1
	s_cbranch_scc0 .LBB0_942
	s_cmp_gt_u32 s24, 19
	s_cbranch_scc0 .LBB0_939
	s_mov_b64 s[48:49], -1
	s_cmp_gt_u32 s24, 35
	s_mov_b64 s[8:9], -1
	s_cbranch_scc0 .LBB0_937
	s_lshl_b64 s[6:7], s[28:29], 12
	s_add_u32 s6, s42, s6
	s_addc_u32 s7, s43, s7
	s_mov_b64 s[8:9], 0

.LBB0_1292:
	s_and_b32 s70, s69, 0xff
	s_mul_i32 s4, s70, 0xab
	s_lshr_b32 s73, s4, 11
	s_mul_i32 s4, s73, 12
	s_sub_i32 s4, s69, s4
	s_and_b32 s4, s4, 0xff
	s_lshl_b32 s4, s4, 10
	s_or_b32 s8, s4, s52
	s_lshl_b32 s71, s8, 10
	s_lshl_b32 s4, s8, 11
	s_add_u32 s4, s53, s4
	s_addc_u32 s5, s54, 0
	s_lshl_b32 s6, s73, 17
	s_add_i32 s72, s6, 0x100000
	s_lshl_b32 s6, s72, 1
	s_add_u32 s6, s55, s6
	s_addc_u32 s7, s56, 0
	v_and_b32_e32 v164, 15, v0
	v_bfe_u32 v165, v0, 4, 2
	v_and_b32_e32 v111, 7, v164
	v_xor_b32_e32 v165, v165, v111
	v_lshlrev_b32_e32 v165, 4, v165
	v_lshl_or_b32 v165, v164, 7, v165
	v_bfe_u32 v164, v0, 7, 1
	v_lshl_or_b32 v100, v164, 13, v165
	v_bfe_u32 v164, v0, 6, 1
	v_lshl_or_b32 v158, v164, 13, v165
	v_or_b32_e32 v158, 0x4000, v158
	v_xor_b32_e32 v111, 64, v100
	v_xor_b32_e32 v159, 64, v158
	v_bfe_u32 v164, v0, 3, 3
	v_and_b32_e32 v165, 7, v0
	v_xor_b32_e32 v165, v165, v164
	v_lshlrev_b32_e32 v165, 4, v165
	v_lshl_or_b32 v165, v164, 11, v165
	v_lshrrev_b32_e32 v164, 6, v0
	v_and_b32_e32 v164, 3, v164
	v_lshl_or_b32 v160, v164, 16, v165
	v_add_u32_e32 v161, 0x3c00, v160
	v_add_u32_e32 v162, 0x7800, v160
	v_add_u32_e32 v163, 0xb400, v160
	v_lshlrev_b32_e32 v164, 12, v164
	s_nop 0
	v_readfirstlane_b32 s10, v164
	s_add_u32 s10, s10, 32
	v_mov_b32_e32 v94, 0
	v_mov_b32_e32 v95, 0
	v_mov_b32_e32 v96, 0
	v_mov_b32_e32 v97, 0
	v_mov_b32_e32 v90, 0
	v_mov_b32_e32 v91, 0
	v_mov_b32_e32 v92, 0
	v_mov_b32_e32 v93, 0
	v_mov_b32_e32 v82, 0
	v_mov_b32_e32 v83, 0
	v_mov_b32_e32 v84, 0
	v_mov_b32_e32 v85, 0
	v_mov_b32_e32 v78, 0
	v_mov_b32_e32 v79, 0
	v_mov_b32_e32 v80, 0
	v_mov_b32_e32 v81, 0
	v_mov_b32_e32 v74, 0
	v_mov_b32_e32 v75, 0
	v_mov_b32_e32 v76, 0
	v_mov_b32_e32 v77, 0
	v_mov_b32_e32 v70, 0
	v_mov_b32_e32 v71, 0
	v_mov_b32_e32 v72, 0
	v_mov_b32_e32 v73, 0
	v_mov_b32_e32 v66, 0
	v_mov_b32_e32 v67, 0
	v_mov_b32_e32 v68, 0
	v_mov_b32_e32 v69, 0
	v_mov_b32_e32 v58, 0
	v_mov_b32_e32 v59, 0
	v_mov_b32_e32 v60, 0
	v_mov_b32_e32 v61, 0
	v_mov_b32_e32 v26, 0
	v_mov_b32_e32 v27, 0
	v_mov_b32_e32 v28, 0
	v_mov_b32_e32 v29, 0
	v_mov_b32_e32 v22, 0
	v_mov_b32_e32 v23, 0
	v_mov_b32_e32 v24, 0
	v_mov_b32_e32 v25, 0
	v_mov_b32_e32 v18, 0
	v_mov_b32_e32 v19, 0
	v_mov_b32_e32 v20, 0
	v_mov_b32_e32 v21, 0
	v_mov_b32_e32 v14, 0
	v_mov_b32_e32 v15, 0
	v_mov_b32_e32 v16, 0
	v_mov_b32_e32 v17, 0
	v_mov_b32_e32 v10, 0
	v_mov_b32_e32 v11, 0
	v_mov_b32_e32 v12, 0
	v_mov_b32_e32 v13, 0
	v_mov_b32_e32 v6, 0
	v_mov_b32_e32 v7, 0
	v_mov_b32_e32 v8, 0
	v_mov_b32_e32 v9, 0
	v_mov_b32_e32 v2, 0
	v_mov_b32_e32 v3, 0
	v_mov_b32_e32 v4, 0
	v_mov_b32_e32 v5, 0
	v_mov_b32_e32 v86, 0
	v_mov_b32_e32 v87, 0
	v_mov_b32_e32 v88, 0
	v_mov_b32_e32 v89, 0
	v_mov_b32_e32 v114, 0
	v_mov_b32_e32 v115, 0
	v_mov_b32_e32 v116, 0
	v_mov_b32_e32 v117, 0
	v_mov_b32_e32 v118, 0
	v_mov_b32_e32 v119, 0
	v_mov_b32_e32 v120, 0
	v_mov_b32_e32 v121, 0
	v_mov_b32_e32 v122, 0
	v_mov_b32_e32 v123, 0
	v_mov_b32_e32 v124, 0
	v_mov_b32_e32 v125, 0
	v_mov_b32_e32 v138, 0
	v_mov_b32_e32 v139, 0
	v_mov_b32_e32 v140, 0
	v_mov_b32_e32 v141, 0
	v_mov_b32_e32 v142, 0
	v_mov_b32_e32 v143, 0
	v_mov_b32_e32 v144, 0
	v_mov_b32_e32 v145, 0
	v_mov_b32_e32 v146, 0
	v_mov_b32_e32 v147, 0
	v_mov_b32_e32 v148, 0
	v_mov_b32_e32 v149, 0
	v_mov_b32_e32 v150, 0
	v_mov_b32_e32 v151, 0
	v_mov_b32_e32 v152, 0
	v_mov_b32_e32 v153, 0
	v_mov_b32_e32 v154, 0
	v_mov_b32_e32 v155, 0
	v_mov_b32_e32 v156, 0
	v_mov_b32_e32 v157, 0
	s_waitcnt lgkmcnt(0)
	s_barrier
	v_readlane_b32 s98, v255, 16
	s_lshr_b32 s98, s98, 3
	s_and_b32 s98, s98, 3
	s_lshl_b32 s98, s98, 2
	s_lshl_b32 s99, s98, 7
	s_add_u32 s4, s4, s99
	s_addc_u32 s5, s5, 0
	s_add_u32 s6, s6, s99
	s_addc_u32 s7, s7, 0
	s_add_u32 m0, s10, 0
	s_nop 0
	global_load_lds_dwordx4 v160, s[4:5] offset:0
	global_load_lds_dwordx4 v161, s[4:5] offset:1024
	global_load_lds_dwordx4 v162, s[4:5] offset:2048
	global_load_lds_dwordx4 v163, s[4:5] offset:3072
	s_add_u32 m0, s10, 16384
	s_nop 0
	global_load_lds_dwordx4 v160, s[6:7] offset:0
	global_load_lds_dwordx4 v161, s[6:7] offset:1024
	global_load_lds_dwordx4 v162, s[6:7] offset:2048
	global_load_lds_dwordx4 v163, s[6:7] offset:3072
	s_add_u32 s99, s98, 1
	s_and_b32 s99, s99, 15
	s_sub_i32 s98, s99, s98
	s_lshl_b32 s98, s98, 7
	s_ashr_i32 s100, s98, 31
	s_add_u32 s4, s4, s98
	s_addc_u32 s5, s5, s100
	s_add_u32 s6, s6, s98
	s_addc_u32 s7, s7, s100
	s_mov_b32 s98, s99
	s_mov_b32 s9, 0
	s_waitcnt vmcnt(0)
.Lk_aol1a_loop:
	s_barrier
	s_add_u32 m0, s10, 32768
	v_mfma_f32_16x16x32_bf16 v[94:97], v[114:117], v[142:145], v[94:97]
	ds_read_b128 v[30:33], v100 offset:32
	global_load_lds_dwordx4 v160, s[4:5] offset:0
	v_mfma_f32_16x16x32_bf16 v[90:93], v[114:117], v[146:149], v[90:93]
	ds_read_b128 v[46:49], v158 offset:32
	global_load_lds_dwordx4 v161, s[4:5] offset:1024
	v_mfma_f32_16x16x32_bf16 v[82:85], v[114:117], v[150:153], v[82:85]
	ds_read_b128 v[50:53], v158 offset:2080
	global_load_lds_dwordx4 v162, s[4:5] offset:2048
	v_mfma_f32_16x16x32_bf16 v[78:81], v[114:117], v[154:157], v[78:81]
	ds_read_b128 v[34:37], v100 offset:2080
	global_load_lds_dwordx4 v163, s[4:5] offset:3072
	s_add_u32 m0, s10, 49152
	v_mfma_f32_16x16x32_bf16 v[74:77], v[118:121], v[142:145], v[74:77]
	ds_read_b128 v[54:57], v158 offset:4128
	global_load_lds_dwordx4 v160, s[6:7] offset:0
	v_mfma_f32_16x16x32_bf16 v[70:73], v[118:121], v[146:149], v[70:73]
	ds_read_b128 v[62:65], v158 offset:6176
	global_load_lds_dwordx4 v161, s[6:7] offset:1024
	v_mfma_f32_16x16x32_bf16 v[66:69], v[118:121], v[150:153], v[66:69]
	ds_read_b128 v[38:41], v100 offset:4128
	global_load_lds_dwordx4 v162, s[6:7] offset:2048
	v_mfma_f32_16x16x32_bf16 v[58:61], v[118:121], v[154:157], v[58:61]
	ds_read_b128 v[42:45], v100 offset:6176
	global_load_lds_dwordx4 v163, s[6:7] offset:3072
	v_mfma_f32_16x16x32_bf16 v[26:29], v[122:125], v[142:145], v[26:29]
	v_mfma_f32_16x16x32_bf16 v[22:25], v[122:125], v[146:149], v[22:25]
	v_mfma_f32_16x16x32_bf16 v[18:21], v[122:125], v[150:153], v[18:21]
	v_mfma_f32_16x16x32_bf16 v[14:17], v[122:125], v[154:157], v[14:17]
	v_mfma_f32_16x16x32_bf16 v[10:13], v[138:141], v[142:145], v[10:13]
	v_mfma_f32_16x16x32_bf16 v[6:9], v[138:141], v[146:149], v[6:9]
	v_mfma_f32_16x16x32_bf16 v[2:5], v[138:141], v[150:153], v[2:5]
	v_mfma_f32_16x16x32_bf16 v[86:89], v[138:141], v[154:157], v[86:89]
	s_add_u32 s99, s98, 1
	s_and_b32 s99, s99, 15
	s_sub_i32 s98, s99, s98
	s_lshl_b32 s98, s98, 7
	s_ashr_i32 s100, s98, 31
	s_add_u32 s4, s4, s98
	s_addc_u32 s5, s5, s100
	s_add_u32 s6, s6, s98
	s_addc_u32 s7, s7, s100
	s_mov_b32 s98, s99
	s_waitcnt lgkmcnt(0)
	v_mfma_f32_16x16x32_bf16 v[94:97], v[30:33], v[46:49], v[94:97]
	ds_read_b128 v[114:117], v111 offset:32
	v_mfma_f32_16x16x32_bf16 v[90:93], v[30:33], v[50:53], v[90:93]
	ds_read_b128 v[142:145], v159 offset:32
	v_mfma_f32_16x16x32_bf16 v[82:85], v[30:33], v[54:57], v[82:85]
	ds_read_b128 v[146:149], v159 offset:2080
	v_mfma_f32_16x16x32_bf16 v[78:81], v[30:33], v[62:65], v[78:81]
	ds_read_b128 v[118:121], v111 offset:2080
	v_mfma_f32_16x16x32_bf16 v[74:77], v[34:37], v[46:49], v[74:77]
	ds_read_b128 v[150:153], v159 offset:4128
	v_mfma_f32_16x16x32_bf16 v[70:73], v[34:37], v[50:53], v[70:73]
	ds_read_b128 v[154:157], v159 offset:6176
	v_mfma_f32_16x16x32_bf16 v[66:69], v[34:37], v[54:57], v[66:69]
	ds_read_b128 v[122:125], v111 offset:4128
	v_mfma_f32_16x16x32_bf16 v[58:61], v[34:37], v[62:65], v[58:61]
	ds_read_b128 v[138:141], v111 offset:6176
	v_mfma_f32_16x16x32_bf16 v[26:29], v[38:41], v[46:49], v[26:29]
	v_mfma_f32_16x16x32_bf16 v[22:25], v[38:41], v[50:53], v[22:25]
	v_mfma_f32_16x16x32_bf16 v[18:21], v[38:41], v[54:57], v[18:21]
	v_mfma_f32_16x16x32_bf16 v[14:17], v[38:41], v[62:65], v[14:17]
	v_mfma_f32_16x16x32_bf16 v[10:13], v[42:45], v[46:49], v[10:13]
	v_mfma_f32_16x16x32_bf16 v[6:9], v[42:45], v[50:53], v[6:9]
	v_mfma_f32_16x16x32_bf16 v[2:5], v[42:45], v[54:57], v[2:5]
	v_mfma_f32_16x16x32_bf16 v[86:89], v[42:45], v[62:65], v[86:89]
	s_waitcnt lgkmcnt(0)
	s_waitcnt vmcnt(0)
	s_barrier
	s_add_u32 m0, s10, 0
	v_mfma_f32_16x16x32_bf16 v[94:97], v[114:117], v[142:145], v[94:97]
	ds_read_b128 v[30:33], v100 offset:32800
	global_load_lds_dwordx4 v160, s[4:5] offset:0
	v_mfma_f32_16x16x32_bf16 v[90:93], v[114:117], v[146:149], v[90:93]
	ds_read_b128 v[46:49], v158 offset:32800
	global_load_lds_dwordx4 v161, s[4:5] offset:1024
	v_mfma_f32_16x16x32_bf16 v[82:85], v[114:117], v[150:153], v[82:85]
	ds_read_b128 v[50:53], v158 offset:34848
	global_load_lds_dwordx4 v162, s[4:5] offset:2048
	v_mfma_f32_16x16x32_bf16 v[78:81], v[114:117], v[154:157], v[78:81]
	ds_read_b128 v[34:37], v100 offset:34848
	global_load_lds_dwordx4 v163, s[4:5] offset:3072
	s_add_u32 m0, s10, 16384
	v_mfma_f32_16x16x32_bf16 v[74:77], v[118:121], v[142:145], v[74:77]
	ds_read_b128 v[54:57], v158 offset:36896
	global_load_lds_dwordx4 v160, s[6:7] offset:0
	v_mfma_f32_16x16x32_bf16 v[70:73], v[118:121], v[146:149], v[70:73]
	ds_read_b128 v[62:65], v158 offset:38944
	global_load_lds_dwordx4 v161, s[6:7] offset:1024
	v_mfma_f32_16x16x32_bf16 v[66:69], v[118:121], v[150:153], v[66:69]
	ds_read_b128 v[38:41], v100 offset:36896
	global_load_lds_dwordx4 v162, s[6:7] offset:2048
	v_mfma_f32_16x16x32_bf16 v[58:61], v[118:121], v[154:157], v[58:61]
	ds_read_b128 v[42:45], v100 offset:38944
	global_load_lds_dwordx4 v163, s[6:7] offset:3072
	v_mfma_f32_16x16x32_bf16 v[26:29], v[122:125], v[142:145], v[26:29]
	v_mfma_f32_16x16x32_bf16 v[22:25], v[122:125], v[146:149], v[22:25]
	v_mfma_f32_16x16x32_bf16 v[18:21], v[122:125], v[150:153], v[18:21]
	v_mfma_f32_16x16x32_bf16 v[14:17], v[122:125], v[154:157], v[14:17]
	v_mfma_f32_16x16x32_bf16 v[10:13], v[138:141], v[142:145], v[10:13]
	v_mfma_f32_16x16x32_bf16 v[6:9], v[138:141], v[146:149], v[6:9]
	v_mfma_f32_16x16x32_bf16 v[2:5], v[138:141], v[150:153], v[2:5]
	v_mfma_f32_16x16x32_bf16 v[86:89], v[138:141], v[154:157], v[86:89]
	s_add_u32 s99, s98, 1
	s_and_b32 s99, s99, 15
	s_sub_i32 s98, s99, s98
	s_lshl_b32 s98, s98, 7
	s_ashr_i32 s100, s98, 31
	s_add_u32 s4, s4, s98
	s_addc_u32 s5, s5, s100
	s_add_u32 s6, s6, s98
	s_addc_u32 s7, s7, s100
	s_mov_b32 s98, s99
	s_waitcnt lgkmcnt(0)
	v_mfma_f32_16x16x32_bf16 v[94:97], v[30:33], v[46:49], v[94:97]
	ds_read_b128 v[114:117], v111 offset:32800
	v_mfma_f32_16x16x32_bf16 v[90:93], v[30:33], v[50:53], v[90:93]
	ds_read_b128 v[142:145], v159 offset:32800
	v_mfma_f32_16x16x32_bf16 v[82:85], v[30:33], v[54:57], v[82:85]
	ds_read_b128 v[146:149], v159 offset:34848
	v_mfma_f32_16x16x32_bf16 v[78:81], v[30:33], v[62:65], v[78:81]
	ds_read_b128 v[118:121], v111 offset:34848
	v_mfma_f32_16x16x32_bf16 v[74:77], v[34:37], v[46:49], v[74:77]
	ds_read_b128 v[150:153], v159 offset:36896
	v_mfma_f32_16x16x32_bf16 v[70:73], v[34:37], v[50:53], v[70:73]
	ds_read_b128 v[154:157], v159 offset:38944
	v_mfma_f32_16x16x32_bf16 v[66:69], v[34:37], v[54:57], v[66:69]
	ds_read_b128 v[122:125], v111 offset:36896
	v_mfma_f32_16x16x32_bf16 v[58:61], v[34:37], v[62:65], v[58:61]
	ds_read_b128 v[138:141], v111 offset:38944
	v_mfma_f32_16x16x32_bf16 v[26:29], v[38:41], v[46:49], v[26:29]
	v_mfma_f32_16x16x32_bf16 v[22:25], v[38:41], v[50:53], v[22:25]
	v_mfma_f32_16x16x32_bf16 v[18:21], v[38:41], v[54:57], v[18:21]
	v_mfma_f32_16x16x32_bf16 v[14:17], v[38:41], v[62:65], v[14:17]
	v_mfma_f32_16x16x32_bf16 v[10:13], v[42:45], v[46:49], v[10:13]
	v_mfma_f32_16x16x32_bf16 v[6:9], v[42:45], v[50:53], v[6:9]
	v_mfma_f32_16x16x32_bf16 v[2:5], v[42:45], v[54:57], v[2:5]
	v_mfma_f32_16x16x32_bf16 v[86:89], v[42:45], v[62:65], v[86:89]
	s_waitcnt lgkmcnt(0)
	s_waitcnt vmcnt(0)
	s_add_u32 s9, s9, 1
	s_cmp_lt_u32 s9, 7
	s_cbranch_scc1 .Lk_aol1a_loop
	s_barrier
	s_add_u32 m0, s10, 32768
	v_mfma_f32_16x16x32_bf16 v[94:97], v[114:117], v[142:145], v[94:97]
	ds_read_b128 v[30:33], v100 offset:32
	global_load_lds_dwordx4 v160, s[4:5] offset:0
	v_mfma_f32_16x16x32_bf16 v[90:93], v[114:117], v[146:149], v[90:93]
	ds_read_b128 v[46:49], v158 offset:32
	global_load_lds_dwordx4 v161, s[4:5] offset:1024
	v_mfma_f32_16x16x32_bf16 v[82:85], v[114:117], v[150:153], v[82:85]
	ds_read_b128 v[50:53], v158 offset:2080
	global_load_lds_dwordx4 v162, s[4:5] offset:2048
	v_mfma_f32_16x16x32_bf16 v[78:81], v[114:117], v[154:157], v[78:81]
	ds_read_b128 v[34:37], v100 offset:2080
	global_load_lds_dwordx4 v163, s[4:5] offset:3072
	s_add_u32 m0, s10, 49152
	v_mfma_f32_16x16x32_bf16 v[74:77], v[118:121], v[142:145], v[74:77]
	ds_read_b128 v[54:57], v158 offset:4128
	global_load_lds_dwordx4 v160, s[6:7] offset:0
	v_mfma_f32_16x16x32_bf16 v[70:73], v[118:121], v[146:149], v[70:73]
	ds_read_b128 v[62:65], v158 offset:6176
	global_load_lds_dwordx4 v161, s[6:7] offset:1024
	v_mfma_f32_16x16x32_bf16 v[66:69], v[118:121], v[150:153], v[66:69]
	ds_read_b128 v[38:41], v100 offset:4128
	global_load_lds_dwordx4 v162, s[6:7] offset:2048
	v_mfma_f32_16x16x32_bf16 v[58:61], v[118:121], v[154:157], v[58:61]
	ds_read_b128 v[42:45], v100 offset:6176
	global_load_lds_dwordx4 v163, s[6:7] offset:3072
	v_mfma_f32_16x16x32_bf16 v[26:29], v[122:125], v[142:145], v[26:29]
	v_mfma_f32_16x16x32_bf16 v[22:25], v[122:125], v[146:149], v[22:25]
	v_mfma_f32_16x16x32_bf16 v[18:21], v[122:125], v[150:153], v[18:21]
	v_mfma_f32_16x16x32_bf16 v[14:17], v[122:125], v[154:157], v[14:17]
	v_mfma_f32_16x16x32_bf16 v[10:13], v[138:141], v[142:145], v[10:13]
	v_mfma_f32_16x16x32_bf16 v[6:9], v[138:141], v[146:149], v[6:9]
	v_mfma_f32_16x16x32_bf16 v[2:5], v[138:141], v[150:153], v[2:5]
	v_mfma_f32_16x16x32_bf16 v[86:89], v[138:141], v[154:157], v[86:89]
	s_add_u32 s99, s98, 1
	s_and_b32 s99, s99, 15
	s_sub_i32 s98, s99, s98
	s_lshl_b32 s98, s98, 7
	s_ashr_i32 s100, s98, 31
	s_add_u32 s4, s4, s98
	s_addc_u32 s5, s5, s100
	s_add_u32 s6, s6, s98
	s_addc_u32 s7, s7, s100
	s_mov_b32 s98, s99
	s_waitcnt lgkmcnt(0)
	v_mfma_f32_16x16x32_bf16 v[94:97], v[30:33], v[46:49], v[94:97]
	ds_read_b128 v[114:117], v111 offset:32
	v_mfma_f32_16x16x32_bf16 v[90:93], v[30:33], v[50:53], v[90:93]
	ds_read_b128 v[142:145], v159 offset:32
	v_mfma_f32_16x16x32_bf16 v[82:85], v[30:33], v[54:57], v[82:85]
	ds_read_b128 v[146:149], v159 offset:2080
	v_mfma_f32_16x16x32_bf16 v[78:81], v[30:33], v[62:65], v[78:81]
	ds_read_b128 v[118:121], v111 offset:2080
	v_mfma_f32_16x16x32_bf16 v[74:77], v[34:37], v[46:49], v[74:77]
	ds_read_b128 v[150:153], v159 offset:4128
	v_mfma_f32_16x16x32_bf16 v[70:73], v[34:37], v[50:53], v[70:73]
	ds_read_b128 v[154:157], v159 offset:6176
	v_mfma_f32_16x16x32_bf16 v[66:69], v[34:37], v[54:57], v[66:69]
	ds_read_b128 v[122:125], v111 offset:4128
	v_mfma_f32_16x16x32_bf16 v[58:61], v[34:37], v[62:65], v[58:61]
	ds_read_b128 v[138:141], v111 offset:6176
	v_mfma_f32_16x16x32_bf16 v[26:29], v[38:41], v[46:49], v[26:29]
	v_mfma_f32_16x16x32_bf16 v[22:25], v[38:41], v[50:53], v[22:25]
	v_mfma_f32_16x16x32_bf16 v[18:21], v[38:41], v[54:57], v[18:21]
	v_mfma_f32_16x16x32_bf16 v[14:17], v[38:41], v[62:65], v[14:17]
	v_mfma_f32_16x16x32_bf16 v[10:13], v[42:45], v[46:49], v[10:13]
	v_mfma_f32_16x16x32_bf16 v[6:9], v[42:45], v[50:53], v[6:9]
	v_mfma_f32_16x16x32_bf16 v[2:5], v[42:45], v[54:57], v[2:5]
	v_mfma_f32_16x16x32_bf16 v[86:89], v[42:45], v[62:65], v[86:89]
	s_waitcnt lgkmcnt(0)
	s_waitcnt vmcnt(0)
	s_barrier
	v_mfma_f32_16x16x32_bf16 v[94:97], v[114:117], v[142:145], v[94:97]
	ds_read_b128 v[30:33], v100 offset:32800
	v_mfma_f32_16x16x32_bf16 v[90:93], v[114:117], v[146:149], v[90:93]
	ds_read_b128 v[46:49], v158 offset:32800
	v_mfma_f32_16x16x32_bf16 v[82:85], v[114:117], v[150:153], v[82:85]
	ds_read_b128 v[50:53], v158 offset:34848
	v_mfma_f32_16x16x32_bf16 v[78:81], v[114:117], v[154:157], v[78:81]
	ds_read_b128 v[34:37], v100 offset:34848
	v_mfma_f32_16x16x32_bf16 v[74:77], v[118:121], v[142:145], v[74:77]
	ds_read_b128 v[54:57], v158 offset:36896
	v_mfma_f32_16x16x32_bf16 v[70:73], v[118:121], v[146:149], v[70:73]
	ds_read_b128 v[62:65], v158 offset:38944
	v_mfma_f32_16x16x32_bf16 v[66:69], v[118:121], v[150:153], v[66:69]
	ds_read_b128 v[38:41], v100 offset:36896
	v_mfma_f32_16x16x32_bf16 v[58:61], v[118:121], v[154:157], v[58:61]
	ds_read_b128 v[42:45], v100 offset:38944
	v_mfma_f32_16x16x32_bf16 v[26:29], v[122:125], v[142:145], v[26:29]
	v_mfma_f32_16x16x32_bf16 v[22:25], v[122:125], v[146:149], v[22:25]
	v_mfma_f32_16x16x32_bf16 v[18:21], v[122:125], v[150:153], v[18:21]
	v_mfma_f32_16x16x32_bf16 v[14:17], v[122:125], v[154:157], v[14:17]
	v_mfma_f32_16x16x32_bf16 v[10:13], v[138:141], v[142:145], v[10:13]
	v_mfma_f32_16x16x32_bf16 v[6:9], v[138:141], v[146:149], v[6:9]
	v_mfma_f32_16x16x32_bf16 v[2:5], v[138:141], v[150:153], v[2:5]
	v_mfma_f32_16x16x32_bf16 v[86:89], v[138:141], v[154:157], v[86:89]
	s_waitcnt lgkmcnt(0)
	v_mfma_f32_16x16x32_bf16 v[94:97], v[30:33], v[46:49], v[94:97]
	ds_read_b128 v[114:117], v111 offset:32800
	v_mfma_f32_16x16x32_bf16 v[90:93], v[30:33], v[50:53], v[90:93]
	ds_read_b128 v[142:145], v159 offset:32800
	v_mfma_f32_16x16x32_bf16 v[82:85], v[30:33], v[54:57], v[82:85]
	ds_read_b128 v[146:149], v159 offset:34848
	v_mfma_f32_16x16x32_bf16 v[78:81], v[30:33], v[62:65], v[78:81]
	ds_read_b128 v[118:121], v111 offset:34848
	v_mfma_f32_16x16x32_bf16 v[74:77], v[34:37], v[46:49], v[74:77]
	ds_read_b128 v[150:153], v159 offset:36896
	v_mfma_f32_16x16x32_bf16 v[70:73], v[34:37], v[50:53], v[70:73]
	ds_read_b128 v[154:157], v159 offset:38944
	v_mfma_f32_16x16x32_bf16 v[66:69], v[34:37], v[54:57], v[66:69]
	ds_read_b128 v[122:125], v111 offset:36896
	v_mfma_f32_16x16x32_bf16 v[58:61], v[34:37], v[62:65], v[58:61]
	ds_read_b128 v[138:141], v111 offset:38944
	v_mfma_f32_16x16x32_bf16 v[26:29], v[38:41], v[46:49], v[26:29]
	v_mfma_f32_16x16x32_bf16 v[22:25], v[38:41], v[50:53], v[22:25]
	v_mfma_f32_16x16x32_bf16 v[18:21], v[38:41], v[54:57], v[18:21]
	v_mfma_f32_16x16x32_bf16 v[14:17], v[38:41], v[62:65], v[14:17]
	v_mfma_f32_16x16x32_bf16 v[10:13], v[42:45], v[46:49], v[10:13]
	v_mfma_f32_16x16x32_bf16 v[6:9], v[42:45], v[50:53], v[6:9]
	v_mfma_f32_16x16x32_bf16 v[2:5], v[42:45], v[54:57], v[2:5]
	v_mfma_f32_16x16x32_bf16 v[86:89], v[42:45], v[62:65], v[86:89]
	s_waitcnt lgkmcnt(0)
	v_mfma_f32_16x16x32_bf16 v[94:97], v[114:117], v[142:145], v[94:97]
	v_mfma_f32_16x16x32_bf16 v[90:93], v[114:117], v[146:149], v[90:93]
	v_mfma_f32_16x16x32_bf16 v[82:85], v[114:117], v[150:153], v[82:85]
	v_mfma_f32_16x16x32_bf16 v[78:81], v[114:117], v[154:157], v[78:81]
	v_mfma_f32_16x16x32_bf16 v[74:77], v[118:121], v[142:145], v[74:77]
	v_mfma_f32_16x16x32_bf16 v[70:73], v[118:121], v[146:149], v[70:73]
	v_mfma_f32_16x16x32_bf16 v[66:69], v[118:121], v[150:153], v[66:69]
	v_mfma_f32_16x16x32_bf16 v[58:61], v[118:121], v[154:157], v[58:61]
	v_mfma_f32_16x16x32_bf16 v[26:29], v[122:125], v[142:145], v[26:29]
	v_mfma_f32_16x16x32_bf16 v[22:25], v[122:125], v[146:149], v[22:25]
	v_mfma_f32_16x16x32_bf16 v[18:21], v[122:125], v[150:153], v[18:21]
	v_mfma_f32_16x16x32_bf16 v[14:17], v[122:125], v[154:157], v[14:17]
	v_mfma_f32_16x16x32_bf16 v[10:13], v[138:141], v[142:145], v[10:13]
	v_mfma_f32_16x16x32_bf16 v[6:9], v[138:141], v[146:149], v[6:9]
	v_mfma_f32_16x16x32_bf16 v[2:5], v[138:141], v[150:153], v[2:5]
	v_mfma_f32_16x16x32_bf16 v[86:89], v[138:141], v[154:157], v[86:89]
	s_mul_i32 s4, s68, s62
	s_add_i32 s4, s4, s67
	s_and_b32 s4, s4, 0xff
	s_waitcnt vmcnt(7)
	v_lshl_or_b32 v30, s4, 10, v132
	s_mul_hi_u32 s4, s4, 0x15555556
	s_mulk_i32 s4, 0xd000
	v_add_u32_e32 v30, s4, v30
	s_lshl_b32 s36, s73, 8
	v_add_u32_e32 v138, 0x400, v129
	v_add_u32_e32 v139, 0x2000, v129
	v_add_u32_e32 v140, 0x2400, v129
	v_add_u32_e32 v141, 0x4000, v129
	v_add_u32_e32 v142, 0x4400, v129
	v_add_u32_e32 v143, 0x4800, v129
	v_add_u32_e32 v144, 0x6000, v129
	v_add_u32_e32 v145, 0x6400, v129
	v_add_u32_e32 v146, 0x6800, v129
	v_lshl_add_u64 v[114:115], v[102:103], 0, s[36:37]
	v_cmp_gt_u32_e32 vcc, s66, v30
	s_barrier
	ds_write2_b32 v129, v94, v90 offset1:16
	ds_write2_b32 v129, v95, v91 offset0:132 offset1:148
	ds_write2_b32 v138, v96, v92 offset0:8 offset1:24
	ds_write2_b32 v138, v97, v93 offset0:140 offset1:156
	ds_write2_b32 v129, v82, v78 offset0:32 offset1:48
	ds_write2_b32 v129, v83, v79 offset0:164 offset1:180
	ds_write2_b32 v138, v84, v80 offset0:40 offset1:56
	ds_write2_b32 v138, v85, v81 offset0:172 offset1:188
	ds_write2_b32 v139, v74, v70 offset0:64 offset1:80
	ds_write2_b32 v139, v75, v71 offset0:196 offset1:212
	ds_write2_b32 v140, v76, v72 offset0:72 offset1:88
	ds_write2_b32 v140, v77, v73 offset0:204 offset1:220
	ds_write2_b32 v139, v66, v58 offset0:96 offset1:112
	ds_write2_b32 v139, v67, v59 offset0:228 offset1:244
	ds_write2_b32 v140, v68, v60 offset0:104 offset1:120
	ds_write2_b32 v140, v69, v61 offset0:236 offset1:252
	ds_write2_b32 v141, v26, v22 offset0:128 offset1:144
	ds_write2_b32 v142, v27, v23 offset0:4 offset1:20
	ds_write2_b32 v142, v28, v24 offset0:136 offset1:152
	ds_write2_b32 v143, v29, v25 offset0:12 offset1:28
	ds_write2_b32 v141, v18, v14 offset0:160 offset1:176
	ds_write2_b32 v142, v19, v15 offset0:36 offset1:52
	ds_write2_b32 v142, v20, v16 offset0:168 offset1:184
	ds_write2_b32 v143, v21, v17 offset0:44 offset1:60
	ds_write2_b32 v144, v10, v6 offset0:192 offset1:208
	ds_write2_b32 v145, v11, v7 offset0:68 offset1:84
	ds_write2_b32 v145, v12, v8 offset0:200 offset1:216
	ds_write2_b32 v146, v13, v9 offset0:76 offset1:92
	ds_write2_b32 v144, v2, v86 offset0:224 offset1:240
	ds_write2_b32 v145, v3, v87 offset0:100 offset1:116
	ds_write2_b32 v145, v4, v88 offset0:232 offset1:248
	ds_write2_b32 v146, v5, v89 offset0:108 offset1:124
	s_waitcnt lgkmcnt(0)
	s_barrier
	s_and_saveexec_b64 s[4:5], vcc
	s_xor_b64 s[4:5], exec, s[4:5]
	s_cbranch_execz .LBB0_1297
	s_mov_b32 s6, s8
	s_mov_b32 s7, 1
	s_mov_b32 s9, 0
	s_mov_b32 s10, 8

.LBB0_1300:
	s_or_b64 exec, exec, s[50:51]
	s_lshl_b32 s4, s73, 7
	s_lshl_b32 s5, s71, 1
	s_add_u32 s6, s58, s5
	s_addc_u32 s7, s59, 0
	s_lshl_b32 s5, s72, 1
	v_mov_b32_e32 v111, v101
	s_add_u32 s8, s60, s5
	s_addc_u32 s9, s61, 0
	s_waitcnt lgkmcnt(0)
	s_barrier
	ds_read2_b32 v[26:27], v129 offset1:16
	ds_read2_b32 v[148:149], v129 offset0:132 offset1:148
	ds_read2_b32 v[28:29], v138 offset0:8 offset1:24
	ds_read2_b32 v[150:151], v138 offset0:140 offset1:156
	ds_read2_b32 v[22:23], v129 offset0:32 offset1:48
	ds_read2_b32 v[152:153], v129 offset0:164 offset1:180
	ds_read2_b32 v[24:25], v138 offset0:40 offset1:56
	ds_read2_b32 v[154:155], v138 offset0:172 offset1:188
	ds_read2_b32 v[18:19], v139 offset0:64 offset1:80
	ds_read2_b32 v[156:157], v139 offset0:196 offset1:212
	ds_read2_b32 v[20:21], v140 offset0:72 offset1:88
	ds_read2_b32 v[158:159], v140 offset0:204 offset1:220
	ds_read2_b32 v[14:15], v139 offset0:96 offset1:112
	ds_read2_b32 v[160:161], v139 offset0:228 offset1:244
	ds_read2_b32 v[16:17], v140 offset0:104 offset1:120
	ds_read2_b32 v[162:163], v140 offset0:236 offset1:252
	ds_read2_b32 v[10:11], v141 offset0:128 offset1:144
	ds_read2_b32 v[164:165], v142 offset0:4 offset1:20
	ds_read2_b32 v[12:13], v142 offset0:136 offset1:152
	ds_read2_b32 v[166:167], v143 offset0:12 offset1:28
	ds_read2_b32 v[6:7], v141 offset0:160 offset1:176
	ds_read2_b32 v[168:169], v142 offset0:36 offset1:52
	ds_read2_b32 v[8:9], v142 offset0:168 offset1:184
	ds_read2_b32 v[170:171], v143 offset0:44 offset1:60
	ds_read2_b32 v[2:3], v144 offset0:192 offset1:208
	ds_read2_b32 v[172:173], v145 offset0:68 offset1:84
	ds_read2_b32 v[4:5], v145 offset0:200 offset1:216
	ds_read2_b32 v[174:175], v146 offset0:76 offset1:92
	ds_read2_b32 v[30:31], v144 offset0:224 offset1:240
	ds_read2_b32 v[176:177], v145 offset0:100 offset1:116
	ds_read2_b32 v[32:33], v145 offset0:232 offset1:248
	ds_read2_b32 v[178:179], v146 offset0:108 offset1:124
	s_waitcnt lgkmcnt(0)
	s_barrier
	v_mov_b32_e32 v94, v31
	v_mov_b32_e32 v95, v177
	v_mov_b32_e32 v96, v33
	v_mov_b32_e32 v97, v179
	v_mov_b32_e32 v31, v176
	v_mov_b32_e32 v33, v178
	v_mov_b32_e32 v66, v3
	v_mov_b32_e32 v67, v173
	v_mov_b32_e32 v68, v5
	v_mov_b32_e32 v69, v175
	v_mov_b32_e32 v3, v172
	v_mov_b32_e32 v5, v174
	v_mov_b32_e32 v70, v7
	v_mov_b32_e32 v71, v169
	v_mov_b32_e32 v72, v9
	v_mov_b32_e32 v73, v171
	v_mov_b32_e32 v7, v168
	v_mov_b32_e32 v9, v170
	v_mov_b32_e32 v74, v11
	v_mov_b32_e32 v75, v165
	v_mov_b32_e32 v76, v13
	v_mov_b32_e32 v77, v167
	v_mov_b32_e32 v11, v164
	v_mov_b32_e32 v13, v166
	v_mov_b32_e32 v78, v15
	v_mov_b32_e32 v79, v161
	v_mov_b32_e32 v80, v17
	v_mov_b32_e32 v81, v163
	v_mov_b32_e32 v15, v160
	v_mov_b32_e32 v17, v162
	v_mov_b32_e32 v82, v19
	v_mov_b32_e32 v83, v157
	v_mov_b32_e32 v84, v21
	v_mov_b32_e32 v85, v159
	v_mov_b32_e32 v19, v156
	v_mov_b32_e32 v21, v158
	v_mov_b32_e32 v86, v23
	v_mov_b32_e32 v87, v153
	v_mov_b32_e32 v88, v25
	v_mov_b32_e32 v89, v155
	v_mov_b32_e32 v23, v152
	v_mov_b32_e32 v25, v154
	v_mov_b32_e32 v90, v27
	v_mov_b32_e32 v91, v149
	v_mov_b32_e32 v92, v29
	v_mov_b32_e32 v93, v151
	v_mov_b32_e32 v27, v148
	v_mov_b32_e32 v29, v150
	s_waitcnt lgkmcnt(0)
	s_barrier
	v_and_b32_e32 v174, 15, v0
	v_bfe_u32 v175, v0, 4, 2
	v_and_b32_e32 v111, 7, v174
	v_xor_b32_e32 v175, v175, v111
	v_lshlrev_b32_e32 v175, 4, v175
	v_lshl_or_b32 v175, v174, 7, v175
	v_bfe_u32 v174, v0, 7, 1
	v_lshl_or_b32 v100, v174, 13, v175
	v_bfe_u32 v174, v0, 6, 1
	v_lshl_or_b32 v168, v174, 13, v175
	v_or_b32_e32 v168, 0x4000, v168
	v_xor_b32_e32 v111, 64, v100
	v_xor_b32_e32 v169, 64, v168
	v_bfe_u32 v174, v0, 3, 3
	v_and_b32_e32 v175, 7, v0
	v_xor_b32_e32 v175, v175, v174
	v_lshlrev_b32_e32 v175, 4, v175
	v_lshl_or_b32 v175, v174, 11, v175
	v_lshrrev_b32_e32 v174, 6, v0
	v_and_b32_e32 v174, 3, v174
	v_lshl_or_b32 v170, v174, 16, v175
	v_add_u32_e32 v171, 0x3c00, v170
	v_add_u32_e32 v172, 0x7800, v170
	v_add_u32_e32 v173, 0xb400, v170
	v_lshlrev_b32_e32 v174, 12, v174
	s_nop 0
	v_readfirstlane_b32 s36, v174
	s_add_u32 s36, s36, 32
	v_mov_b32_e32 v116, 0
	v_mov_b32_e32 v117, 0
	v_mov_b32_e32 v118, 0
	v_mov_b32_e32 v119, 0
	v_mov_b32_e32 v120, 0
	v_mov_b32_e32 v121, 0
	v_mov_b32_e32 v122, 0
	v_mov_b32_e32 v123, 0
	v_mov_b32_e32 v124, 0
	v_mov_b32_e32 v125, 0
	v_mov_b32_e32 v126, 0
	v_mov_b32_e32 v127, 0
	v_mov_b32_e32 v148, 0
	v_mov_b32_e32 v149, 0
	v_mov_b32_e32 v150, 0
	v_mov_b32_e32 v151, 0
	v_mov_b32_e32 v152, 0
	v_mov_b32_e32 v153, 0
	v_mov_b32_e32 v154, 0
	v_mov_b32_e32 v155, 0
	v_mov_b32_e32 v156, 0
	v_mov_b32_e32 v157, 0
	v_mov_b32_e32 v158, 0
	v_mov_b32_e32 v159, 0
	v_mov_b32_e32 v160, 0
	v_mov_b32_e32 v161, 0
	v_mov_b32_e32 v162, 0
	v_mov_b32_e32 v163, 0
	v_mov_b32_e32 v164, 0
	v_mov_b32_e32 v165, 0
	v_mov_b32_e32 v166, 0
	v_mov_b32_e32 v167, 0
	s_waitcnt lgkmcnt(0)
	s_barrier
	v_readlane_b32 s98, v255, 16
	s_lshr_b32 s98, s98, 3
	s_and_b32 s98, s98, 3
	s_lshl_b32 s98, s98, 2
	s_lshl_b32 s99, s98, 7
	s_add_u32 s6, s6, s99
	s_addc_u32 s7, s7, 0
	s_add_u32 s8, s8, s99
	s_addc_u32 s9, s9, 0
	s_add_u32 m0, s36, 0
	s_nop 0
	global_load_lds_dwordx4 v170, s[6:7] offset:0
	global_load_lds_dwordx4 v171, s[6:7] offset:1024
	global_load_lds_dwordx4 v172, s[6:7] offset:2048
	global_load_lds_dwordx4 v173, s[6:7] offset:3072
	s_add_u32 m0, s36, 16384
	s_nop 0
	global_load_lds_dwordx4 v170, s[8:9] offset:0
	global_load_lds_dwordx4 v171, s[8:9] offset:1024
	global_load_lds_dwordx4 v172, s[8:9] offset:2048
	global_load_lds_dwordx4 v173, s[8:9] offset:3072
	s_add_u32 s99, s98, 1
	s_and_b32 s99, s99, 15
	s_sub_i32 s98, s99, s98
	s_lshl_b32 s98, s98, 7
	s_ashr_i32 s100, s98, 31
	s_add_u32 s6, s6, s98
	s_addc_u32 s7, s7, s100
	s_add_u32 s8, s8, s98
	s_addc_u32 s9, s9, s100
	s_mov_b32 s98, s99
	s_mov_b32 s5, 0
	s_waitcnt vmcnt(0)
.Lk_aol1b_loop:
	s_barrier
	s_add_u32 m0, s36, 32768
	v_mfma_f32_16x16x32_bf16 v[26:29], v[116:119], v[152:155], v[26:29]
	ds_read_b128 v[34:37], v100 offset:32
	global_load_lds_dwordx4 v170, s[6:7] offset:0
	v_mfma_f32_16x16x32_bf16 v[90:93], v[116:119], v[156:159], v[90:93]
	ds_read_b128 v[50:53], v168 offset:32
	global_load_lds_dwordx4 v171, s[6:7] offset:1024
	v_mfma_f32_16x16x32_bf16 v[22:25], v[116:119], v[160:163], v[22:25]
	ds_read_b128 v[54:57], v168 offset:2080
	global_load_lds_dwordx4 v172, s[6:7] offset:2048
	v_mfma_f32_16x16x32_bf16 v[86:89], v[116:119], v[164:167], v[86:89]
	ds_read_b128 v[38:41], v100 offset:2080
	global_load_lds_dwordx4 v173, s[6:7] offset:3072
	s_add_u32 m0, s36, 49152
	v_mfma_f32_16x16x32_bf16 v[18:21], v[120:123], v[152:155], v[18:21]
	ds_read_b128 v[58:61], v168 offset:4128
	global_load_lds_dwordx4 v170, s[8:9] offset:0
	v_mfma_f32_16x16x32_bf16 v[82:85], v[120:123], v[156:159], v[82:85]
	ds_read_b128 v[62:65], v168 offset:6176
	global_load_lds_dwordx4 v171, s[8:9] offset:1024
	v_mfma_f32_16x16x32_bf16 v[14:17], v[120:123], v[160:163], v[14:17]
	ds_read_b128 v[42:45], v100 offset:4128
	global_load_lds_dwordx4 v172, s[8:9] offset:2048
	v_mfma_f32_16x16x32_bf16 v[78:81], v[120:123], v[164:167], v[78:81]
	ds_read_b128 v[46:49], v100 offset:6176
	global_load_lds_dwordx4 v173, s[8:9] offset:3072
	v_mfma_f32_16x16x32_bf16 v[10:13], v[124:127], v[152:155], v[10:13]
	v_mfma_f32_16x16x32_bf16 v[74:77], v[124:127], v[156:159], v[74:77]
	v_mfma_f32_16x16x32_bf16 v[6:9], v[124:127], v[160:163], v[6:9]
	v_mfma_f32_16x16x32_bf16 v[70:73], v[124:127], v[164:167], v[70:73]
	v_mfma_f32_16x16x32_bf16 v[2:5], v[148:151], v[152:155], v[2:5]
	v_mfma_f32_16x16x32_bf16 v[66:69], v[148:151], v[156:159], v[66:69]
	v_mfma_f32_16x16x32_bf16 v[30:33], v[148:151], v[160:163], v[30:33]
	v_mfma_f32_16x16x32_bf16 v[94:97], v[148:151], v[164:167], v[94:97]
	s_add_u32 s99, s98, 1
	s_and_b32 s99, s99, 15
	s_sub_i32 s98, s99, s98
	s_lshl_b32 s98, s98, 7
	s_ashr_i32 s100, s98, 31
	s_add_u32 s6, s6, s98
	s_addc_u32 s7, s7, s100
	s_add_u32 s8, s8, s98
	s_addc_u32 s9, s9, s100
	s_mov_b32 s98, s99
	s_waitcnt lgkmcnt(0)
	v_mfma_f32_16x16x32_bf16 v[26:29], v[34:37], v[50:53], v[26:29]
	ds_read_b128 v[116:119], v111 offset:32
	v_mfma_f32_16x16x32_bf16 v[90:93], v[34:37], v[54:57], v[90:93]
	ds_read_b128 v[152:155], v169 offset:32
	v_mfma_f32_16x16x32_bf16 v[22:25], v[34:37], v[58:61], v[22:25]
	ds_read_b128 v[156:159], v169 offset:2080
	v_mfma_f32_16x16x32_bf16 v[86:89], v[34:37], v[62:65], v[86:89]
	ds_read_b128 v[120:123], v111 offset:2080
	v_mfma_f32_16x16x32_bf16 v[18:21], v[38:41], v[50:53], v[18:21]
	ds_read_b128 v[160:163], v169 offset:4128
	v_mfma_f32_16x16x32_bf16 v[82:85], v[38:41], v[54:57], v[82:85]
	ds_read_b128 v[164:167], v169 offset:6176
	v_mfma_f32_16x16x32_bf16 v[14:17], v[38:41], v[58:61], v[14:17]
	ds_read_b128 v[124:127], v111 offset:4128
	v_mfma_f32_16x16x32_bf16 v[78:81], v[38:41], v[62:65], v[78:81]
	ds_read_b128 v[148:151], v111 offset:6176
	v_mfma_f32_16x16x32_bf16 v[10:13], v[42:45], v[50:53], v[10:13]
	v_mfma_f32_16x16x32_bf16 v[74:77], v[42:45], v[54:57], v[74:77]
	v_mfma_f32_16x16x32_bf16 v[6:9], v[42:45], v[58:61], v[6:9]
	v_mfma_f32_16x16x32_bf16 v[70:73], v[42:45], v[62:65], v[70:73]
	v_mfma_f32_16x16x32_bf16 v[2:5], v[46:49], v[50:53], v[2:5]
	v_mfma_f32_16x16x32_bf16 v[66:69], v[46:49], v[54:57], v[66:69]
	v_mfma_f32_16x16x32_bf16 v[30:33], v[46:49], v[58:61], v[30:33]
	v_mfma_f32_16x16x32_bf16 v[94:97], v[46:49], v[62:65], v[94:97]
	s_waitcnt lgkmcnt(0)
	s_waitcnt vmcnt(0)
	s_barrier
	s_add_u32 m0, s36, 0
	v_mfma_f32_16x16x32_bf16 v[26:29], v[116:119], v[152:155], v[26:29]
	ds_read_b128 v[34:37], v100 offset:32800
	global_load_lds_dwordx4 v170, s[6:7] offset:0
	v_mfma_f32_16x16x32_bf16 v[90:93], v[116:119], v[156:159], v[90:93]
	ds_read_b128 v[50:53], v168 offset:32800
	global_load_lds_dwordx4 v171, s[6:7] offset:1024
	v_mfma_f32_16x16x32_bf16 v[22:25], v[116:119], v[160:163], v[22:25]
	ds_read_b128 v[54:57], v168 offset:34848
	global_load_lds_dwordx4 v172, s[6:7] offset:2048
	v_mfma_f32_16x16x32_bf16 v[86:89], v[116:119], v[164:167], v[86:89]
	ds_read_b128 v[38:41], v100 offset:34848
	global_load_lds_dwordx4 v173, s[6:7] offset:3072
	s_add_u32 m0, s36, 16384
	v_mfma_f32_16x16x32_bf16 v[18:21], v[120:123], v[152:155], v[18:21]
	ds_read_b128 v[58:61], v168 offset:36896
	global_load_lds_dwordx4 v170, s[8:9] offset:0
	v_mfma_f32_16x16x32_bf16 v[82:85], v[120:123], v[156:159], v[82:85]
	ds_read_b128 v[62:65], v168 offset:38944
	global_load_lds_dwordx4 v171, s[8:9] offset:1024
	v_mfma_f32_16x16x32_bf16 v[14:17], v[120:123], v[160:163], v[14:17]
	ds_read_b128 v[42:45], v100 offset:36896
	global_load_lds_dwordx4 v172, s[8:9] offset:2048
	v_mfma_f32_16x16x32_bf16 v[78:81], v[120:123], v[164:167], v[78:81]
	ds_read_b128 v[46:49], v100 offset:38944
	global_load_lds_dwordx4 v173, s[8:9] offset:3072
	v_mfma_f32_16x16x32_bf16 v[10:13], v[124:127], v[152:155], v[10:13]
	v_mfma_f32_16x16x32_bf16 v[74:77], v[124:127], v[156:159], v[74:77]
	v_mfma_f32_16x16x32_bf16 v[6:9], v[124:127], v[160:163], v[6:9]
	v_mfma_f32_16x16x32_bf16 v[70:73], v[124:127], v[164:167], v[70:73]
	v_mfma_f32_16x16x32_bf16 v[2:5], v[148:151], v[152:155], v[2:5]
	v_mfma_f32_16x16x32_bf16 v[66:69], v[148:151], v[156:159], v[66:69]
	v_mfma_f32_16x16x32_bf16 v[30:33], v[148:151], v[160:163], v[30:33]
	v_mfma_f32_16x16x32_bf16 v[94:97], v[148:151], v[164:167], v[94:97]
	s_add_u32 s99, s98, 1
	s_and_b32 s99, s99, 15
	s_sub_i32 s98, s99, s98
	s_lshl_b32 s98, s98, 7
	s_ashr_i32 s100, s98, 31
	s_add_u32 s6, s6, s98
	s_addc_u32 s7, s7, s100
	s_add_u32 s8, s8, s98
	s_addc_u32 s9, s9, s100
	s_mov_b32 s98, s99
	s_waitcnt lgkmcnt(0)
	v_mfma_f32_16x16x32_bf16 v[26:29], v[34:37], v[50:53], v[26:29]
	ds_read_b128 v[116:119], v111 offset:32800
	v_mfma_f32_16x16x32_bf16 v[90:93], v[34:37], v[54:57], v[90:93]
	ds_read_b128 v[152:155], v169 offset:32800
	v_mfma_f32_16x16x32_bf16 v[22:25], v[34:37], v[58:61], v[22:25]
	ds_read_b128 v[156:159], v169 offset:34848
	v_mfma_f32_16x16x32_bf16 v[86:89], v[34:37], v[62:65], v[86:89]
	ds_read_b128 v[120:123], v111 offset:34848
	v_mfma_f32_16x16x32_bf16 v[18:21], v[38:41], v[50:53], v[18:21]
	ds_read_b128 v[160:163], v169 offset:36896
	v_mfma_f32_16x16x32_bf16 v[82:85], v[38:41], v[54:57], v[82:85]
	ds_read_b128 v[164:167], v169 offset:38944
	v_mfma_f32_16x16x32_bf16 v[14:17], v[38:41], v[58:61], v[14:17]
	ds_read_b128 v[124:127], v111 offset:36896
	v_mfma_f32_16x16x32_bf16 v[78:81], v[38:41], v[62:65], v[78:81]
	ds_read_b128 v[148:151], v111 offset:38944
	v_mfma_f32_16x16x32_bf16 v[10:13], v[42:45], v[50:53], v[10:13]
	v_mfma_f32_16x16x32_bf16 v[74:77], v[42:45], v[54:57], v[74:77]
	v_mfma_f32_16x16x32_bf16 v[6:9], v[42:45], v[58:61], v[6:9]
	v_mfma_f32_16x16x32_bf16 v[70:73], v[42:45], v[62:65], v[70:73]
	v_mfma_f32_16x16x32_bf16 v[2:5], v[46:49], v[50:53], v[2:5]
	v_mfma_f32_16x16x32_bf16 v[66:69], v[46:49], v[54:57], v[66:69]
	v_mfma_f32_16x16x32_bf16 v[30:33], v[46:49], v[58:61], v[30:33]
	v_mfma_f32_16x16x32_bf16 v[94:97], v[46:49], v[62:65], v[94:97]
	s_waitcnt lgkmcnt(0)
	s_waitcnt vmcnt(0)
	s_add_u32 s5, s5, 1
	s_cmp_lt_u32 s5, 7
	s_cbranch_scc1 .Lk_aol1b_loop
	s_barrier
	s_add_u32 m0, s36, 32768
	v_mfma_f32_16x16x32_bf16 v[26:29], v[116:119], v[152:155], v[26:29]
	ds_read_b128 v[34:37], v100 offset:32
	global_load_lds_dwordx4 v170, s[6:7] offset:0
	v_mfma_f32_16x16x32_bf16 v[90:93], v[116:119], v[156:159], v[90:93]
	ds_read_b128 v[50:53], v168 offset:32
	global_load_lds_dwordx4 v171, s[6:7] offset:1024
	v_mfma_f32_16x16x32_bf16 v[22:25], v[116:119], v[160:163], v[22:25]
	ds_read_b128 v[54:57], v168 offset:2080
	global_load_lds_dwordx4 v172, s[6:7] offset:2048
	v_mfma_f32_16x16x32_bf16 v[86:89], v[116:119], v[164:167], v[86:89]
	ds_read_b128 v[38:41], v100 offset:2080
	global_load_lds_dwordx4 v173, s[6:7] offset:3072
	s_add_u32 m0, s36, 49152
	v_mfma_f32_16x16x32_bf16 v[18:21], v[120:123], v[152:155], v[18:21]
	ds_read_b128 v[58:61], v168 offset:4128
	global_load_lds_dwordx4 v170, s[8:9] offset:0
	v_mfma_f32_16x16x32_bf16 v[82:85], v[120:123], v[156:159], v[82:85]
	ds_read_b128 v[62:65], v168 offset:6176
	global_load_lds_dwordx4 v171, s[8:9] offset:1024
	v_mfma_f32_16x16x32_bf16 v[14:17], v[120:123], v[160:163], v[14:17]
	ds_read_b128 v[42:45], v100 offset:4128
	global_load_lds_dwordx4 v172, s[8:9] offset:2048
	v_mfma_f32_16x16x32_bf16 v[78:81], v[120:123], v[164:167], v[78:81]
	ds_read_b128 v[46:49], v100 offset:6176
	global_load_lds_dwordx4 v173, s[8:9] offset:3072
	v_mfma_f32_16x16x32_bf16 v[10:13], v[124:127], v[152:155], v[10:13]
	v_mfma_f32_16x16x32_bf16 v[74:77], v[124:127], v[156:159], v[74:77]
	v_mfma_f32_16x16x32_bf16 v[6:9], v[124:127], v[160:163], v[6:9]
	v_mfma_f32_16x16x32_bf16 v[70:73], v[124:127], v[164:167], v[70:73]
	v_mfma_f32_16x16x32_bf16 v[2:5], v[148:151], v[152:155], v[2:5]
	v_mfma_f32_16x16x32_bf16 v[66:69], v[148:151], v[156:159], v[66:69]
	v_mfma_f32_16x16x32_bf16 v[30:33], v[148:151], v[160:163], v[30:33]
	v_mfma_f32_16x16x32_bf16 v[94:97], v[148:151], v[164:167], v[94:97]
	s_add_u32 s99, s98, 1
	s_and_b32 s99, s99, 15
	s_sub_i32 s98, s99, s98
	s_lshl_b32 s98, s98, 7
	s_ashr_i32 s100, s98, 31
	s_add_u32 s6, s6, s98
	s_addc_u32 s7, s7, s100
	s_add_u32 s8, s8, s98
	s_addc_u32 s9, s9, s100
	s_mov_b32 s98, s99
	s_waitcnt lgkmcnt(0)
	v_mfma_f32_16x16x32_bf16 v[26:29], v[34:37], v[50:53], v[26:29]
	ds_read_b128 v[116:119], v111 offset:32
	v_mfma_f32_16x16x32_bf16 v[90:93], v[34:37], v[54:57], v[90:93]
	ds_read_b128 v[152:155], v169 offset:32
	v_mfma_f32_16x16x32_bf16 v[22:25], v[34:37], v[58:61], v[22:25]
	ds_read_b128 v[156:159], v169 offset:2080
	v_mfma_f32_16x16x32_bf16 v[86:89], v[34:37], v[62:65], v[86:89]
	ds_read_b128 v[120:123], v111 offset:2080
	v_mfma_f32_16x16x32_bf16 v[18:21], v[38:41], v[50:53], v[18:21]
	ds_read_b128 v[160:163], v169 offset:4128
	v_mfma_f32_16x16x32_bf16 v[82:85], v[38:41], v[54:57], v[82:85]
	ds_read_b128 v[164:167], v169 offset:6176
	v_mfma_f32_16x16x32_bf16 v[14:17], v[38:41], v[58:61], v[14:17]
	ds_read_b128 v[124:127], v111 offset:4128
	v_mfma_f32_16x16x32_bf16 v[78:81], v[38:41], v[62:65], v[78:81]
	ds_read_b128 v[148:151], v111 offset:6176
	v_mfma_f32_16x16x32_bf16 v[10:13], v[42:45], v[50:53], v[10:13]
	v_mfma_f32_16x16x32_bf16 v[74:77], v[42:45], v[54:57], v[74:77]
	v_mfma_f32_16x16x32_bf16 v[6:9], v[42:45], v[58:61], v[6:9]
	v_mfma_f32_16x16x32_bf16 v[70:73], v[42:45], v[62:65], v[70:73]
	v_mfma_f32_16x16x32_bf16 v[2:5], v[46:49], v[50:53], v[2:5]
	v_mfma_f32_16x16x32_bf16 v[66:69], v[46:49], v[54:57], v[66:69]
	v_mfma_f32_16x16x32_bf16 v[30:33], v[46:49], v[58:61], v[30:33]
	v_mfma_f32_16x16x32_bf16 v[94:97], v[46:49], v[62:65], v[94:97]
	s_waitcnt lgkmcnt(0)
	s_waitcnt vmcnt(0)
	s_barrier
	v_mfma_f32_16x16x32_bf16 v[26:29], v[116:119], v[152:155], v[26:29]
	ds_read_b128 v[34:37], v100 offset:32800
	v_mfma_f32_16x16x32_bf16 v[90:93], v[116:119], v[156:159], v[90:93]
	ds_read_b128 v[50:53], v168 offset:32800
	v_mfma_f32_16x16x32_bf16 v[22:25], v[116:119], v[160:163], v[22:25]
	ds_read_b128 v[54:57], v168 offset:34848
	v_mfma_f32_16x16x32_bf16 v[86:89], v[116:119], v[164:167], v[86:89]
	ds_read_b128 v[38:41], v100 offset:34848
	v_mfma_f32_16x16x32_bf16 v[18:21], v[120:123], v[152:155], v[18:21]
	ds_read_b128 v[58:61], v168 offset:36896
	v_mfma_f32_16x16x32_bf16 v[82:85], v[120:123], v[156:159], v[82:85]
	ds_read_b128 v[62:65], v168 offset:38944
	v_mfma_f32_16x16x32_bf16 v[14:17], v[120:123], v[160:163], v[14:17]
	ds_read_b128 v[42:45], v100 offset:36896
	v_mfma_f32_16x16x32_bf16 v[78:81], v[120:123], v[164:167], v[78:81]
	ds_read_b128 v[46:49], v100 offset:38944
	v_mfma_f32_16x16x32_bf16 v[10:13], v[124:127], v[152:155], v[10:13]
	v_mfma_f32_16x16x32_bf16 v[74:77], v[124:127], v[156:159], v[74:77]
	v_mfma_f32_16x16x32_bf16 v[6:9], v[124:127], v[160:163], v[6:9]
	v_mfma_f32_16x16x32_bf16 v[70:73], v[124:127], v[164:167], v[70:73]
	v_mfma_f32_16x16x32_bf16 v[2:5], v[148:151], v[152:155], v[2:5]
	v_mfma_f32_16x16x32_bf16 v[66:69], v[148:151], v[156:159], v[66:69]
	v_mfma_f32_16x16x32_bf16 v[30:33], v[148:151], v[160:163], v[30:33]
	v_mfma_f32_16x16x32_bf16 v[94:97], v[148:151], v[164:167], v[94:97]
	s_waitcnt lgkmcnt(0)
	v_mfma_f32_16x16x32_bf16 v[26:29], v[34:37], v[50:53], v[26:29]
	ds_read_b128 v[116:119], v111 offset:32800
	v_mfma_f32_16x16x32_bf16 v[90:93], v[34:37], v[54:57], v[90:93]
	ds_read_b128 v[152:155], v169 offset:32800
	v_mfma_f32_16x16x32_bf16 v[22:25], v[34:37], v[58:61], v[22:25]
	ds_read_b128 v[156:159], v169 offset:34848
	v_mfma_f32_16x16x32_bf16 v[86:89], v[34:37], v[62:65], v[86:89]
	ds_read_b128 v[120:123], v111 offset:34848
	v_mfma_f32_16x16x32_bf16 v[18:21], v[38:41], v[50:53], v[18:21]
	ds_read_b128 v[160:163], v169 offset:36896
	v_mfma_f32_16x16x32_bf16 v[82:85], v[38:41], v[54:57], v[82:85]
	ds_read_b128 v[164:167], v169 offset:38944
	v_mfma_f32_16x16x32_bf16 v[14:17], v[38:41], v[58:61], v[14:17]
	ds_read_b128 v[124:127], v111 offset:36896
	v_mfma_f32_16x16x32_bf16 v[78:81], v[38:41], v[62:65], v[78:81]
	ds_read_b128 v[148:151], v111 offset:38944
	v_mfma_f32_16x16x32_bf16 v[10:13], v[42:45], v[50:53], v[10:13]
	v_mfma_f32_16x16x32_bf16 v[74:77], v[42:45], v[54:57], v[74:77]
	v_mfma_f32_16x16x32_bf16 v[6:9], v[42:45], v[58:61], v[6:9]
	v_mfma_f32_16x16x32_bf16 v[70:73], v[42:45], v[62:65], v[70:73]
	v_mfma_f32_16x16x32_bf16 v[2:5], v[46:49], v[50:53], v[2:5]
	v_mfma_f32_16x16x32_bf16 v[66:69], v[46:49], v[54:57], v[66:69]
	v_mfma_f32_16x16x32_bf16 v[30:33], v[46:49], v[58:61], v[30:33]
	v_mfma_f32_16x16x32_bf16 v[94:97], v[46:49], v[62:65], v[94:97]
	s_waitcnt lgkmcnt(0)
	v_mfma_f32_16x16x32_bf16 v[26:29], v[116:119], v[152:155], v[26:29]
	v_mfma_f32_16x16x32_bf16 v[90:93], v[116:119], v[156:159], v[90:93]
	v_mfma_f32_16x16x32_bf16 v[22:25], v[116:119], v[160:163], v[22:25]
	v_mfma_f32_16x16x32_bf16 v[86:89], v[116:119], v[164:167], v[86:89]
	v_mfma_f32_16x16x32_bf16 v[18:21], v[120:123], v[152:155], v[18:21]
	v_mfma_f32_16x16x32_bf16 v[82:85], v[120:123], v[156:159], v[82:85]
	v_mfma_f32_16x16x32_bf16 v[14:17], v[120:123], v[160:163], v[14:17]
	v_mfma_f32_16x16x32_bf16 v[78:81], v[120:123], v[164:167], v[78:81]
	v_mfma_f32_16x16x32_bf16 v[10:13], v[124:127], v[152:155], v[10:13]
	v_mfma_f32_16x16x32_bf16 v[74:77], v[124:127], v[156:159], v[74:77]
	v_mfma_f32_16x16x32_bf16 v[6:9], v[124:127], v[160:163], v[6:9]
	v_mfma_f32_16x16x32_bf16 v[70:73], v[124:127], v[164:167], v[70:73]
	v_mfma_f32_16x16x32_bf16 v[2:5], v[148:151], v[152:155], v[2:5]
	v_mfma_f32_16x16x32_bf16 v[66:69], v[148:151], v[156:159], v[66:69]
	v_mfma_f32_16x16x32_bf16 v[30:33], v[148:151], v[160:163], v[30:33]
	v_mfma_f32_16x16x32_bf16 v[94:97], v[148:151], v[164:167], v[94:97]
	s_lshl_b32 s36, s4, 1
	s_lshl_b32 s4, s70, 10
	s_mul_hi_u32 s5, s70, 0x15555556
	s_barrier
	ds_write2_b32 v129, v26, v90 offset1:16
	ds_write2_b32 v129, v27, v91 offset0:132 offset1:148
	ds_write2_b32 v138, v28, v92 offset0:8 offset1:24
	ds_write2_b32 v138, v29, v93 offset0:140 offset1:156
	ds_write2_b32 v129, v22, v86 offset0:32 offset1:48
	ds_write2_b32 v129, v23, v87 offset0:164 offset1:180
	ds_write2_b32 v138, v24, v88 offset0:40 offset1:56
	ds_write2_b32 v138, v25, v89 offset0:172 offset1:188
	ds_write2_b32 v139, v18, v82 offset0:64 offset1:80
	ds_write2_b32 v139, v19, v83 offset0:196 offset1:212
	ds_write2_b32 v140, v20, v84 offset0:72 offset1:88
	ds_write2_b32 v140, v21, v85 offset0:204 offset1:220
	ds_write2_b32 v139, v14, v78 offset0:96 offset1:112
	ds_write2_b32 v139, v15, v79 offset0:228 offset1:244
	ds_write2_b32 v140, v16, v80 offset0:104 offset1:120
	ds_write2_b32 v140, v17, v81 offset0:236 offset1:252
	ds_write2_b32 v141, v10, v74 offset0:128 offset1:144
	ds_write2_b32 v142, v11, v75 offset0:4 offset1:20
	ds_write2_b32 v142, v12, v76 offset0:136 offset1:152
	ds_write2_b32 v143, v13, v77 offset0:12 offset1:28
	ds_write2_b32 v141, v6, v70 offset0:160 offset1:176
	ds_write2_b32 v142, v7, v71 offset0:36 offset1:52
	ds_write2_b32 v142, v8, v72 offset0:168 offset1:184
	ds_write2_b32 v143, v9, v73 offset0:44 offset1:60
	ds_write2_b32 v144, v2, v66 offset0:192 offset1:208
	ds_write2_b32 v145, v3, v67 offset0:68 offset1:84
	ds_write2_b32 v145, v4, v68 offset0:200 offset1:216
	ds_write2_b32 v146, v5, v69 offset0:76 offset1:92
	ds_write2_b32 v144, v30, v94 offset0:224 offset1:240
	ds_write2_b32 v145, v31, v95 offset0:100 offset1:116
	ds_write2_b32 v145, v32, v96 offset0:232 offset1:248
	ds_write2_b32 v146, v33, v97 offset0:108 offset1:124
	v_or_b32_e32 v4, s4, v134
	s_mulk_i32 s5, 0x3000
	v_or_b32_e32 v5, s4, v132
	v_lshl_add_u64 v[2:3], v[106:107], 0, s[36:37]
	v_subrev_u32_e32 v4, s5, v4
	v_subrev_u32_e32 v100, s5, v5
	s_mov_b32 s4, 0
	s_waitcnt lgkmcnt(0)
	s_barrier

.LBB0_1372:
	s_and_b32 s28, s11, 0xff
	s_mul_i32 s2, s28, 0xab
	s_lshr_b32 s29, s2, 11
	s_mul_i32 s2, s29, 12
	s_sub_i32 s2, s11, s2
	s_and_b32 s2, s2, 0xff
	s_lshl_b32 s2, s2, 21
	s_or_b32 s2, s2, s21
	s_add_u32 s14, s16, s2
	s_addc_u32 s15, s17, 0
	s_lshl_b32 s2, s29, 18
	s_add_u32 s12, s18, s2
	s_addc_u32 s13, s19, 0
	v_and_b32_e32 v162, 15, v0
	v_bfe_u32 v163, v0, 4, 2
	v_and_b32_e32 v107, 7, v162
	v_xor_b32_e32 v163, v163, v107
	v_lshlrev_b32_e32 v163, 4, v163
	v_lshl_or_b32 v163, v162, 7, v163
	v_bfe_u32 v162, v0, 7, 1
	v_lshl_or_b32 v98, v162, 13, v163
	v_bfe_u32 v162, v0, 6, 1
	v_lshl_or_b32 v156, v162, 13, v163
	v_or_b32_e32 v156, 0x4000, v156
	v_xor_b32_e32 v107, 64, v98
	v_xor_b32_e32 v157, 64, v156
	v_bfe_u32 v162, v0, 3, 3
	v_and_b32_e32 v163, 7, v0
	v_xor_b32_e32 v163, v163, v162
	v_lshlrev_b32_e32 v163, 4, v163
	v_lshl_or_b32 v163, v162, 11, v163
	v_lshrrev_b32_e32 v162, 6, v0
	v_and_b32_e32 v162, 3, v162
	v_lshl_or_b32 v158, v162, 16, v163
	v_add_u32_e32 v159, 0x3c00, v158
	v_add_u32_e32 v160, 0x7800, v158
	v_add_u32_e32 v161, 0xb400, v158
	v_lshlrev_b32_e32 v162, 12, v162
	s_nop 0
	v_readfirstlane_b32 s31, v162
	s_add_u32 s31, s31, 32
	v_mov_b32_e32 v94, 0
	v_mov_b32_e32 v95, 0
	v_mov_b32_e32 v96, 0
	v_mov_b32_e32 v97, 0
	v_mov_b32_e32 v90, 0
	v_mov_b32_e32 v91, 0
	v_mov_b32_e32 v92, 0
	v_mov_b32_e32 v93, 0
	v_mov_b32_e32 v82, 0
	v_mov_b32_e32 v83, 0
	v_mov_b32_e32 v84, 0
	v_mov_b32_e32 v85, 0
	v_mov_b32_e32 v78, 0
	v_mov_b32_e32 v79, 0
	v_mov_b32_e32 v80, 0
	v_mov_b32_e32 v81, 0
	v_mov_b32_e32 v74, 0
	v_mov_b32_e32 v75, 0
	v_mov_b32_e32 v76, 0
	v_mov_b32_e32 v77, 0
	v_mov_b32_e32 v70, 0
	v_mov_b32_e32 v71, 0
	v_mov_b32_e32 v72, 0
	v_mov_b32_e32 v73, 0
	v_mov_b32_e32 v66, 0
	v_mov_b32_e32 v67, 0
	v_mov_b32_e32 v68, 0
	v_mov_b32_e32 v69, 0
	v_mov_b32_e32 v62, 0
	v_mov_b32_e32 v63, 0
	v_mov_b32_e32 v64, 0
	v_mov_b32_e32 v65, 0
	v_mov_b32_e32 v58, 0
	v_mov_b32_e32 v59, 0
	v_mov_b32_e32 v60, 0
	v_mov_b32_e32 v61, 0
	v_mov_b32_e32 v42, 0
	v_mov_b32_e32 v43, 0
	v_mov_b32_e32 v44, 0
	v_mov_b32_e32 v45, 0
	v_mov_b32_e32 v22, 0
	v_mov_b32_e32 v23, 0
	v_mov_b32_e32 v24, 0
	v_mov_b32_e32 v25, 0
	v_mov_b32_e32 v14, 0
	v_mov_b32_e32 v15, 0
	v_mov_b32_e32 v16, 0
	v_mov_b32_e32 v17, 0
	v_mov_b32_e32 v10, 0
	v_mov_b32_e32 v11, 0
	v_mov_b32_e32 v12, 0
	v_mov_b32_e32 v13, 0
	v_mov_b32_e32 v6, 0
	v_mov_b32_e32 v7, 0
	v_mov_b32_e32 v8, 0
	v_mov_b32_e32 v9, 0
	v_mov_b32_e32 v2, 0
	v_mov_b32_e32 v3, 0
	v_mov_b32_e32 v4, 0
	v_mov_b32_e32 v5, 0
	v_mov_b32_e32 v86, 0
	v_mov_b32_e32 v87, 0
	v_mov_b32_e32 v88, 0
	v_mov_b32_e32 v89, 0
	v_mov_b32_e32 v108, 0
	v_mov_b32_e32 v109, 0
	v_mov_b32_e32 v110, 0
	v_mov_b32_e32 v111, 0
	v_mov_b32_e32 v112, 0
	v_mov_b32_e32 v113, 0
	v_mov_b32_e32 v114, 0
	v_mov_b32_e32 v115, 0
	v_mov_b32_e32 v116, 0
	v_mov_b32_e32 v117, 0
	v_mov_b32_e32 v118, 0
	v_mov_b32_e32 v119, 0
	v_mov_b32_e32 v136, 0
	v_mov_b32_e32 v137, 0
	v_mov_b32_e32 v138, 0
	v_mov_b32_e32 v139, 0
	v_mov_b32_e32 v140, 0
	v_mov_b32_e32 v141, 0
	v_mov_b32_e32 v142, 0
	v_mov_b32_e32 v143, 0
	v_mov_b32_e32 v144, 0
	v_mov_b32_e32 v145, 0
	v_mov_b32_e32 v146, 0
	v_mov_b32_e32 v147, 0
	v_mov_b32_e32 v148, 0
	v_mov_b32_e32 v149, 0
	v_mov_b32_e32 v150, 0
	v_mov_b32_e32 v151, 0
	v_mov_b32_e32 v152, 0
	v_mov_b32_e32 v153, 0
	v_mov_b32_e32 v154, 0
	v_mov_b32_e32 v155, 0
	s_waitcnt lgkmcnt(0)
	s_barrier
	v_readlane_b32 s98, v255, 16
	s_lshr_b32 s98, s98, 3
	s_and_b32 s98, s98, 3
	s_lshl_b32 s98, s98, 2
	s_lshl_b32 s99, s98, 7
	s_add_u32 s14, s14, s99
	s_addc_u32 s15, s15, 0
	s_add_u32 s12, s12, s99
	s_addc_u32 s13, s13, 0
	s_add_u32 m0, s31, 0
	s_nop 0
	global_load_lds_dwordx4 v158, s[14:15] offset:0
	global_load_lds_dwordx4 v159, s[14:15] offset:1024
	global_load_lds_dwordx4 v160, s[14:15] offset:2048
	global_load_lds_dwordx4 v161, s[14:15] offset:3072
	s_add_u32 m0, s31, 16384
	s_nop 0
	global_load_lds_dwordx4 v158, s[12:13] offset:0
	global_load_lds_dwordx4 v159, s[12:13] offset:1024
	global_load_lds_dwordx4 v160, s[12:13] offset:2048
	global_load_lds_dwordx4 v161, s[12:13] offset:3072
	s_add_u32 s99, s98, 1
	s_and_b32 s99, s99, 15
	s_sub_i32 s98, s99, s98
	s_lshl_b32 s98, s98, 7
	s_ashr_i32 s100, s98, 31
	s_add_u32 s14, s14, s98
	s_addc_u32 s15, s15, s100
	s_add_u32 s12, s12, s98
	s_addc_u32 s13, s13, s100
	s_mov_b32 s98, s99
	s_mov_b32 s30, 0
	s_waitcnt vmcnt(0)
.Lk_outl1_loop:
	s_barrier
	s_add_u32 m0, s31, 32768
	v_mfma_f32_16x16x32_bf16 v[94:97], v[108:111], v[140:143], v[94:97]
	ds_read_b128 v[18:21], v98 offset:32
	global_load_lds_dwordx4 v158, s[14:15] offset:0
	v_mfma_f32_16x16x32_bf16 v[90:93], v[108:111], v[144:147], v[90:93]
	ds_read_b128 v[38:41], v156 offset:32
	global_load_lds_dwordx4 v159, s[14:15] offset:1024
	v_mfma_f32_16x16x32_bf16 v[82:85], v[108:111], v[148:151], v[82:85]
	ds_read_b128 v[46:49], v156 offset:2080
	global_load_lds_dwordx4 v160, s[14:15] offset:2048
	v_mfma_f32_16x16x32_bf16 v[78:81], v[108:111], v[152:155], v[78:81]
	ds_read_b128 v[26:29], v98 offset:2080
	global_load_lds_dwordx4 v161, s[14:15] offset:3072
	s_add_u32 m0, s31, 49152
	v_mfma_f32_16x16x32_bf16 v[74:77], v[112:115], v[140:143], v[74:77]
	ds_read_b128 v[50:53], v156 offset:4128
	global_load_lds_dwordx4 v158, s[12:13] offset:0
	v_mfma_f32_16x16x32_bf16 v[70:73], v[112:115], v[144:147], v[70:73]
	ds_read_b128 v[54:57], v156 offset:6176
	global_load_lds_dwordx4 v159, s[12:13] offset:1024
	v_mfma_f32_16x16x32_bf16 v[66:69], v[112:115], v[148:151], v[66:69]
	ds_read_b128 v[30:33], v98 offset:4128
	global_load_lds_dwordx4 v160, s[12:13] offset:2048
	v_mfma_f32_16x16x32_bf16 v[62:65], v[112:115], v[152:155], v[62:65]
	ds_read_b128 v[34:37], v98 offset:6176
	global_load_lds_dwordx4 v161, s[12:13] offset:3072
	v_mfma_f32_16x16x32_bf16 v[58:61], v[116:119], v[140:143], v[58:61]
	v_mfma_f32_16x16x32_bf16 v[42:45], v[116:119], v[144:147], v[42:45]
	v_mfma_f32_16x16x32_bf16 v[22:25], v[116:119], v[148:151], v[22:25]
	v_mfma_f32_16x16x32_bf16 v[14:17], v[116:119], v[152:155], v[14:17]
	v_mfma_f32_16x16x32_bf16 v[10:13], v[136:139], v[140:143], v[10:13]
	v_mfma_f32_16x16x32_bf16 v[6:9], v[136:139], v[144:147], v[6:9]
	v_mfma_f32_16x16x32_bf16 v[2:5], v[136:139], v[148:151], v[2:5]
	v_mfma_f32_16x16x32_bf16 v[86:89], v[136:139], v[152:155], v[86:89]
	s_add_u32 s99, s98, 1
	s_and_b32 s99, s99, 15
	s_sub_i32 s98, s99, s98
	s_lshl_b32 s98, s98, 7
	s_ashr_i32 s100, s98, 31
	s_add_u32 s14, s14, s98
	s_addc_u32 s15, s15, s100
	s_add_u32 s12, s12, s98
	s_addc_u32 s13, s13, s100
	s_mov_b32 s98, s99
	s_waitcnt lgkmcnt(0)
	v_mfma_f32_16x16x32_bf16 v[94:97], v[18:21], v[38:41], v[94:97]
	ds_read_b128 v[108:111], v107 offset:32
	v_mfma_f32_16x16x32_bf16 v[90:93], v[18:21], v[46:49], v[90:93]
	ds_read_b128 v[140:143], v157 offset:32
	v_mfma_f32_16x16x32_bf16 v[82:85], v[18:21], v[50:53], v[82:85]
	ds_read_b128 v[144:147], v157 offset:2080
	v_mfma_f32_16x16x32_bf16 v[78:81], v[18:21], v[54:57], v[78:81]
	ds_read_b128 v[112:115], v107 offset:2080
	v_mfma_f32_16x16x32_bf16 v[74:77], v[26:29], v[38:41], v[74:77]
	ds_read_b128 v[148:151], v157 offset:4128
	v_mfma_f32_16x16x32_bf16 v[70:73], v[26:29], v[46:49], v[70:73]
	ds_read_b128 v[152:155], v157 offset:6176
	v_mfma_f32_16x16x32_bf16 v[66:69], v[26:29], v[50:53], v[66:69]
	ds_read_b128 v[116:119], v107 offset:4128
	v_mfma_f32_16x16x32_bf16 v[62:65], v[26:29], v[54:57], v[62:65]
	ds_read_b128 v[136:139], v107 offset:6176
	v_mfma_f32_16x16x32_bf16 v[58:61], v[30:33], v[38:41], v[58:61]
	v_mfma_f32_16x16x32_bf16 v[42:45], v[30:33], v[46:49], v[42:45]
	v_mfma_f32_16x16x32_bf16 v[22:25], v[30:33], v[50:53], v[22:25]
	v_mfma_f32_16x16x32_bf16 v[14:17], v[30:33], v[54:57], v[14:17]
	v_mfma_f32_16x16x32_bf16 v[10:13], v[34:37], v[38:41], v[10:13]
	v_mfma_f32_16x16x32_bf16 v[6:9], v[34:37], v[46:49], v[6:9]
	v_mfma_f32_16x16x32_bf16 v[2:5], v[34:37], v[50:53], v[2:5]
	v_mfma_f32_16x16x32_bf16 v[86:89], v[34:37], v[54:57], v[86:89]
	s_waitcnt lgkmcnt(0)
	s_waitcnt vmcnt(0)
	s_barrier
	s_add_u32 m0, s31, 0
	v_mfma_f32_16x16x32_bf16 v[94:97], v[108:111], v[140:143], v[94:97]
	ds_read_b128 v[18:21], v98 offset:32800
	global_load_lds_dwordx4 v158, s[14:15] offset:0
	v_mfma_f32_16x16x32_bf16 v[90:93], v[108:111], v[144:147], v[90:93]
	ds_read_b128 v[38:41], v156 offset:32800
	global_load_lds_dwordx4 v159, s[14:15] offset:1024
	v_mfma_f32_16x16x32_bf16 v[82:85], v[108:111], v[148:151], v[82:85]
	ds_read_b128 v[46:49], v156 offset:34848
	global_load_lds_dwordx4 v160, s[14:15] offset:2048
	v_mfma_f32_16x16x32_bf16 v[78:81], v[108:111], v[152:155], v[78:81]
	ds_read_b128 v[26:29], v98 offset:34848
	global_load_lds_dwordx4 v161, s[14:15] offset:3072
	s_add_u32 m0, s31, 16384
	v_mfma_f32_16x16x32_bf16 v[74:77], v[112:115], v[140:143], v[74:77]
	ds_read_b128 v[50:53], v156 offset:36896
	global_load_lds_dwordx4 v158, s[12:13] offset:0
	v_mfma_f32_16x16x32_bf16 v[70:73], v[112:115], v[144:147], v[70:73]
	ds_read_b128 v[54:57], v156 offset:38944
	global_load_lds_dwordx4 v159, s[12:13] offset:1024
	v_mfma_f32_16x16x32_bf16 v[66:69], v[112:115], v[148:151], v[66:69]
	ds_read_b128 v[30:33], v98 offset:36896
	global_load_lds_dwordx4 v160, s[12:13] offset:2048
	v_mfma_f32_16x16x32_bf16 v[62:65], v[112:115], v[152:155], v[62:65]
	ds_read_b128 v[34:37], v98 offset:38944
	global_load_lds_dwordx4 v161, s[12:13] offset:3072
	v_mfma_f32_16x16x32_bf16 v[58:61], v[116:119], v[140:143], v[58:61]
	v_mfma_f32_16x16x32_bf16 v[42:45], v[116:119], v[144:147], v[42:45]
	v_mfma_f32_16x16x32_bf16 v[22:25], v[116:119], v[148:151], v[22:25]
	v_mfma_f32_16x16x32_bf16 v[14:17], v[116:119], v[152:155], v[14:17]
	v_mfma_f32_16x16x32_bf16 v[10:13], v[136:139], v[140:143], v[10:13]
	v_mfma_f32_16x16x32_bf16 v[6:9], v[136:139], v[144:147], v[6:9]
	v_mfma_f32_16x16x32_bf16 v[2:5], v[136:139], v[148:151], v[2:5]
	v_mfma_f32_16x16x32_bf16 v[86:89], v[136:139], v[152:155], v[86:89]
	s_add_u32 s99, s98, 1
	s_and_b32 s99, s99, 15
	s_sub_i32 s98, s99, s98
	s_lshl_b32 s98, s98, 7
	s_ashr_i32 s100, s98, 31
	s_add_u32 s14, s14, s98
	s_addc_u32 s15, s15, s100
	s_add_u32 s12, s12, s98
	s_addc_u32 s13, s13, s100
	s_mov_b32 s98, s99
	s_waitcnt lgkmcnt(0)
	v_mfma_f32_16x16x32_bf16 v[94:97], v[18:21], v[38:41], v[94:97]
	ds_read_b128 v[108:111], v107 offset:32800
	v_mfma_f32_16x16x32_bf16 v[90:93], v[18:21], v[46:49], v[90:93]
	ds_read_b128 v[140:143], v157 offset:32800
	v_mfma_f32_16x16x32_bf16 v[82:85], v[18:21], v[50:53], v[82:85]
	ds_read_b128 v[144:147], v157 offset:34848
	v_mfma_f32_16x16x32_bf16 v[78:81], v[18:21], v[54:57], v[78:81]
	ds_read_b128 v[112:115], v107 offset:34848
	v_mfma_f32_16x16x32_bf16 v[74:77], v[26:29], v[38:41], v[74:77]
	ds_read_b128 v[148:151], v157 offset:36896
	v_mfma_f32_16x16x32_bf16 v[70:73], v[26:29], v[46:49], v[70:73]
	ds_read_b128 v[152:155], v157 offset:38944
	v_mfma_f32_16x16x32_bf16 v[66:69], v[26:29], v[50:53], v[66:69]
	ds_read_b128 v[116:119], v107 offset:36896
	v_mfma_f32_16x16x32_bf16 v[62:65], v[26:29], v[54:57], v[62:65]
	ds_read_b128 v[136:139], v107 offset:38944
	v_mfma_f32_16x16x32_bf16 v[58:61], v[30:33], v[38:41], v[58:61]
	v_mfma_f32_16x16x32_bf16 v[42:45], v[30:33], v[46:49], v[42:45]
	v_mfma_f32_16x16x32_bf16 v[22:25], v[30:33], v[50:53], v[22:25]
	v_mfma_f32_16x16x32_bf16 v[14:17], v[30:33], v[54:57], v[14:17]
	v_mfma_f32_16x16x32_bf16 v[10:13], v[34:37], v[38:41], v[10:13]
	v_mfma_f32_16x16x32_bf16 v[6:9], v[34:37], v[46:49], v[6:9]
	v_mfma_f32_16x16x32_bf16 v[2:5], v[34:37], v[50:53], v[2:5]
	v_mfma_f32_16x16x32_bf16 v[86:89], v[34:37], v[54:57], v[86:89]
	s_waitcnt lgkmcnt(0)
	s_waitcnt vmcnt(0)
	s_add_u32 s30, s30, 1
	s_cmp_lt_u32 s30, 7
	s_cbranch_scc1 .Lk_outl1_loop
	s_barrier
	s_add_u32 m0, s31, 32768
	v_mfma_f32_16x16x32_bf16 v[94:97], v[108:111], v[140:143], v[94:97]
	ds_read_b128 v[18:21], v98 offset:32
	global_load_lds_dwordx4 v158, s[14:15] offset:0
	v_mfma_f32_16x16x32_bf16 v[90:93], v[108:111], v[144:147], v[90:93]
	ds_read_b128 v[38:41], v156 offset:32
	global_load_lds_dwordx4 v159, s[14:15] offset:1024
	v_mfma_f32_16x16x32_bf16 v[82:85], v[108:111], v[148:151], v[82:85]
	ds_read_b128 v[46:49], v156 offset:2080
	global_load_lds_dwordx4 v160, s[14:15] offset:2048
	v_mfma_f32_16x16x32_bf16 v[78:81], v[108:111], v[152:155], v[78:81]
	ds_read_b128 v[26:29], v98 offset:2080
	global_load_lds_dwordx4 v161, s[14:15] offset:3072
	s_add_u32 m0, s31, 49152
	v_mfma_f32_16x16x32_bf16 v[74:77], v[112:115], v[140:143], v[74:77]
	ds_read_b128 v[50:53], v156 offset:4128
	global_load_lds_dwordx4 v158, s[12:13] offset:0
	v_mfma_f32_16x16x32_bf16 v[70:73], v[112:115], v[144:147], v[70:73]
	ds_read_b128 v[54:57], v156 offset:6176
	global_load_lds_dwordx4 v159, s[12:13] offset:1024
	v_mfma_f32_16x16x32_bf16 v[66:69], v[112:115], v[148:151], v[66:69]
	ds_read_b128 v[30:33], v98 offset:4128
	global_load_lds_dwordx4 v160, s[12:13] offset:2048
	v_mfma_f32_16x16x32_bf16 v[62:65], v[112:115], v[152:155], v[62:65]
	ds_read_b128 v[34:37], v98 offset:6176
	global_load_lds_dwordx4 v161, s[12:13] offset:3072
	v_mfma_f32_16x16x32_bf16 v[58:61], v[116:119], v[140:143], v[58:61]
	v_mfma_f32_16x16x32_bf16 v[42:45], v[116:119], v[144:147], v[42:45]
	v_mfma_f32_16x16x32_bf16 v[22:25], v[116:119], v[148:151], v[22:25]
	v_mfma_f32_16x16x32_bf16 v[14:17], v[116:119], v[152:155], v[14:17]
	v_mfma_f32_16x16x32_bf16 v[10:13], v[136:139], v[140:143], v[10:13]
	v_mfma_f32_16x16x32_bf16 v[6:9], v[136:139], v[144:147], v[6:9]
	v_mfma_f32_16x16x32_bf16 v[2:5], v[136:139], v[148:151], v[2:5]
	v_mfma_f32_16x16x32_bf16 v[86:89], v[136:139], v[152:155], v[86:89]
	s_add_u32 s99, s98, 1
	s_and_b32 s99, s99, 15
	s_sub_i32 s98, s99, s98
	s_lshl_b32 s98, s98, 7
	s_ashr_i32 s100, s98, 31
	s_add_u32 s14, s14, s98
	s_addc_u32 s15, s15, s100
	s_add_u32 s12, s12, s98
	s_addc_u32 s13, s13, s100
	s_mov_b32 s98, s99
	s_waitcnt lgkmcnt(0)
	v_mfma_f32_16x16x32_bf16 v[94:97], v[18:21], v[38:41], v[94:97]
	ds_read_b128 v[108:111], v107 offset:32
	v_mfma_f32_16x16x32_bf16 v[90:93], v[18:21], v[46:49], v[90:93]
	ds_read_b128 v[140:143], v157 offset:32
	v_mfma_f32_16x16x32_bf16 v[82:85], v[18:21], v[50:53], v[82:85]
	ds_read_b128 v[144:147], v157 offset:2080
	v_mfma_f32_16x16x32_bf16 v[78:81], v[18:21], v[54:57], v[78:81]
	ds_read_b128 v[112:115], v107 offset:2080
	v_mfma_f32_16x16x32_bf16 v[74:77], v[26:29], v[38:41], v[74:77]
	ds_read_b128 v[148:151], v157 offset:4128
	v_mfma_f32_16x16x32_bf16 v[70:73], v[26:29], v[46:49], v[70:73]
	ds_read_b128 v[152:155], v157 offset:6176
	v_mfma_f32_16x16x32_bf16 v[66:69], v[26:29], v[50:53], v[66:69]
	ds_read_b128 v[116:119], v107 offset:4128
	v_mfma_f32_16x16x32_bf16 v[62:65], v[26:29], v[54:57], v[62:65]
	ds_read_b128 v[136:139], v107 offset:6176
	v_mfma_f32_16x16x32_bf16 v[58:61], v[30:33], v[38:41], v[58:61]
	v_mfma_f32_16x16x32_bf16 v[42:45], v[30:33], v[46:49], v[42:45]
	v_mfma_f32_16x16x32_bf16 v[22:25], v[30:33], v[50:53], v[22:25]
	v_mfma_f32_16x16x32_bf16 v[14:17], v[30:33], v[54:57], v[14:17]
	v_mfma_f32_16x16x32_bf16 v[10:13], v[34:37], v[38:41], v[10:13]
	v_mfma_f32_16x16x32_bf16 v[6:9], v[34:37], v[46:49], v[6:9]
	v_mfma_f32_16x16x32_bf16 v[2:5], v[34:37], v[50:53], v[2:5]
	v_mfma_f32_16x16x32_bf16 v[86:89], v[34:37], v[54:57], v[86:89]
	s_waitcnt lgkmcnt(0)
	s_waitcnt vmcnt(0)
	s_barrier
	v_mfma_f32_16x16x32_bf16 v[94:97], v[108:111], v[140:143], v[94:97]
	ds_read_b128 v[18:21], v98 offset:32800
	v_mfma_f32_16x16x32_bf16 v[90:93], v[108:111], v[144:147], v[90:93]
	ds_read_b128 v[38:41], v156 offset:32800
	v_mfma_f32_16x16x32_bf16 v[82:85], v[108:111], v[148:151], v[82:85]
	ds_read_b128 v[46:49], v156 offset:34848
	v_mfma_f32_16x16x32_bf16 v[78:81], v[108:111], v[152:155], v[78:81]
	ds_read_b128 v[26:29], v98 offset:34848
	v_mfma_f32_16x16x32_bf16 v[74:77], v[112:115], v[140:143], v[74:77]
	ds_read_b128 v[50:53], v156 offset:36896
	v_mfma_f32_16x16x32_bf16 v[70:73], v[112:115], v[144:147], v[70:73]
	ds_read_b128 v[54:57], v156 offset:38944
	v_mfma_f32_16x16x32_bf16 v[66:69], v[112:115], v[148:151], v[66:69]
	ds_read_b128 v[30:33], v98 offset:36896
	v_mfma_f32_16x16x32_bf16 v[62:65], v[112:115], v[152:155], v[62:65]
	ds_read_b128 v[34:37], v98 offset:38944
	v_mfma_f32_16x16x32_bf16 v[58:61], v[116:119], v[140:143], v[58:61]
	v_mfma_f32_16x16x32_bf16 v[42:45], v[116:119], v[144:147], v[42:45]
	v_mfma_f32_16x16x32_bf16 v[22:25], v[116:119], v[148:151], v[22:25]
	v_mfma_f32_16x16x32_bf16 v[14:17], v[116:119], v[152:155], v[14:17]
	v_mfma_f32_16x16x32_bf16 v[10:13], v[136:139], v[140:143], v[10:13]
	v_mfma_f32_16x16x32_bf16 v[6:9], v[136:139], v[144:147], v[6:9]
	v_mfma_f32_16x16x32_bf16 v[2:5], v[136:139], v[148:151], v[2:5]
	v_mfma_f32_16x16x32_bf16 v[86:89], v[136:139], v[152:155], v[86:89]
	s_waitcnt lgkmcnt(0)
	v_mfma_f32_16x16x32_bf16 v[94:97], v[18:21], v[38:41], v[94:97]
	ds_read_b128 v[108:111], v107 offset:32800
	v_mfma_f32_16x16x32_bf16 v[90:93], v[18:21], v[46:49], v[90:93]
	ds_read_b128 v[140:143], v157 offset:32800
	v_mfma_f32_16x16x32_bf16 v[82:85], v[18:21], v[50:53], v[82:85]
	ds_read_b128 v[144:147], v157 offset:34848
	v_mfma_f32_16x16x32_bf16 v[78:81], v[18:21], v[54:57], v[78:81]
	ds_read_b128 v[112:115], v107 offset:34848
	v_mfma_f32_16x16x32_bf16 v[74:77], v[26:29], v[38:41], v[74:77]
	ds_read_b128 v[148:151], v157 offset:36896
	v_mfma_f32_16x16x32_bf16 v[70:73], v[26:29], v[46:49], v[70:73]
	ds_read_b128 v[152:155], v157 offset:38944
	v_mfma_f32_16x16x32_bf16 v[66:69], v[26:29], v[50:53], v[66:69]
	ds_read_b128 v[116:119], v107 offset:36896
	v_mfma_f32_16x16x32_bf16 v[62:65], v[26:29], v[54:57], v[62:65]
	ds_read_b128 v[136:139], v107 offset:38944
	v_mfma_f32_16x16x32_bf16 v[58:61], v[30:33], v[38:41], v[58:61]
	v_mfma_f32_16x16x32_bf16 v[42:45], v[30:33], v[46:49], v[42:45]
	v_mfma_f32_16x16x32_bf16 v[22:25], v[30:33], v[50:53], v[22:25]
	v_mfma_f32_16x16x32_bf16 v[14:17], v[30:33], v[54:57], v[14:17]
	v_mfma_f32_16x16x32_bf16 v[10:13], v[34:37], v[38:41], v[10:13]
	v_mfma_f32_16x16x32_bf16 v[6:9], v[34:37], v[46:49], v[6:9]
	v_mfma_f32_16x16x32_bf16 v[2:5], v[34:37], v[50:53], v[2:5]
	v_mfma_f32_16x16x32_bf16 v[86:89], v[34:37], v[54:57], v[86:89]
	s_waitcnt lgkmcnt(0)
	v_mfma_f32_16x16x32_bf16 v[94:97], v[108:111], v[140:143], v[94:97]
	v_mfma_f32_16x16x32_bf16 v[90:93], v[108:111], v[144:147], v[90:93]
	v_mfma_f32_16x16x32_bf16 v[82:85], v[108:111], v[148:151], v[82:85]
	v_mfma_f32_16x16x32_bf16 v[78:81], v[108:111], v[152:155], v[78:81]
	v_mfma_f32_16x16x32_bf16 v[74:77], v[112:115], v[140:143], v[74:77]
	v_mfma_f32_16x16x32_bf16 v[70:73], v[112:115], v[144:147], v[70:73]
	v_mfma_f32_16x16x32_bf16 v[66:69], v[112:115], v[148:151], v[66:69]
	v_mfma_f32_16x16x32_bf16 v[62:65], v[112:115], v[152:155], v[62:65]
	v_mfma_f32_16x16x32_bf16 v[58:61], v[116:119], v[140:143], v[58:61]
	v_mfma_f32_16x16x32_bf16 v[42:45], v[116:119], v[144:147], v[42:45]
	v_mfma_f32_16x16x32_bf16 v[22:25], v[116:119], v[148:151], v[22:25]
	v_mfma_f32_16x16x32_bf16 v[14:17], v[116:119], v[152:155], v[14:17]
	v_mfma_f32_16x16x32_bf16 v[10:13], v[136:139], v[140:143], v[10:13]
	v_mfma_f32_16x16x32_bf16 v[6:9], v[136:139], v[144:147], v[6:9]
	v_mfma_f32_16x16x32_bf16 v[2:5], v[136:139], v[148:151], v[2:5]
	v_mfma_f32_16x16x32_bf16 v[86:89], v[136:139], v[152:155], v[86:89]
	s_waitcnt vmcnt(7)
	v_add_u32_e32 v18, 0x400, v123
	s_barrier
	ds_write2_b32 v123, v94, v90 offset1:16
	ds_write2_b32 v123, v95, v91 offset0:132 offset1:148
	ds_write2_b32 v18, v96, v92 offset0:8 offset1:24
	ds_write2_b32 v18, v97, v93 offset0:140 offset1:156
	ds_write2_b32 v123, v82, v78 offset0:32 offset1:48
	ds_write2_b32 v123, v83, v79 offset0:164 offset1:180
	ds_write2_b32 v18, v84, v80 offset0:40 offset1:56
	ds_write2_b32 v18, v85, v81 offset0:172 offset1:188
	v_add_u32_e32 v18, 0x2000, v123
	v_add_u32_e32 v19, 0x2400, v123
	ds_write2_b32 v18, v74, v70 offset0:64 offset1:80
	ds_write2_b32 v18, v75, v71 offset0:196 offset1:212
	ds_write2_b32 v19, v76, v72 offset0:72 offset1:88
	ds_write2_b32 v19, v77, v73 offset0:204 offset1:220
	ds_write2_b32 v18, v66, v62 offset0:96 offset1:112
	ds_write2_b32 v18, v67, v63 offset0:228 offset1:244
	ds_write2_b32 v19, v68, v64 offset0:104 offset1:120
	ds_write2_b32 v19, v69, v65 offset0:236 offset1:252
	v_add_u32_e32 v18, 0x4000, v123
	v_add_u32_e32 v19, 0x4400, v123
	v_add_u32_e32 v20, 0x4800, v123
	ds_write2_b32 v18, v58, v42 offset0:128 offset1:144
	ds_write2_b32 v19, v59, v43 offset0:4 offset1:20
	ds_write2_b32 v19, v60, v44 offset0:136 offset1:152
	ds_write2_b32 v20, v61, v45 offset0:12 offset1:28
	ds_write2_b32 v18, v22, v14 offset0:160 offset1:176
	ds_write2_b32 v19, v23, v15 offset0:36 offset1:52
	ds_write2_b32 v19, v24, v16 offset0:168 offset1:184
	ds_write2_b32 v20, v25, v17 offset0:44 offset1:60
	v_add_u32_e32 v14, 0x6000, v123
	ds_write2_b32 v14, v10, v6 offset0:192 offset1:208
	v_add_u32_e32 v6, 0x6400, v123
	ds_write2_b32 v6, v11, v7 offset0:68 offset1:84
	ds_write2_b32 v6, v12, v8 offset0:200 offset1:216
	v_add_u32_e32 v7, 0x6800, v123
	s_lshl_b32 s2, s29, 9
	ds_write2_b32 v7, v13, v9 offset0:76 offset1:92
	ds_write2_b32 v14, v2, v86 offset0:224 offset1:240
	ds_write2_b32 v6, v3, v87 offset0:100 offset1:116
	ds_write2_b32 v6, v4, v88 offset0:232 offset1:248
	ds_write2_b32 v7, v5, v89 offset0:108 offset1:124
	v_lshl_add_u64 v[2:3], v[100:101], 0, s[2:3]
	v_lshl_add_u64 v[4:5], v[102:103], 0, s[2:3]
	s_lshl_b32 s2, s28, 10
	s_mul_hi_u32 s12, s28, 0x15555556
	s_lshl_b32 s13, s29, 7
	v_or_b32_e32 v6, s2, v125
	s_mulk_i32 s12, 0x3000
	v_or_b32_e32 v7, s2, v127
	v_or_b32_e32 v8, s2, v129
	v_or_b32_e32 v9, s2, v133
	v_subrev_u32_e32 v6, s12, v6
	v_subrev_u32_e32 v7, s12, v7
	v_subrev_u32_e32 v8, s12, v8
	v_subrev_u32_e32 v9, s12, v9
	s_mov_b32 s12, 0
	s_lshl_b32 s2, s13, 2
	v_mov_b32_e32 v10, v132
	v_mov_b32_e32 v11, v128
	v_mov_b32_e32 v12, v126
	v_mov_b32_e32 v13, v124
	s_waitcnt lgkmcnt(0)
	s_barrier

	.amdhsa_kernel _Z4mega6Paramsiiii
		.amdhsa_group_segment_fixed_size 32
		.amdhsa_private_segment_fixed_size 0
		.amdhsa_kernarg_size 496
		.amdhsa_user_sgpr_count 2
		.amdhsa_user_sgpr_dispatch_ptr 0
		.amdhsa_user_sgpr_queue_ptr 0
		.amdhsa_user_sgpr_kernarg_segment_ptr 1
		.amdhsa_user_sgpr_dispatch_id 0
		.amdhsa_user_sgpr_kernarg_preload_length 0
		.amdhsa_user_sgpr_kernarg_preload_offset 0
		.amdhsa_user_sgpr_private_segment_size 0
		.amdhsa_uses_dynamic_stack 0
		.amdhsa_enable_private_segment 0
		.amdhsa_system_sgpr_workgroup_id_x 1
		.amdhsa_system_sgpr_workgroup_id_y 0
		.amdhsa_system_sgpr_workgroup_id_z 0
		.amdhsa_system_sgpr_workgroup_info 0
		.amdhsa_system_vgpr_workitem_id 2
		.amdhsa_next_free_vgpr 256
		.amdhsa_next_free_sgpr 102
		.amdhsa_accum_offset 256
		.amdhsa_reserve_vcc 1
		.amdhsa_float_round_mode_32 0
		.amdhsa_float_round_mode_16_64 0
		.amdhsa_float_denorm_mode_32 3
		.amdhsa_float_denorm_mode_16_64 3
		.amdhsa_dx10_clamp 1
		.amdhsa_ieee_mode 1
		.amdhsa_fp16_overflow 0
		.amdhsa_tg_split 0
		.amdhsa_exception_fp_ieee_invalid_op 0
		.amdhsa_exception_fp_denorm_src 0
		.amdhsa_exception_fp_ieee_div_zero 0
		.amdhsa_exception_fp_ieee_overflow 0
		.amdhsa_exception_fp_ieee_underflow 0
		.amdhsa_exception_fp_ieee_inexact 0
		.amdhsa_exception_int_div_zero 0
	.end_amdhsa_kernel

amdhsa.kernels:
  - .agpr_count:     0
    .args:
      - .offset:         0
        .size:           224
        .value_kind:     by_value
      - .offset:         224
        .size:           4
        .value_kind:     by_value
      - .offset:         228
        .size:           4
        .value_kind:     by_value
      - .offset:         232
        .size:           4
        .value_kind:     by_value
      - .offset:         236
        .size:           4
        .value_kind:     by_value
      - .offset:         240
        .size:           4
        .value_kind:     hidden_block_count_x
      - .offset:         244
        .size:           4
        .value_kind:     hidden_block_count_y
      - .offset:         248
        .size:           4
        .value_kind:     hidden_block_count_z
      - .offset:         252
        .size:           2
        .value_kind:     hidden_group_size_x
      - .offset:         254
        .size:           2
        .value_kind:     hidden_group_size_y
      - .offset:         256
        .size:           2
        .value_kind:     hidden_group_size_z
      - .offset:         258
        .size:           2
        .value_kind:     hidden_remainder_x
      - .offset:         260
        .size:           2
        .value_kind:     hidden_remainder_y
      - .offset:         262
        .size:           2
        .value_kind:     hidden_remainder_z
      - .offset:         280
        .size:           8
        .value_kind:     hidden_global_offset_x
      - .offset:         288
        .size:           8
        .value_kind:     hidden_global_offset_y
      - .offset:         296
        .size:           8
        .value_kind:     hidden_global_offset_z
      - .offset:         304
        .size:           2
        .value_kind:     hidden_grid_dims
      - .offset:         328
        .size:           8
        .value_kind:     hidden_multigrid_sync_arg
      - .offset:         360
        .size:           4
        .value_kind:     hidden_dynamic_lds_size
    .group_segment_fixed_size: 32
    .kernarg_segment_align: 8
    .kernarg_segment_size: 496
    .language:       OpenCL C
    .language_version:
      - 2
      - 0
    .max_flat_workgroup_size: 256
    .name:           _Z4mega6Paramsiiii
    .private_segment_fixed_size: 0
    .sgpr_count:     108
    .sgpr_spill_count: 83
    .symbol:         _Z4mega6Paramsiiii.kd
    .uniform_work_group_size: 1
    .uses_dynamic_stack: false
    .vgpr_count:     256
    .vgpr_spill_count: 0
    .wavefront_size: 64
